# s_setprio 2 during the GEMM k-loop, 0 in tile prologue/epilogue (main-loop block gets issue priority over the co-resident block's epilogue)
# baseline (speedup 1.0000x reference)
.LBB0_215:
	s_mul_hi_i32 s0, s8, 0x2aaaaaab
	s_lshr_b32 s1, s0, 31
	s_ashr_i32 s0, s0, 5
	s_add_i32 s0, s0, s1
	s_lshl_b32 s1, s0, 3
	s_sub_i32 s2, 17, s1
	s_min_u32 s2, s2, 8
	v_cvt_f32_ubyte0_e32 v0, s2
	v_rcp_iflag_f32_e32 v0, v0
	s_sub_i32 s5, 0, s2
	s_mulk_i32 s0, 0xff40
	s_add_i32 s3, s0, s8
	v_mul_f32_e32 v0, 0x4f7ffffe, v0
	v_cvt_u32_f32_e32 v0, v0
	s_abs_i32 s4, s3
	s_ashr_i32 s0, s3, 31
	v_mov_b32_e32 v181, v179
	v_readfirstlane_b32 s6, v0
	s_mul_i32 s5, s5, s6
	s_mul_hi_u32 s5, s6, s5
	s_add_i32 s6, s6, s5
	s_mul_hi_u32 s5, s4, s6
	s_mul_i32 s6, s5, s2
	s_sub_i32 s4, s4, s6
	s_add_i32 s6, s5, 1
	s_sub_i32 s7, s4, s2
	s_cmp_ge_u32 s4, s2
	s_cselect_b32 s5, s6, s5
	s_cselect_b32 s4, s7, s4
	s_add_i32 s6, s5, 1
	s_cmp_ge_u32 s4, s2
	s_cselect_b32 s4, s6, s5
	s_xor_b32 s4, s4, s0
	s_sub_i32 s0, s4, s0
	s_mul_i32 s2, s2, s0
	s_sub_i32 s2, s3, s2
	s_add_i32 s1, s1, s11
	s_add_i32 s2, s1, s2
	v_ashrrev_i32_e32 v233, 6, v181
	v_lshlrev_b32_e32 v0, 1, v233
	v_lshl_add_u32 v0, s2, 3, v0
	v_ashrrev_i32_e32 v1, 31, v0
	v_bfe_u32 v183, v181, 5, 1
	v_lshlrev_b64 v[0:1], 16, v[0:1]
	v_and_b32_e32 v231, 31, v181
	v_lshl_add_u64 v[0:1], s[64:65], 0, v[0:1]
	v_lshlrev_b32_e32 v176, 9, v183
	s_ashr_i32 s1, s0, 31
	v_lshl_add_u64 v[0:1], v[0:1], 0, v[176:177]
	v_lshlrev_b32_e32 v176, 4, v231
	v_ashrrev_i32_e32 v12, 2, v181
	s_lshl_b64 s[4:5], s[0:1], 18
	v_lshl_add_u64 v[184:185], v[0:1], 0, v[176:177]
	s_add_u32 s4, s9, s4
	v_lshlrev_b32_e32 v0, 5, v12
	s_addc_u32 s5, s10, s5
	v_ashrrev_i32_e32 v1, 31, v0
	v_lshlrev_b32_e32 v2, 4, v181
	v_lshl_add_u64 v[0:1], v[0:1], 1, s[4:5]
	v_and_b32_e32 v176, 48, v2
	v_lshl_add_u64 v[186:187], v[0:1], 0, v[176:177]
	s_movk_i32 s1, 0x2000
	v_add_co_u32_e32 v8, vcc, s1, v186
	v_mul_u32_u24_e32 v10, 40, v231
	s_nop 0
	v_addc_co_u32_e32 v9, vcc, 0, v187, vcc
	v_lshlrev_b32_e32 v11, 4, v183
	v_lshl_add_u32 v235, v10, 1, v11
	v_add_co_u32_e32 v10, vcc, s41, v184
	s_movk_i32 s3, 0x50
	s_nop 0
	v_addc_co_u32_e32 v11, vcc, 0, v185, vcc
	v_and_b32_e32 v232, 63, v181
	v_lshlrev_b32_e32 v234, 3, v181
	v_bfe_u32 v197, v181, 4, 2
	v_lshlrev_b32_e32 v197, 1, v197
	v_mov_b32_e32 v176, 0x78
	v_lshrrev_b32_e32 v197, v197, v176
	v_and_b32_e32 v197, 3, v197
	v_and_b32_e32 v196, 3, v181
	v_xor_b32_e32 v197, v197, v196
	v_lshlrev_b32_e32 v197, 4, v197
	v_and_b32_e32 v188, 0xffffffcf, v186
	v_or_b32_e32 v188, v188, v197
	v_mov_b32_e32 v189, v187
	v_lshrrev_b32_e32 v176, 6, v181
	v_lshlrev_b32_e32 v197, 11, v176
	v_lshlrev_b32_e32 v176, 10, v176
	v_lshl_add_u64 v[188:189], v[188:189], 0, v[176:177]
	v_readfirstlane_b32 vcc_lo, v197
	v_bfe_u32 v197, v181, 4, 1
	v_lshlrev_b32_e32 v176, 9, v183
	v_lshl_add_u32 v176, v197, 8, v176
	v_lshl_add_u64 v[184:185], v[184:185], 0, v[176:177]
	v_mov_b32_e32 v176, s41
	v_lshl_add_u64 v[186:187], v[184:185], 0, v[176:177]
	v_mov_b32_e32 v176, 0x78
	v_bfe_u32 v197, v181, 2, 2
	v_lshlrev_b32_e32 v197, 1, v197
	v_lshrrev_b32_e32 v197, v197, v176
	v_and_b32_e32 v197, 3, v197
	v_bfe_u32 v196, v181, 4, 2
	v_xor_b32_e32 v197, v197, v196
	v_lshlrev_b32_e32 v197, 4, v197
	v_and_b32_e32 v196, 15, v181
	v_lshl_add_u32 v196, v196, 6, v197
	s_mov_b32 s96, 0
	s_mov_b32 m0, vcc_lo
	v_lshl_add_u64 v[160:161], v[188:189], 0, s[96:97]
	global_load_lds_dwordx4 v[160:161], off
	global_load_lds_dwordx4 v[160:161], off offset:1024
	s_mov_b32 s96, 0
	v_lshl_add_u64 v[198:199], v[184:185], 0, s[96:97]
	v_lshl_add_u64 v[200:201], v[186:187], 0, s[96:97]
	global_load_dwordx4 v[128:131], v[198:199], off
	global_load_dwordx4 v[132:135], v[198:199], off offset:256
	global_load_dwordx4 v[136:139], v[200:201], off
	global_load_dwordx4 v[140:143], v[200:201], off offset:256
	s_movk_i32 s96, 0x2000
	s_add_i32 m0, vcc_lo, 8192
	v_lshl_add_u64 v[160:161], v[188:189], 0, s[96:97]
	global_load_lds_dwordx4 v[160:161], off
	global_load_lds_dwordx4 v[160:161], off offset:1024
	s_movk_i32 s96, 0x800
	v_lshl_add_u64 v[198:199], v[184:185], 0, s[96:97]
	v_lshl_add_u64 v[200:201], v[186:187], 0, s[96:97]
	global_load_dwordx4 v[144:147], v[198:199], off
	global_load_dwordx4 v[148:151], v[198:199], off offset:256
	global_load_dwordx4 v[152:155], v[200:201], off
	global_load_dwordx4 v[156:159], v[200:201], off offset:256
	v_mov_b32_e32 v0, 0
	v_mov_b32_e32 v1, 0
	v_mov_b32_e32 v2, 0
	v_mov_b32_e32 v3, 0
	v_mov_b32_e32 v4, 0
	v_mov_b32_e32 v5, 0
	v_mov_b32_e32 v6, 0
	v_mov_b32_e32 v7, 0
	v_mov_b32_e32 v8, 0
	v_mov_b32_e32 v9, 0
	v_mov_b32_e32 v10, 0
	v_mov_b32_e32 v11, 0
	v_mov_b32_e32 v12, 0
	v_mov_b32_e32 v13, 0
	v_mov_b32_e32 v14, 0
	v_mov_b32_e32 v15, 0
	v_mov_b32_e32 v16, 0
	v_mov_b32_e32 v17, 0
	v_mov_b32_e32 v18, 0
	v_mov_b32_e32 v19, 0
	v_mov_b32_e32 v20, 0
	v_mov_b32_e32 v21, 0
	v_mov_b32_e32 v22, 0
	v_mov_b32_e32 v23, 0
	v_mov_b32_e32 v24, 0
	v_mov_b32_e32 v25, 0
	v_mov_b32_e32 v26, 0
	v_mov_b32_e32 v27, 0
	v_mov_b32_e32 v28, 0
	v_mov_b32_e32 v29, 0
	v_mov_b32_e32 v30, 0
	v_mov_b32_e32 v31, 0
	v_mov_b32_e32 v32, 0
	v_mov_b32_e32 v33, 0
	v_mov_b32_e32 v34, 0
	v_mov_b32_e32 v35, 0
	v_mov_b32_e32 v36, 0
	v_mov_b32_e32 v37, 0
	v_mov_b32_e32 v38, 0
	v_mov_b32_e32 v39, 0
	v_mov_b32_e32 v40, 0
	v_mov_b32_e32 v41, 0
	v_mov_b32_e32 v42, 0
	v_mov_b32_e32 v43, 0
	v_mov_b32_e32 v44, 0
	v_mov_b32_e32 v45, 0
	v_mov_b32_e32 v46, 0
	v_mov_b32_e32 v47, 0
	v_mov_b32_e32 v48, 0
	v_mov_b32_e32 v49, 0
	v_mov_b32_e32 v50, 0
	v_mov_b32_e32 v51, 0
	v_mov_b32_e32 v52, 0
	v_mov_b32_e32 v53, 0
	v_mov_b32_e32 v54, 0
	v_mov_b32_e32 v55, 0
	v_mov_b32_e32 v56, 0
	v_mov_b32_e32 v57, 0
	v_mov_b32_e32 v58, 0
	v_mov_b32_e32 v59, 0
	v_mov_b32_e32 v60, 0
	v_mov_b32_e32 v61, 0
	v_mov_b32_e32 v62, 0
	v_mov_b32_e32 v63, 0
	v_mov_b32_e32 v64, 0
	v_mov_b32_e32 v65, 0
	v_mov_b32_e32 v66, 0
	v_mov_b32_e32 v67, 0
	v_mov_b32_e32 v68, 0
	v_mov_b32_e32 v69, 0
	v_mov_b32_e32 v70, 0
	v_mov_b32_e32 v71, 0
	v_mov_b32_e32 v72, 0
	v_mov_b32_e32 v73, 0
	v_mov_b32_e32 v74, 0
	v_mov_b32_e32 v75, 0
	v_mov_b32_e32 v76, 0
	v_mov_b32_e32 v77, 0
	v_mov_b32_e32 v78, 0
	v_mov_b32_e32 v79, 0
	v_mov_b32_e32 v80, 0
	v_mov_b32_e32 v81, 0
	v_mov_b32_e32 v82, 0
	v_mov_b32_e32 v83, 0
	v_mov_b32_e32 v84, 0
	v_mov_b32_e32 v85, 0
	v_mov_b32_e32 v86, 0
	v_mov_b32_e32 v87, 0
	v_mov_b32_e32 v88, 0
	v_mov_b32_e32 v89, 0
	v_mov_b32_e32 v90, 0
	v_mov_b32_e32 v91, 0
	v_mov_b32_e32 v92, 0
	v_mov_b32_e32 v93, 0
	v_mov_b32_e32 v94, 0
	v_mov_b32_e32 v95, 0
	v_mov_b32_e32 v96, 0
	v_mov_b32_e32 v97, 0
	v_mov_b32_e32 v98, 0
	v_mov_b32_e32 v99, 0
	v_mov_b32_e32 v100, 0
	v_mov_b32_e32 v101, 0
	v_mov_b32_e32 v102, 0
	v_mov_b32_e32 v103, 0
	v_mov_b32_e32 v104, 0
	v_mov_b32_e32 v105, 0
	v_mov_b32_e32 v106, 0
	v_mov_b32_e32 v107, 0
	v_mov_b32_e32 v108, 0
	v_mov_b32_e32 v109, 0
	v_mov_b32_e32 v110, 0
	v_mov_b32_e32 v111, 0
	v_mov_b32_e32 v112, 0
	v_mov_b32_e32 v113, 0
	v_mov_b32_e32 v114, 0
	v_mov_b32_e32 v115, 0
	v_mov_b32_e32 v116, 0
	v_mov_b32_e32 v117, 0
	v_mov_b32_e32 v118, 0
	v_mov_b32_e32 v119, 0
	v_mov_b32_e32 v120, 0
	v_mov_b32_e32 v121, 0
	v_mov_b32_e32 v122, 0
	v_mov_b32_e32 v123, 0
	v_mov_b32_e32 v124, 0
	v_mov_b32_e32 v125, 0
	v_mov_b32_e32 v126, 0
	v_mov_b32_e32 v127, 0
	s_mov_b32 s1, 0
	s_waitcnt vmcnt(4)
	s_barrier
	s_setprio 2
.Lg16_proj_k:
	s_add_i32 s3, s1, 2
	s_lshl_b32 s96, s3, 13
	s_add_i32 m0, vcc_lo, 16384
	v_lshl_add_u64 v[160:161], v[188:189], 0, s[96:97]
	global_load_lds_dwordx4 v[160:161], off
	global_load_lds_dwordx4 v[160:161], off offset:1024
	ds_read_b128 v[236:239], v196 offset:0
	ds_read_b128 v[240:243], v196 offset:1024
	ds_read_b128 v[244:247], v196 offset:2048
	ds_read_b128 v[248:251], v196 offset:3072
	s_add_i32 s3, s1, 2
	s_lshl_b32 s96, s3, 11
	v_lshl_add_u64 v[198:199], v[184:185], 0, s[96:97]
	v_lshl_add_u64 v[200:201], v[186:187], 0, s[96:97]
	s_waitcnt vmcnt(8) lgkmcnt(3)
	v_mfma_f32_16x16x32_bf16 v[16:19], v[128:131], v[236:239], v[16:19]
	v_mfma_f32_16x16x32_bf16 v[24:27], v[132:135], v[236:239], v[24:27]
	v_mfma_f32_16x16x32_bf16 v[0:3], v[136:139], v[236:239], v[0:3]
	v_mfma_f32_16x16x32_bf16 v[8:11], v[140:143], v[236:239], v[8:11]
	ds_read_b128 v[236:239], v196 offset:4096
	s_waitcnt lgkmcnt(3)
	v_mfma_f32_16x16x32_bf16 v[20:23], v[128:131], v[240:243], v[20:23]
	v_mfma_f32_16x16x32_bf16 v[28:31], v[132:135], v[240:243], v[28:31]
	v_mfma_f32_16x16x32_bf16 v[4:7], v[136:139], v[240:243], v[4:7]
	v_mfma_f32_16x16x32_bf16 v[12:15], v[140:143], v[240:243], v[12:15]
	ds_read_b128 v[240:243], v196 offset:5120
	s_waitcnt lgkmcnt(3)
	v_mfma_f32_16x16x32_bf16 v[112:115], v[128:131], v[244:247], v[112:115]
	v_mfma_f32_16x16x32_bf16 v[120:123], v[132:135], v[244:247], v[120:123]
	v_mfma_f32_16x16x32_bf16 v[96:99], v[136:139], v[244:247], v[96:99]
	v_mfma_f32_16x16x32_bf16 v[104:107], v[140:143], v[244:247], v[104:107]
	ds_read_b128 v[244:247], v196 offset:6144
	s_waitcnt lgkmcnt(3)
	v_mfma_f32_16x16x32_bf16 v[116:119], v[128:131], v[248:251], v[116:119]
	v_mfma_f32_16x16x32_bf16 v[124:127], v[132:135], v[248:251], v[124:127]
	v_mfma_f32_16x16x32_bf16 v[100:103], v[136:139], v[248:251], v[100:103]
	v_mfma_f32_16x16x32_bf16 v[108:111], v[140:143], v[248:251], v[108:111]
	ds_read_b128 v[248:251], v196 offset:7168
	s_waitcnt lgkmcnt(3)
	v_mfma_f32_16x16x32_bf16 v[80:83], v[128:131], v[236:239], v[80:83]
	v_mfma_f32_16x16x32_bf16 v[88:91], v[132:135], v[236:239], v[88:91]
	v_mfma_f32_16x16x32_bf16 v[48:51], v[136:139], v[236:239], v[48:51]
	v_mfma_f32_16x16x32_bf16 v[56:59], v[140:143], v[236:239], v[56:59]
	s_waitcnt lgkmcnt(2)
	v_mfma_f32_16x16x32_bf16 v[84:87], v[128:131], v[240:243], v[84:87]
	v_mfma_f32_16x16x32_bf16 v[92:95], v[132:135], v[240:243], v[92:95]
	v_mfma_f32_16x16x32_bf16 v[52:55], v[136:139], v[240:243], v[52:55]
	v_mfma_f32_16x16x32_bf16 v[60:63], v[140:143], v[240:243], v[60:63]
	s_waitcnt lgkmcnt(1)
	v_mfma_f32_16x16x32_bf16 v[64:67], v[128:131], v[244:247], v[64:67]
	v_mfma_f32_16x16x32_bf16 v[72:75], v[132:135], v[244:247], v[72:75]
	v_mfma_f32_16x16x32_bf16 v[32:35], v[136:139], v[244:247], v[32:35]
	v_mfma_f32_16x16x32_bf16 v[40:43], v[140:143], v[244:247], v[40:43]
	s_waitcnt lgkmcnt(0)
	v_mfma_f32_16x16x32_bf16 v[68:71], v[128:131], v[248:251], v[68:71]
	v_mfma_f32_16x16x32_bf16 v[76:79], v[132:135], v[248:251], v[76:79]
	v_mfma_f32_16x16x32_bf16 v[36:39], v[136:139], v[248:251], v[36:39]
	v_mfma_f32_16x16x32_bf16 v[44:47], v[140:143], v[248:251], v[44:47]
	global_load_dwordx4 v[128:131], v[198:199], off
	global_load_dwordx4 v[132:135], v[198:199], off offset:256
	global_load_dwordx4 v[136:139], v[200:201], off
	global_load_dwordx4 v[140:143], v[200:201], off offset:256
	s_waitcnt vmcnt(10)
	s_barrier
	s_add_i32 s3, s1, 3
	s_lshl_b32 s96, s3, 13
	s_mov_b32 m0, vcc_lo
	v_lshl_add_u64 v[160:161], v[188:189], 0, s[96:97]
	global_load_lds_dwordx4 v[160:161], off
	global_load_lds_dwordx4 v[160:161], off offset:1024
	ds_read_b128 v[236:239], v196 offset:8192
	ds_read_b128 v[240:243], v196 offset:9216
	ds_read_b128 v[244:247], v196 offset:10240
	ds_read_b128 v[248:251], v196 offset:11264
	s_add_i32 s3, s1, 3
	s_lshl_b32 s96, s3, 11
	v_lshl_add_u64 v[198:199], v[184:185], 0, s[96:97]
	v_lshl_add_u64 v[200:201], v[186:187], 0, s[96:97]
	s_waitcnt vmcnt(8) lgkmcnt(3)
	v_mfma_f32_16x16x32_bf16 v[16:19], v[144:147], v[236:239], v[16:19]
	v_mfma_f32_16x16x32_bf16 v[24:27], v[148:151], v[236:239], v[24:27]
	v_mfma_f32_16x16x32_bf16 v[0:3], v[152:155], v[236:239], v[0:3]
	v_mfma_f32_16x16x32_bf16 v[8:11], v[156:159], v[236:239], v[8:11]
	ds_read_b128 v[236:239], v196 offset:12288
	s_waitcnt lgkmcnt(3)
	v_mfma_f32_16x16x32_bf16 v[20:23], v[144:147], v[240:243], v[20:23]
	v_mfma_f32_16x16x32_bf16 v[28:31], v[148:151], v[240:243], v[28:31]
	v_mfma_f32_16x16x32_bf16 v[4:7], v[152:155], v[240:243], v[4:7]
	v_mfma_f32_16x16x32_bf16 v[12:15], v[156:159], v[240:243], v[12:15]
	ds_read_b128 v[240:243], v196 offset:13312
	s_waitcnt lgkmcnt(3)
	v_mfma_f32_16x16x32_bf16 v[112:115], v[144:147], v[244:247], v[112:115]
	v_mfma_f32_16x16x32_bf16 v[120:123], v[148:151], v[244:247], v[120:123]
	v_mfma_f32_16x16x32_bf16 v[96:99], v[152:155], v[244:247], v[96:99]
	v_mfma_f32_16x16x32_bf16 v[104:107], v[156:159], v[244:247], v[104:107]
	ds_read_b128 v[244:247], v196 offset:14336
	s_waitcnt lgkmcnt(3)
	v_mfma_f32_16x16x32_bf16 v[116:119], v[144:147], v[248:251], v[116:119]
	v_mfma_f32_16x16x32_bf16 v[124:127], v[148:151], v[248:251], v[124:127]
	v_mfma_f32_16x16x32_bf16 v[100:103], v[152:155], v[248:251], v[100:103]
	v_mfma_f32_16x16x32_bf16 v[108:111], v[156:159], v[248:251], v[108:111]
	ds_read_b128 v[248:251], v196 offset:15360
	s_waitcnt lgkmcnt(3)
	v_mfma_f32_16x16x32_bf16 v[80:83], v[144:147], v[236:239], v[80:83]
	v_mfma_f32_16x16x32_bf16 v[88:91], v[148:151], v[236:239], v[88:91]
	v_mfma_f32_16x16x32_bf16 v[48:51], v[152:155], v[236:239], v[48:51]
	v_mfma_f32_16x16x32_bf16 v[56:59], v[156:159], v[236:239], v[56:59]
	s_waitcnt lgkmcnt(2)
	v_mfma_f32_16x16x32_bf16 v[84:87], v[144:147], v[240:243], v[84:87]
	v_mfma_f32_16x16x32_bf16 v[92:95], v[148:151], v[240:243], v[92:95]
	v_mfma_f32_16x16x32_bf16 v[52:55], v[152:155], v[240:243], v[52:55]
	v_mfma_f32_16x16x32_bf16 v[60:63], v[156:159], v[240:243], v[60:63]
	s_waitcnt lgkmcnt(1)
	v_mfma_f32_16x16x32_bf16 v[64:67], v[144:147], v[244:247], v[64:67]
	v_mfma_f32_16x16x32_bf16 v[72:75], v[148:151], v[244:247], v[72:75]
	v_mfma_f32_16x16x32_bf16 v[32:35], v[152:155], v[244:247], v[32:35]
	v_mfma_f32_16x16x32_bf16 v[40:43], v[156:159], v[244:247], v[40:43]
	s_waitcnt lgkmcnt(0)
	v_mfma_f32_16x16x32_bf16 v[68:71], v[144:147], v[248:251], v[68:71]
	v_mfma_f32_16x16x32_bf16 v[76:79], v[148:151], v[248:251], v[76:79]
	v_mfma_f32_16x16x32_bf16 v[36:39], v[152:155], v[248:251], v[36:39]
	v_mfma_f32_16x16x32_bf16 v[44:47], v[156:159], v[248:251], v[44:47]
	global_load_dwordx4 v[144:147], v[198:199], off
	global_load_dwordx4 v[148:151], v[198:199], off offset:256
	global_load_dwordx4 v[152:155], v[200:201], off
	global_load_dwordx4 v[156:159], v[200:201], off offset:256
	s_waitcnt vmcnt(10)
	s_barrier
	s_add_i32 s3, s1, 4
	s_lshl_b32 s96, s3, 13
	s_add_i32 m0, vcc_lo, 8192
	v_lshl_add_u64 v[160:161], v[188:189], 0, s[96:97]
	global_load_lds_dwordx4 v[160:161], off
	global_load_lds_dwordx4 v[160:161], off offset:1024
	ds_read_b128 v[236:239], v196 offset:16384
	ds_read_b128 v[240:243], v196 offset:17408
	ds_read_b128 v[244:247], v196 offset:18432
	ds_read_b128 v[248:251], v196 offset:19456
	s_add_i32 s3, s1, 4
	s_lshl_b32 s96, s3, 11
	v_lshl_add_u64 v[198:199], v[184:185], 0, s[96:97]
	v_lshl_add_u64 v[200:201], v[186:187], 0, s[96:97]
	s_waitcnt vmcnt(8) lgkmcnt(3)
	v_mfma_f32_16x16x32_bf16 v[16:19], v[128:131], v[236:239], v[16:19]
	v_mfma_f32_16x16x32_bf16 v[24:27], v[132:135], v[236:239], v[24:27]
	v_mfma_f32_16x16x32_bf16 v[0:3], v[136:139], v[236:239], v[0:3]
	v_mfma_f32_16x16x32_bf16 v[8:11], v[140:143], v[236:239], v[8:11]
	ds_read_b128 v[236:239], v196 offset:20480
	s_waitcnt lgkmcnt(3)
	v_mfma_f32_16x16x32_bf16 v[20:23], v[128:131], v[240:243], v[20:23]
	v_mfma_f32_16x16x32_bf16 v[28:31], v[132:135], v[240:243], v[28:31]
	v_mfma_f32_16x16x32_bf16 v[4:7], v[136:139], v[240:243], v[4:7]
	v_mfma_f32_16x16x32_bf16 v[12:15], v[140:143], v[240:243], v[12:15]
	ds_read_b128 v[240:243], v196 offset:21504
	s_waitcnt lgkmcnt(3)
	v_mfma_f32_16x16x32_bf16 v[112:115], v[128:131], v[244:247], v[112:115]
	v_mfma_f32_16x16x32_bf16 v[120:123], v[132:135], v[244:247], v[120:123]
	v_mfma_f32_16x16x32_bf16 v[96:99], v[136:139], v[244:247], v[96:99]
	v_mfma_f32_16x16x32_bf16 v[104:107], v[140:143], v[244:247], v[104:107]
	ds_read_b128 v[244:247], v196 offset:22528
	s_waitcnt lgkmcnt(3)
	v_mfma_f32_16x16x32_bf16 v[116:119], v[128:131], v[248:251], v[116:119]
	v_mfma_f32_16x16x32_bf16 v[124:127], v[132:135], v[248:251], v[124:127]
	v_mfma_f32_16x16x32_bf16 v[100:103], v[136:139], v[248:251], v[100:103]
	v_mfma_f32_16x16x32_bf16 v[108:111], v[140:143], v[248:251], v[108:111]
	ds_read_b128 v[248:251], v196 offset:23552
	s_waitcnt lgkmcnt(3)
	v_mfma_f32_16x16x32_bf16 v[80:83], v[128:131], v[236:239], v[80:83]
	v_mfma_f32_16x16x32_bf16 v[88:91], v[132:135], v[236:239], v[88:91]
	v_mfma_f32_16x16x32_bf16 v[48:51], v[136:139], v[236:239], v[48:51]
	v_mfma_f32_16x16x32_bf16 v[56:59], v[140:143], v[236:239], v[56:59]
	s_waitcnt lgkmcnt(2)
	v_mfma_f32_16x16x32_bf16 v[84:87], v[128:131], v[240:243], v[84:87]
	v_mfma_f32_16x16x32_bf16 v[92:95], v[132:135], v[240:243], v[92:95]
	v_mfma_f32_16x16x32_bf16 v[52:55], v[136:139], v[240:243], v[52:55]
	v_mfma_f32_16x16x32_bf16 v[60:63], v[140:143], v[240:243], v[60:63]
	s_waitcnt lgkmcnt(1)
	v_mfma_f32_16x16x32_bf16 v[64:67], v[128:131], v[244:247], v[64:67]
	v_mfma_f32_16x16x32_bf16 v[72:75], v[132:135], v[244:247], v[72:75]
	v_mfma_f32_16x16x32_bf16 v[32:35], v[136:139], v[244:247], v[32:35]
	v_mfma_f32_16x16x32_bf16 v[40:43], v[140:143], v[244:247], v[40:43]
	s_waitcnt lgkmcnt(0)
	v_mfma_f32_16x16x32_bf16 v[68:71], v[128:131], v[248:251], v[68:71]
	v_mfma_f32_16x16x32_bf16 v[76:79], v[132:135], v[248:251], v[76:79]
	v_mfma_f32_16x16x32_bf16 v[36:39], v[136:139], v[248:251], v[36:39]
	v_mfma_f32_16x16x32_bf16 v[44:47], v[140:143], v[248:251], v[44:47]
	global_load_dwordx4 v[128:131], v[198:199], off
	global_load_dwordx4 v[132:135], v[198:199], off offset:256
	global_load_dwordx4 v[136:139], v[200:201], off
	global_load_dwordx4 v[140:143], v[200:201], off offset:256
	s_waitcnt vmcnt(10)
	s_barrier
	s_add_i32 s3, s1, 5
	s_lshl_b32 s96, s3, 13
	s_add_i32 m0, vcc_lo, 16384
	v_lshl_add_u64 v[160:161], v[188:189], 0, s[96:97]
	global_load_lds_dwordx4 v[160:161], off
	global_load_lds_dwordx4 v[160:161], off offset:1024
	ds_read_b128 v[236:239], v196 offset:0
	ds_read_b128 v[240:243], v196 offset:1024
	ds_read_b128 v[244:247], v196 offset:2048
	ds_read_b128 v[248:251], v196 offset:3072
	s_add_i32 s3, s1, 5
	s_lshl_b32 s96, s3, 11
	v_lshl_add_u64 v[198:199], v[184:185], 0, s[96:97]
	v_lshl_add_u64 v[200:201], v[186:187], 0, s[96:97]
	s_waitcnt vmcnt(8) lgkmcnt(3)
	v_mfma_f32_16x16x32_bf16 v[16:19], v[144:147], v[236:239], v[16:19]
	v_mfma_f32_16x16x32_bf16 v[24:27], v[148:151], v[236:239], v[24:27]
	v_mfma_f32_16x16x32_bf16 v[0:3], v[152:155], v[236:239], v[0:3]
	v_mfma_f32_16x16x32_bf16 v[8:11], v[156:159], v[236:239], v[8:11]
	ds_read_b128 v[236:239], v196 offset:4096
	s_waitcnt lgkmcnt(3)
	v_mfma_f32_16x16x32_bf16 v[20:23], v[144:147], v[240:243], v[20:23]
	v_mfma_f32_16x16x32_bf16 v[28:31], v[148:151], v[240:243], v[28:31]
	v_mfma_f32_16x16x32_bf16 v[4:7], v[152:155], v[240:243], v[4:7]
	v_mfma_f32_16x16x32_bf16 v[12:15], v[156:159], v[240:243], v[12:15]
	ds_read_b128 v[240:243], v196 offset:5120
	s_waitcnt lgkmcnt(3)
	v_mfma_f32_16x16x32_bf16 v[112:115], v[144:147], v[244:247], v[112:115]
	v_mfma_f32_16x16x32_bf16 v[120:123], v[148:151], v[244:247], v[120:123]
	v_mfma_f32_16x16x32_bf16 v[96:99], v[152:155], v[244:247], v[96:99]
	v_mfma_f32_16x16x32_bf16 v[104:107], v[156:159], v[244:247], v[104:107]
	ds_read_b128 v[244:247], v196 offset:6144
	s_waitcnt lgkmcnt(3)
	v_mfma_f32_16x16x32_bf16 v[116:119], v[144:147], v[248:251], v[116:119]
	v_mfma_f32_16x16x32_bf16 v[124:127], v[148:151], v[248:251], v[124:127]
	v_mfma_f32_16x16x32_bf16 v[100:103], v[152:155], v[248:251], v[100:103]
	v_mfma_f32_16x16x32_bf16 v[108:111], v[156:159], v[248:251], v[108:111]
	ds_read_b128 v[248:251], v196 offset:7168
	s_waitcnt lgkmcnt(3)
	v_mfma_f32_16x16x32_bf16 v[80:83], v[144:147], v[236:239], v[80:83]
	v_mfma_f32_16x16x32_bf16 v[88:91], v[148:151], v[236:239], v[88:91]
	v_mfma_f32_16x16x32_bf16 v[48:51], v[152:155], v[236:239], v[48:51]
	v_mfma_f32_16x16x32_bf16 v[56:59], v[156:159], v[236:239], v[56:59]
	s_waitcnt lgkmcnt(2)
	v_mfma_f32_16x16x32_bf16 v[84:87], v[144:147], v[240:243], v[84:87]
	v_mfma_f32_16x16x32_bf16 v[92:95], v[148:151], v[240:243], v[92:95]
	v_mfma_f32_16x16x32_bf16 v[52:55], v[152:155], v[240:243], v[52:55]
	v_mfma_f32_16x16x32_bf16 v[60:63], v[156:159], v[240:243], v[60:63]
	s_waitcnt lgkmcnt(1)
	v_mfma_f32_16x16x32_bf16 v[64:67], v[144:147], v[244:247], v[64:67]
	v_mfma_f32_16x16x32_bf16 v[72:75], v[148:151], v[244:247], v[72:75]
	v_mfma_f32_16x16x32_bf16 v[32:35], v[152:155], v[244:247], v[32:35]
	v_mfma_f32_16x16x32_bf16 v[40:43], v[156:159], v[244:247], v[40:43]
	s_waitcnt lgkmcnt(0)
	v_mfma_f32_16x16x32_bf16 v[68:71], v[144:147], v[248:251], v[68:71]
	v_mfma_f32_16x16x32_bf16 v[76:79], v[148:151], v[248:251], v[76:79]
	v_mfma_f32_16x16x32_bf16 v[36:39], v[152:155], v[248:251], v[36:39]
	v_mfma_f32_16x16x32_bf16 v[44:47], v[156:159], v[248:251], v[44:47]
	global_load_dwordx4 v[144:147], v[198:199], off
	global_load_dwordx4 v[148:151], v[198:199], off offset:256
	global_load_dwordx4 v[152:155], v[200:201], off
	global_load_dwordx4 v[156:159], v[200:201], off offset:256
	s_waitcnt vmcnt(10)
	s_barrier
	s_add_i32 s3, s1, 6
	s_lshl_b32 s96, s3, 13
	s_mov_b32 m0, vcc_lo
	v_lshl_add_u64 v[160:161], v[188:189], 0, s[96:97]
	global_load_lds_dwordx4 v[160:161], off
	global_load_lds_dwordx4 v[160:161], off offset:1024
	ds_read_b128 v[236:239], v196 offset:8192
	ds_read_b128 v[240:243], v196 offset:9216
	ds_read_b128 v[244:247], v196 offset:10240
	ds_read_b128 v[248:251], v196 offset:11264
	s_add_i32 s3, s1, 6
	s_lshl_b32 s96, s3, 11
	v_lshl_add_u64 v[198:199], v[184:185], 0, s[96:97]
	v_lshl_add_u64 v[200:201], v[186:187], 0, s[96:97]
	s_waitcnt vmcnt(8) lgkmcnt(3)
	v_mfma_f32_16x16x32_bf16 v[16:19], v[128:131], v[236:239], v[16:19]
	v_mfma_f32_16x16x32_bf16 v[24:27], v[132:135], v[236:239], v[24:27]
	v_mfma_f32_16x16x32_bf16 v[0:3], v[136:139], v[236:239], v[0:3]
	v_mfma_f32_16x16x32_bf16 v[8:11], v[140:143], v[236:239], v[8:11]
	ds_read_b128 v[236:239], v196 offset:12288
	s_waitcnt lgkmcnt(3)
	v_mfma_f32_16x16x32_bf16 v[20:23], v[128:131], v[240:243], v[20:23]
	v_mfma_f32_16x16x32_bf16 v[28:31], v[132:135], v[240:243], v[28:31]
	v_mfma_f32_16x16x32_bf16 v[4:7], v[136:139], v[240:243], v[4:7]
	v_mfma_f32_16x16x32_bf16 v[12:15], v[140:143], v[240:243], v[12:15]
	ds_read_b128 v[240:243], v196 offset:13312
	s_waitcnt lgkmcnt(3)
	v_mfma_f32_16x16x32_bf16 v[112:115], v[128:131], v[244:247], v[112:115]
	v_mfma_f32_16x16x32_bf16 v[120:123], v[132:135], v[244:247], v[120:123]
	v_mfma_f32_16x16x32_bf16 v[96:99], v[136:139], v[244:247], v[96:99]
	v_mfma_f32_16x16x32_bf16 v[104:107], v[140:143], v[244:247], v[104:107]
	ds_read_b128 v[244:247], v196 offset:14336
	s_waitcnt lgkmcnt(3)
	v_mfma_f32_16x16x32_bf16 v[116:119], v[128:131], v[248:251], v[116:119]
	v_mfma_f32_16x16x32_bf16 v[124:127], v[132:135], v[248:251], v[124:127]
	v_mfma_f32_16x16x32_bf16 v[100:103], v[136:139], v[248:251], v[100:103]
	v_mfma_f32_16x16x32_bf16 v[108:111], v[140:143], v[248:251], v[108:111]
	ds_read_b128 v[248:251], v196 offset:15360
	s_waitcnt lgkmcnt(3)
	v_mfma_f32_16x16x32_bf16 v[80:83], v[128:131], v[236:239], v[80:83]
	v_mfma_f32_16x16x32_bf16 v[88:91], v[132:135], v[236:239], v[88:91]
	v_mfma_f32_16x16x32_bf16 v[48:51], v[136:139], v[236:239], v[48:51]
	v_mfma_f32_16x16x32_bf16 v[56:59], v[140:143], v[236:239], v[56:59]
	s_waitcnt lgkmcnt(2)
	v_mfma_f32_16x16x32_bf16 v[84:87], v[128:131], v[240:243], v[84:87]
	v_mfma_f32_16x16x32_bf16 v[92:95], v[132:135], v[240:243], v[92:95]
	v_mfma_f32_16x16x32_bf16 v[52:55], v[136:139], v[240:243], v[52:55]
	v_mfma_f32_16x16x32_bf16 v[60:63], v[140:143], v[240:243], v[60:63]
	s_waitcnt lgkmcnt(1)
	v_mfma_f32_16x16x32_bf16 v[64:67], v[128:131], v[244:247], v[64:67]
	v_mfma_f32_16x16x32_bf16 v[72:75], v[132:135], v[244:247], v[72:75]
	v_mfma_f32_16x16x32_bf16 v[32:35], v[136:139], v[244:247], v[32:35]
	v_mfma_f32_16x16x32_bf16 v[40:43], v[140:143], v[244:247], v[40:43]
	s_waitcnt lgkmcnt(0)
	v_mfma_f32_16x16x32_bf16 v[68:71], v[128:131], v[248:251], v[68:71]
	v_mfma_f32_16x16x32_bf16 v[76:79], v[132:135], v[248:251], v[76:79]
	v_mfma_f32_16x16x32_bf16 v[36:39], v[136:139], v[248:251], v[36:39]
	v_mfma_f32_16x16x32_bf16 v[44:47], v[140:143], v[248:251], v[44:47]
	global_load_dwordx4 v[128:131], v[198:199], off
	global_load_dwordx4 v[132:135], v[198:199], off offset:256
	global_load_dwordx4 v[136:139], v[200:201], off
	global_load_dwordx4 v[140:143], v[200:201], off offset:256
	s_waitcnt vmcnt(10)
	s_barrier
	s_add_i32 s3, s1, 7
	s_lshl_b32 s96, s3, 13
	s_add_i32 m0, vcc_lo, 8192
	v_lshl_add_u64 v[160:161], v[188:189], 0, s[96:97]
	global_load_lds_dwordx4 v[160:161], off
	global_load_lds_dwordx4 v[160:161], off offset:1024
	ds_read_b128 v[236:239], v196 offset:16384
	ds_read_b128 v[240:243], v196 offset:17408
	ds_read_b128 v[244:247], v196 offset:18432
	ds_read_b128 v[248:251], v196 offset:19456
	s_add_i32 s3, s1, 7
	s_lshl_b32 s96, s3, 11
	v_lshl_add_u64 v[198:199], v[184:185], 0, s[96:97]
	v_lshl_add_u64 v[200:201], v[186:187], 0, s[96:97]
	s_waitcnt vmcnt(8) lgkmcnt(3)
	v_mfma_f32_16x16x32_bf16 v[16:19], v[144:147], v[236:239], v[16:19]
	v_mfma_f32_16x16x32_bf16 v[24:27], v[148:151], v[236:239], v[24:27]
	v_mfma_f32_16x16x32_bf16 v[0:3], v[152:155], v[236:239], v[0:3]
	v_mfma_f32_16x16x32_bf16 v[8:11], v[156:159], v[236:239], v[8:11]
	ds_read_b128 v[236:239], v196 offset:20480
	s_waitcnt lgkmcnt(3)
	v_mfma_f32_16x16x32_bf16 v[20:23], v[144:147], v[240:243], v[20:23]
	v_mfma_f32_16x16x32_bf16 v[28:31], v[148:151], v[240:243], v[28:31]
	v_mfma_f32_16x16x32_bf16 v[4:7], v[152:155], v[240:243], v[4:7]
	v_mfma_f32_16x16x32_bf16 v[12:15], v[156:159], v[240:243], v[12:15]
	ds_read_b128 v[240:243], v196 offset:21504
	s_waitcnt lgkmcnt(3)
	v_mfma_f32_16x16x32_bf16 v[112:115], v[144:147], v[244:247], v[112:115]
	v_mfma_f32_16x16x32_bf16 v[120:123], v[148:151], v[244:247], v[120:123]
	v_mfma_f32_16x16x32_bf16 v[96:99], v[152:155], v[244:247], v[96:99]
	v_mfma_f32_16x16x32_bf16 v[104:107], v[156:159], v[244:247], v[104:107]
	ds_read_b128 v[244:247], v196 offset:22528
	s_waitcnt lgkmcnt(3)
	v_mfma_f32_16x16x32_bf16 v[116:119], v[144:147], v[248:251], v[116:119]
	v_mfma_f32_16x16x32_bf16 v[124:127], v[148:151], v[248:251], v[124:127]
	v_mfma_f32_16x16x32_bf16 v[100:103], v[152:155], v[248:251], v[100:103]
	v_mfma_f32_16x16x32_bf16 v[108:111], v[156:159], v[248:251], v[108:111]
	ds_read_b128 v[248:251], v196 offset:23552
	s_waitcnt lgkmcnt(3)
	v_mfma_f32_16x16x32_bf16 v[80:83], v[144:147], v[236:239], v[80:83]
	v_mfma_f32_16x16x32_bf16 v[88:91], v[148:151], v[236:239], v[88:91]
	v_mfma_f32_16x16x32_bf16 v[48:51], v[152:155], v[236:239], v[48:51]
	v_mfma_f32_16x16x32_bf16 v[56:59], v[156:159], v[236:239], v[56:59]
	s_waitcnt lgkmcnt(2)
	v_mfma_f32_16x16x32_bf16 v[84:87], v[144:147], v[240:243], v[84:87]
	v_mfma_f32_16x16x32_bf16 v[92:95], v[148:151], v[240:243], v[92:95]
	v_mfma_f32_16x16x32_bf16 v[52:55], v[152:155], v[240:243], v[52:55]
	v_mfma_f32_16x16x32_bf16 v[60:63], v[156:159], v[240:243], v[60:63]
	s_waitcnt lgkmcnt(1)
	v_mfma_f32_16x16x32_bf16 v[64:67], v[144:147], v[244:247], v[64:67]
	v_mfma_f32_16x16x32_bf16 v[72:75], v[148:151], v[244:247], v[72:75]
	v_mfma_f32_16x16x32_bf16 v[32:35], v[152:155], v[244:247], v[32:35]
	v_mfma_f32_16x16x32_bf16 v[40:43], v[156:159], v[244:247], v[40:43]
	s_waitcnt lgkmcnt(0)
	v_mfma_f32_16x16x32_bf16 v[68:71], v[144:147], v[248:251], v[68:71]
	v_mfma_f32_16x16x32_bf16 v[76:79], v[148:151], v[248:251], v[76:79]
	v_mfma_f32_16x16x32_bf16 v[36:39], v[152:155], v[248:251], v[36:39]
	v_mfma_f32_16x16x32_bf16 v[44:47], v[156:159], v[248:251], v[44:47]
	global_load_dwordx4 v[144:147], v[198:199], off
	global_load_dwordx4 v[148:151], v[198:199], off offset:256
	global_load_dwordx4 v[152:155], v[200:201], off
	global_load_dwordx4 v[156:159], v[200:201], off offset:256
	s_waitcnt vmcnt(10)
	s_barrier
	s_add_i32 s1, s1, 6
	s_cmp_lt_u32 s1, 30
	s_cbranch_scc1 .Lg16_proj_k
	ds_read_b128 v[236:239], v196 offset:0
	ds_read_b128 v[240:243], v196 offset:1024
	ds_read_b128 v[244:247], v196 offset:2048
	ds_read_b128 v[248:251], v196 offset:3072
	s_waitcnt vmcnt(6) lgkmcnt(3)
	v_mfma_f32_16x16x32_bf16 v[16:19], v[128:131], v[236:239], v[16:19]
	v_mfma_f32_16x16x32_bf16 v[24:27], v[132:135], v[236:239], v[24:27]
	v_mfma_f32_16x16x32_bf16 v[0:3], v[136:139], v[236:239], v[0:3]
	v_mfma_f32_16x16x32_bf16 v[8:11], v[140:143], v[236:239], v[8:11]
	ds_read_b128 v[236:239], v196 offset:4096
	s_waitcnt lgkmcnt(3)
	v_mfma_f32_16x16x32_bf16 v[20:23], v[128:131], v[240:243], v[20:23]
	v_mfma_f32_16x16x32_bf16 v[28:31], v[132:135], v[240:243], v[28:31]
	v_mfma_f32_16x16x32_bf16 v[4:7], v[136:139], v[240:243], v[4:7]
	v_mfma_f32_16x16x32_bf16 v[12:15], v[140:143], v[240:243], v[12:15]
	ds_read_b128 v[240:243], v196 offset:5120
	s_waitcnt lgkmcnt(3)
	v_mfma_f32_16x16x32_bf16 v[112:115], v[128:131], v[244:247], v[112:115]
	v_mfma_f32_16x16x32_bf16 v[120:123], v[132:135], v[244:247], v[120:123]
	v_mfma_f32_16x16x32_bf16 v[96:99], v[136:139], v[244:247], v[96:99]
	v_mfma_f32_16x16x32_bf16 v[104:107], v[140:143], v[244:247], v[104:107]
	ds_read_b128 v[244:247], v196 offset:6144
	s_waitcnt lgkmcnt(3)
	v_mfma_f32_16x16x32_bf16 v[116:119], v[128:131], v[248:251], v[116:119]
	v_mfma_f32_16x16x32_bf16 v[124:127], v[132:135], v[248:251], v[124:127]
	v_mfma_f32_16x16x32_bf16 v[100:103], v[136:139], v[248:251], v[100:103]
	v_mfma_f32_16x16x32_bf16 v[108:111], v[140:143], v[248:251], v[108:111]
	ds_read_b128 v[248:251], v196 offset:7168
	s_waitcnt lgkmcnt(3)
	v_mfma_f32_16x16x32_bf16 v[80:83], v[128:131], v[236:239], v[80:83]
	v_mfma_f32_16x16x32_bf16 v[88:91], v[132:135], v[236:239], v[88:91]
	v_mfma_f32_16x16x32_bf16 v[48:51], v[136:139], v[236:239], v[48:51]
	v_mfma_f32_16x16x32_bf16 v[56:59], v[140:143], v[236:239], v[56:59]
	s_waitcnt lgkmcnt(2)
	v_mfma_f32_16x16x32_bf16 v[84:87], v[128:131], v[240:243], v[84:87]
	v_mfma_f32_16x16x32_bf16 v[92:95], v[132:135], v[240:243], v[92:95]
	v_mfma_f32_16x16x32_bf16 v[52:55], v[136:139], v[240:243], v[52:55]
	v_mfma_f32_16x16x32_bf16 v[60:63], v[140:143], v[240:243], v[60:63]
	s_waitcnt lgkmcnt(1)
	v_mfma_f32_16x16x32_bf16 v[64:67], v[128:131], v[244:247], v[64:67]
	v_mfma_f32_16x16x32_bf16 v[72:75], v[132:135], v[244:247], v[72:75]
	v_mfma_f32_16x16x32_bf16 v[32:35], v[136:139], v[244:247], v[32:35]
	v_mfma_f32_16x16x32_bf16 v[40:43], v[140:143], v[244:247], v[40:43]
	s_waitcnt lgkmcnt(0)
	v_mfma_f32_16x16x32_bf16 v[68:71], v[128:131], v[248:251], v[68:71]
	v_mfma_f32_16x16x32_bf16 v[76:79], v[132:135], v[248:251], v[76:79]
	v_mfma_f32_16x16x32_bf16 v[36:39], v[136:139], v[248:251], v[36:39]
	v_mfma_f32_16x16x32_bf16 v[44:47], v[140:143], v[248:251], v[44:47]
	s_waitcnt vmcnt(4)
	s_barrier
	ds_read_b128 v[236:239], v196 offset:8192
	ds_read_b128 v[240:243], v196 offset:9216
	ds_read_b128 v[244:247], v196 offset:10240
	ds_read_b128 v[248:251], v196 offset:11264
	s_waitcnt vmcnt(0) lgkmcnt(3)
	v_mfma_f32_16x16x32_bf16 v[16:19], v[144:147], v[236:239], v[16:19]
	v_mfma_f32_16x16x32_bf16 v[24:27], v[148:151], v[236:239], v[24:27]
	v_mfma_f32_16x16x32_bf16 v[0:3], v[152:155], v[236:239], v[0:3]
	v_mfma_f32_16x16x32_bf16 v[8:11], v[156:159], v[236:239], v[8:11]
	ds_read_b128 v[236:239], v196 offset:12288
	s_waitcnt lgkmcnt(3)
	v_mfma_f32_16x16x32_bf16 v[20:23], v[144:147], v[240:243], v[20:23]
	v_mfma_f32_16x16x32_bf16 v[28:31], v[148:151], v[240:243], v[28:31]
	v_mfma_f32_16x16x32_bf16 v[4:7], v[152:155], v[240:243], v[4:7]
	v_mfma_f32_16x16x32_bf16 v[12:15], v[156:159], v[240:243], v[12:15]
	ds_read_b128 v[240:243], v196 offset:13312
	s_waitcnt lgkmcnt(3)
	v_mfma_f32_16x16x32_bf16 v[112:115], v[144:147], v[244:247], v[112:115]
	v_mfma_f32_16x16x32_bf16 v[120:123], v[148:151], v[244:247], v[120:123]
	v_mfma_f32_16x16x32_bf16 v[96:99], v[152:155], v[244:247], v[96:99]
	v_mfma_f32_16x16x32_bf16 v[104:107], v[156:159], v[244:247], v[104:107]
	ds_read_b128 v[244:247], v196 offset:14336
	s_waitcnt lgkmcnt(3)
	v_mfma_f32_16x16x32_bf16 v[116:119], v[144:147], v[248:251], v[116:119]
	v_mfma_f32_16x16x32_bf16 v[124:127], v[148:151], v[248:251], v[124:127]
	v_mfma_f32_16x16x32_bf16 v[100:103], v[152:155], v[248:251], v[100:103]
	v_mfma_f32_16x16x32_bf16 v[108:111], v[156:159], v[248:251], v[108:111]
	ds_read_b128 v[248:251], v196 offset:15360
	v_permlane16_swap_b32_e32 v16, v20
	v_permlane16_swap_b32_e32 v17, v21
	v_permlane16_swap_b32_e32 v18, v22
	v_permlane16_swap_b32_e32 v19, v23
	v_permlane16_swap_b32_e32 v24, v28
	v_permlane16_swap_b32_e32 v25, v29
	v_permlane16_swap_b32_e32 v26, v30
	v_permlane16_swap_b32_e32 v27, v31
	v_permlane16_swap_b32_e32 v0, v4
	v_permlane16_swap_b32_e32 v1, v5
	v_permlane16_swap_b32_e32 v2, v6
	v_permlane16_swap_b32_e32 v3, v7
	v_permlane16_swap_b32_e32 v8, v12
	v_permlane16_swap_b32_e32 v9, v13
	v_permlane16_swap_b32_e32 v10, v14
	v_permlane16_swap_b32_e32 v11, v15
	v_permlane32_swap_b32_e32 v16, v20
	v_permlane32_swap_b32_e32 v17, v21
	v_permlane32_swap_b32_e32 v18, v22
	v_permlane32_swap_b32_e32 v19, v23
	v_permlane32_swap_b32_e32 v24, v28
	v_permlane32_swap_b32_e32 v25, v29
	v_permlane32_swap_b32_e32 v26, v30
	v_permlane32_swap_b32_e32 v27, v31
	v_permlane32_swap_b32_e32 v0, v4
	v_permlane32_swap_b32_e32 v1, v5
	v_permlane32_swap_b32_e32 v2, v6
	v_permlane32_swap_b32_e32 v3, v7
	v_permlane32_swap_b32_e32 v8, v12
	v_permlane32_swap_b32_e32 v9, v13
	v_permlane32_swap_b32_e32 v10, v14
	v_permlane32_swap_b32_e32 v11, v15
	s_waitcnt lgkmcnt(3)
	v_mfma_f32_16x16x32_bf16 v[80:83], v[144:147], v[236:239], v[80:83]
	v_mfma_f32_16x16x32_bf16 v[88:91], v[148:151], v[236:239], v[88:91]
	v_mfma_f32_16x16x32_bf16 v[48:51], v[152:155], v[236:239], v[48:51]
	v_mfma_f32_16x16x32_bf16 v[56:59], v[156:159], v[236:239], v[56:59]
	s_waitcnt lgkmcnt(2)
	v_mfma_f32_16x16x32_bf16 v[84:87], v[144:147], v[240:243], v[84:87]
	v_mfma_f32_16x16x32_bf16 v[92:95], v[148:151], v[240:243], v[92:95]
	v_mfma_f32_16x16x32_bf16 v[52:55], v[152:155], v[240:243], v[52:55]
	v_mfma_f32_16x16x32_bf16 v[60:63], v[156:159], v[240:243], v[60:63]
	v_permlane16_swap_b32_e32 v112, v116
	v_permlane16_swap_b32_e32 v113, v117
	v_permlane16_swap_b32_e32 v114, v118
	v_permlane16_swap_b32_e32 v115, v119
	v_permlane16_swap_b32_e32 v120, v124
	v_permlane16_swap_b32_e32 v121, v125
	v_permlane16_swap_b32_e32 v122, v126
	v_permlane16_swap_b32_e32 v123, v127
	v_permlane16_swap_b32_e32 v96, v100
	v_permlane16_swap_b32_e32 v97, v101
	v_permlane16_swap_b32_e32 v98, v102
	v_permlane16_swap_b32_e32 v99, v103
	v_permlane16_swap_b32_e32 v104, v108
	v_permlane16_swap_b32_e32 v105, v109
	v_permlane16_swap_b32_e32 v106, v110
	v_permlane16_swap_b32_e32 v107, v111
	v_permlane32_swap_b32_e32 v112, v116
	v_permlane32_swap_b32_e32 v113, v117
	v_permlane32_swap_b32_e32 v114, v118
	v_permlane32_swap_b32_e32 v115, v119
	v_permlane32_swap_b32_e32 v120, v124
	v_permlane32_swap_b32_e32 v121, v125
	v_permlane32_swap_b32_e32 v122, v126
	v_permlane32_swap_b32_e32 v123, v127
	v_permlane32_swap_b32_e32 v96, v100
	v_permlane32_swap_b32_e32 v97, v101
	v_permlane32_swap_b32_e32 v98, v102
	v_permlane32_swap_b32_e32 v99, v103
	v_permlane32_swap_b32_e32 v104, v108
	v_permlane32_swap_b32_e32 v105, v109
	v_permlane32_swap_b32_e32 v106, v110
	v_permlane32_swap_b32_e32 v107, v111
	s_waitcnt lgkmcnt(1)
	v_mfma_f32_16x16x32_bf16 v[64:67], v[144:147], v[244:247], v[64:67]
	v_mfma_f32_16x16x32_bf16 v[72:75], v[148:151], v[244:247], v[72:75]
	v_mfma_f32_16x16x32_bf16 v[32:35], v[152:155], v[244:247], v[32:35]
	v_mfma_f32_16x16x32_bf16 v[40:43], v[156:159], v[244:247], v[40:43]
	s_waitcnt lgkmcnt(0)
	v_mfma_f32_16x16x32_bf16 v[68:71], v[144:147], v[248:251], v[68:71]
	v_mfma_f32_16x16x32_bf16 v[76:79], v[148:151], v[248:251], v[76:79]
	v_mfma_f32_16x16x32_bf16 v[36:39], v[152:155], v[248:251], v[36:39]
	v_mfma_f32_16x16x32_bf16 v[44:47], v[156:159], v[248:251], v[44:47]
	v_permlane16_swap_b32_e32 v80, v84
	v_permlane16_swap_b32_e32 v81, v85
	v_permlane16_swap_b32_e32 v82, v86
	v_permlane16_swap_b32_e32 v83, v87
	v_permlane16_swap_b32_e32 v88, v92
	v_permlane16_swap_b32_e32 v89, v93
	v_permlane16_swap_b32_e32 v90, v94
	v_permlane16_swap_b32_e32 v91, v95
	v_permlane16_swap_b32_e32 v48, v52
	v_permlane16_swap_b32_e32 v49, v53
	v_permlane16_swap_b32_e32 v50, v54
	v_permlane16_swap_b32_e32 v51, v55
	v_permlane16_swap_b32_e32 v56, v60
	v_permlane16_swap_b32_e32 v57, v61
	v_permlane16_swap_b32_e32 v58, v62
	v_permlane16_swap_b32_e32 v59, v63
	v_permlane32_swap_b32_e32 v80, v84
	v_permlane32_swap_b32_e32 v81, v85
	v_permlane32_swap_b32_e32 v82, v86
	v_permlane32_swap_b32_e32 v83, v87
	v_permlane32_swap_b32_e32 v88, v92
	v_permlane32_swap_b32_e32 v89, v93
	v_permlane32_swap_b32_e32 v90, v94
	v_permlane32_swap_b32_e32 v91, v95
	v_permlane32_swap_b32_e32 v48, v52
	v_permlane32_swap_b32_e32 v49, v53
	v_permlane32_swap_b32_e32 v50, v54
	v_permlane32_swap_b32_e32 v51, v55
	v_permlane32_swap_b32_e32 v56, v60
	v_permlane32_swap_b32_e32 v57, v61
	v_permlane32_swap_b32_e32 v58, v62
	v_permlane32_swap_b32_e32 v59, v63
	s_barrier
	s_setprio 0
	s_nop 7
	v_permlane16_swap_b32_e32 v64, v68
	v_permlane16_swap_b32_e32 v65, v69
	v_permlane16_swap_b32_e32 v66, v70
	v_permlane16_swap_b32_e32 v67, v71
	v_permlane16_swap_b32_e32 v72, v76
	v_permlane16_swap_b32_e32 v73, v77
	v_permlane16_swap_b32_e32 v74, v78
	v_permlane16_swap_b32_e32 v75, v79
	v_permlane16_swap_b32_e32 v32, v36
	v_permlane16_swap_b32_e32 v33, v37
	v_permlane16_swap_b32_e32 v34, v38
	v_permlane16_swap_b32_e32 v35, v39
	v_permlane16_swap_b32_e32 v40, v44
	v_permlane16_swap_b32_e32 v41, v45
	v_permlane16_swap_b32_e32 v42, v46
	v_permlane16_swap_b32_e32 v43, v47
	v_permlane32_swap_b32_e32 v64, v68
	v_permlane32_swap_b32_e32 v65, v69
	v_permlane32_swap_b32_e32 v66, v70
	v_permlane32_swap_b32_e32 v67, v71
	v_permlane32_swap_b32_e32 v72, v76
	v_permlane32_swap_b32_e32 v73, v77
	v_permlane32_swap_b32_e32 v74, v78
	v_permlane32_swap_b32_e32 v75, v79
	v_permlane32_swap_b32_e32 v32, v36
	v_permlane32_swap_b32_e32 v33, v37
	v_permlane32_swap_b32_e32 v34, v38
	v_permlane32_swap_b32_e32 v35, v39
	v_permlane32_swap_b32_e32 v40, v44
	v_permlane32_swap_b32_e32 v41, v45
	v_permlane32_swap_b32_e32 v42, v46
	v_permlane32_swap_b32_e32 v43, v47
	s_waitcnt vmcnt(0)
	s_lshl_b32 s12, s2, 8
	s_cmp_eq_u32 s0, 23
	s_mov_b64 s[2:3], -1
	s_cbranch_scc1 .LBB0_347
	s_movk_i32 s1, 0x2400
	s_waitcnt vmcnt(6)
	v_and_b32_e32 v130, 0xffffffc0, v181
	s_cmp_gt_i32 s0, 10
	v_mul_lo_u32 v129, v233, s1
	v_and_b32_e32 v128, 56, v234
	v_add_u32_e32 v131, s12, v130
	s_cselect_b64 s[2:3], -1, 0
	s_cmp_gt_u32 s0, 19
	v_mul_u32_u24_e32 v130, 0x120, v183
	s_waitcnt vmcnt(0)
	v_lshl_or_b32 v132, v128, 1, v129
	v_lshl_or_b32 v128, s0, 7, v128
	s_cselect_b64 s[0:1], -1, 0
	v_lshl_add_u32 v129, v130, 1, v129
	v_lshl_or_b32 v130, v231, 1, v129
	v_cvt_pk_bf16_f32 v112, v112, s0
	ds_write_b16 v130, v112 offset:64
	v_cvt_pk_bf16_f32 v112, v17, s0
	v_cvt_pk_bf16_f32 v96, v96, s0
	ds_write_b16 v130, v112 offset:144
	v_cvt_pk_bf16_f32 v112, v113, s0
	ds_write_b16 v130, v96 offset:4672
	v_cvt_pk_bf16_f32 v96, v1, s0
	ds_write_b16 v130, v112 offset:208
	v_cvt_pk_bf16_f32 v112, v18, s0
	ds_write_b16 v130, v96 offset:4752
	v_cvt_pk_bf16_f32 v96, v97, s0
	ds_write_b16 v130, v112 offset:288
	v_cvt_pk_bf16_f32 v112, v114, s0
	ds_write_b16 v130, v96 offset:4816
	v_cvt_pk_bf16_f32 v96, v2, s0
	ds_write_b16 v130, v112 offset:352
	v_cvt_pk_bf16_f32 v112, v19, s0
	ds_write_b16 v130, v96 offset:4896
	v_cvt_pk_bf16_f32 v96, v98, s0
	ds_write_b16 v130, v112 offset:432
	v_cvt_pk_bf16_f32 v112, v115, s0
	ds_write_b16 v130, v96 offset:4960
	v_cvt_pk_bf16_f32 v96, v3, s0
	ds_write_b16 v130, v112 offset:496
	v_cvt_pk_bf16_f32 v112, v20, s0
	ds_write_b16 v130, v96 offset:5040
	v_cvt_pk_bf16_f32 v96, v99, s0
	ds_write_b16 v130, v112 offset:1152
	v_cvt_pk_bf16_f32 v112, v116, s0
	ds_write_b16 v130, v96 offset:5104
	v_cvt_pk_bf16_f32 v96, v4, s0
	ds_write_b16 v130, v112 offset:1216
	v_cvt_pk_bf16_f32 v112, v21, s0
	ds_write_b16 v130, v96 offset:5760
	v_cvt_pk_bf16_f32 v96, v100, s0
	ds_write_b16 v130, v112 offset:1296
	v_cvt_pk_bf16_f32 v112, v117, s0
	ds_write_b16 v130, v96 offset:5824
	v_cvt_pk_bf16_f32 v96, v5, s0
	ds_write_b16 v130, v112 offset:1360
	v_cvt_pk_bf16_f32 v112, v22, s0
	ds_write_b16 v130, v96 offset:5904
	v_cvt_pk_bf16_f32 v96, v101, s0
	ds_write_b16 v130, v112 offset:1440
	v_cvt_pk_bf16_f32 v112, v118, s0
	ds_write_b16 v130, v96 offset:5968
	v_cvt_pk_bf16_f32 v96, v6, s0
	ds_write_b16 v130, v112 offset:1504
	v_cvt_pk_bf16_f32 v112, v23, s0
	ds_write_b16 v130, v96 offset:6048
	v_cvt_pk_bf16_f32 v96, v102, s0
	ds_write_b16 v130, v112 offset:1584
	v_cvt_pk_bf16_f32 v112, v119, s0
	ds_write_b16 v130, v96 offset:6112
	v_cvt_pk_bf16_f32 v96, v7, s0
	ds_write_b16 v130, v112 offset:1648
	v_cvt_pk_bf16_f32 v112, v24, s0
	ds_write_b16 v130, v96 offset:6192
	v_cvt_pk_bf16_f32 v96, v103, s0
	ds_write_b16 v130, v112 offset:2304
	v_cvt_pk_bf16_f32 v112, v120, s0
	ds_write_b16 v130, v96 offset:6256
	v_cvt_pk_bf16_f32 v96, v8, s0
	ds_write_b16 v130, v112 offset:2368
	v_cvt_pk_bf16_f32 v112, v25, s0
	ds_write_b16 v130, v96 offset:6912
	v_cvt_pk_bf16_f32 v96, v104, s0
	ds_write_b16 v130, v112 offset:2448
	v_cvt_pk_bf16_f32 v112, v121, s0
	ds_write_b16 v130, v96 offset:6976
	v_cvt_pk_bf16_f32 v96, v9, s0
	ds_write_b16 v130, v112 offset:2512
	v_cvt_pk_bf16_f32 v112, v26, s0
	ds_write_b16 v130, v96 offset:7056
	v_cvt_pk_bf16_f32 v96, v105, s0
	ds_write_b16 v130, v112 offset:2592
	v_cvt_pk_bf16_f32 v112, v122, s0
	ds_write_b16 v130, v96 offset:7120
	v_cvt_pk_bf16_f32 v96, v10, s0
	ds_write_b16 v130, v112 offset:2656
	v_cvt_pk_bf16_f32 v112, v27, s0
	ds_write_b16 v130, v96 offset:7200
	v_cvt_pk_bf16_f32 v96, v106, s0
	ds_write_b16 v130, v112 offset:2736
	v_cvt_pk_bf16_f32 v112, v123, s0
	ds_write_b16 v130, v96 offset:7264
	v_cvt_pk_bf16_f32 v96, v11, s0
	ds_write_b16 v130, v112 offset:2800
	v_cvt_pk_bf16_f32 v112, v28, s0
	ds_write_b16 v130, v96 offset:7344
	v_cvt_pk_bf16_f32 v96, v107, s0
	ds_write_b16 v130, v112 offset:3456
	v_cvt_pk_bf16_f32 v112, v124, s0
	ds_write_b16 v130, v96 offset:7408
	v_cvt_pk_bf16_f32 v96, v12, s0
	ds_write_b16 v130, v112 offset:3520
	v_cvt_pk_bf16_f32 v112, v29, s0
	ds_write_b16 v130, v96 offset:8064
	v_cvt_pk_bf16_f32 v96, v108, s0
	ds_write_b16 v130, v112 offset:3600
	v_cvt_pk_bf16_f32 v112, v125, s0
	ds_write_b16 v130, v96 offset:8128
	v_cvt_pk_bf16_f32 v96, v13, s0
	ds_write_b16 v130, v112 offset:3664
	v_cvt_pk_bf16_f32 v112, v30, s0
	ds_write_b16 v130, v96 offset:8208
	v_cvt_pk_bf16_f32 v96, v109, s0
	ds_write_b16 v130, v112 offset:3744
	v_cvt_pk_bf16_f32 v112, v126, s0
	ds_write_b16 v130, v96 offset:8272
	v_cvt_pk_bf16_f32 v96, v14, s0
	ds_write_b16 v130, v112 offset:3808
	v_cvt_pk_bf16_f32 v112, v31, s0
	ds_write_b16 v130, v96 offset:8352
	v_cvt_pk_bf16_f32 v96, v110, s0
	ds_write_b16 v130, v112 offset:3888
	v_cvt_pk_bf16_f32 v112, v127, s0
	ds_write_b16 v130, v96 offset:8416
	v_cvt_pk_bf16_f32 v96, v15, s0
	v_cvt_pk_bf16_f32 v133, v16, s0
	ds_write_b16 v130, v112 offset:3952
	v_cvt_pk_bf16_f32 v112, v0, s0
	ds_write_b16 v130, v96 offset:8496
	v_cvt_pk_bf16_f32 v96, v111, s0
	ds_write_b16 v130, v133
	ds_write_b16 v130, v112 offset:4608
	ds_write_b16 v130, v96 offset:8560
	v_lshrrev_b32_e32 v109, 3, v232
	s_waitcnt lgkmcnt(0)
	v_mad_u32_u24 v96, v109, s42, v132
	ds_read_b128 v[96:99], v96
	v_mov_b32_e32 v176, v128
	v_or_b32_e32 v110, v131, v109
	s_mov_b64 s[4:5], -1
	s_and_b64 vcc, exec, s[2:3]
	s_cbranch_vccz .LBB0_224
	s_and_b64 vcc, exec, s[0:1]
	s_cbranch_vccz .LBB0_221
	v_readlane_b32 s16, v254, 15
	v_readlane_b32 s18, v254, 17
	v_readlane_b32 s19, v254, 18
	v_readlane_b32 s17, v254, 16
	v_readlane_b32 s20, v254, 19
	v_mov_b64_e32 v[100:101], s[18:19]
	v_mad_i64_i32 v[100:101], s[4:5], v110, s89, v[100:101]
	s_movk_i32 s4, 0xec00
	v_lshl_add_u64 v[100:101], v[176:177], 1, v[100:101]
	s_mov_b32 s5, -1
	v_readlane_b32 s21, v254, 20
	v_readlane_b32 s22, v254, 21
	v_readlane_b32 s23, v254, 22
	v_readlane_b32 s24, v254, 23
	v_readlane_b32 s25, v254, 24
	v_readlane_b32 s26, v254, 25
	v_readlane_b32 s27, v254, 26
	v_readlane_b32 s28, v254, 27
	v_readlane_b32 s29, v254, 28
	v_readlane_b32 s30, v254, 29
	v_readlane_b32 s31, v254, 30
	v_lshl_add_u64 v[100:101], v[100:101], 0, s[4:5]
	s_mov_b64 s[4:5], 0

.LBB0_923:
	s_ashr_i32 s2, s4, 31
	s_lshr_b32 s2, s2, 26
	s_add_i32 s2, s4, s2
	s_ashr_i32 s3, s2, 6
	s_lshl_b32 s3, s3, 3
	s_sub_i32 s8, s25, s3
	s_min_i32 s8, s8, 8
	s_abs_i32 s9, s8
	v_cvt_f32_u32_e32 v0, s9
	s_sub_i32 s12, 0, s9
	s_andn2_b32 s2, s2, 63
	s_sub_i32 s10, s4, s2
	v_rcp_iflag_f32_e32 v0, v0
	s_abs_i32 s2, s10
	s_xor_b32 s11, s10, s8
	s_ashr_i32 s11, s11, 31
	v_mul_f32_e32 v0, 0x4f7ffffe, v0
	v_cvt_u32_f32_e32 v0, v0
	v_mov_b32_e32 v181, v179
	v_readfirstlane_b32 s13, v0
	s_mul_i32 s12, s12, s13
	s_mul_hi_u32 s12, s13, s12
	s_add_i32 s13, s13, s12
	s_mul_hi_u32 s12, s2, s13
	s_mul_i32 s13, s12, s9
	s_sub_i32 s2, s2, s13
	s_add_i32 s14, s12, 1
	s_sub_i32 s13, s2, s9
	s_cmp_ge_u32 s2, s9
	s_cselect_b32 s12, s14, s12
	s_cselect_b32 s2, s13, s2
	s_add_i32 s13, s12, 1
	s_cmp_ge_u32 s2, s9
	s_cselect_b32 s2, s13, s12
	s_xor_b32 s2, s2, s11
	s_sub_i32 s2, s2, s11
	s_mul_i32 s8, s8, s2
	s_add_i32 s3, s3, s7
	s_sub_i32 s8, s10, s8
	v_ashrrev_i32_e32 v237, 6, v181
	s_add_i32 s8, s3, s8
	v_lshlrev_b32_e32 v0, 1, v237
	v_lshl_add_u32 v0, s8, 3, v0
	v_ashrrev_i32_e32 v1, 31, v0
	v_bfe_u32 v183, v181, 5, 1
	v_lshlrev_b64 v[0:1], 16, v[0:1]
	v_and_b32_e32 v238, 31, v181
	v_lshl_add_u64 v[0:1], s[64:65], 0, v[0:1]
	v_lshlrev_b32_e32 v176, 9, v183
	s_ashr_i32 s3, s2, 31
	v_lshl_add_u64 v[0:1], v[0:1], 0, v[176:177]
	v_lshlrev_b32_e32 v176, 4, v238
	v_ashrrev_i32_e32 v40, 2, v181
	s_lshl_b64 s[10:11], s[2:3], 18
	v_lshl_add_u64 v[184:185], v[0:1], 0, v[176:177]
	s_add_u32 s10, s5, s10
	v_lshlrev_b32_e32 v0, 5, v40
	s_addc_u32 s11, s6, s11
	v_ashrrev_i32_e32 v1, 31, v0
	v_lshlrev_b32_e32 v2, 4, v181
	v_lshl_add_u64 v[0:1], v[0:1], 1, s[10:11]
	v_and_b32_e32 v176, 48, v2
	v_lshl_add_u64 v[186:187], v[0:1], 0, v[176:177]
	s_movk_i32 s3, 0x2000
	v_add_co_u32_e32 v36, vcc, s3, v186
	v_mul_u32_u24_e32 v38, 40, v238
	s_nop 0
	v_addc_co_u32_e32 v37, vcc, 0, v187, vcc
	v_lshlrev_b32_e32 v39, 4, v183
	v_lshl_add_u32 v240, v38, 1, v39
	v_add_co_u32_e32 v38, vcc, s41, v184
	s_movk_i32 s9, 0x50
	s_nop 0
	v_addc_co_u32_e32 v39, vcc, 0, v185, vcc
	v_and_b32_e32 v239, 63, v181
	v_bfe_u32 v247, v181, 4, 2
	v_lshlrev_b32_e32 v247, 1, v247
	v_mov_b32_e32 v176, 0x78
	v_lshrrev_b32_e32 v247, v247, v176
	v_and_b32_e32 v247, 3, v247
	v_and_b32_e32 v246, 3, v181
	v_xor_b32_e32 v247, v247, v246
	v_lshlrev_b32_e32 v247, 4, v247
	v_and_b32_e32 v188, 0xffffffcf, v186
	v_or_b32_e32 v188, v188, v247
	v_mov_b32_e32 v189, v187
	v_lshrrev_b32_e32 v176, 6, v181
	v_lshlrev_b32_e32 v247, 11, v176
	v_lshlrev_b32_e32 v176, 10, v176
	v_lshl_add_u64 v[188:189], v[188:189], 0, v[176:177]
	v_readfirstlane_b32 vcc_lo, v247
	v_bfe_u32 v247, v181, 4, 1
	v_lshlrev_b32_e32 v176, 9, v183
	v_lshl_add_u32 v176, v247, 8, v176
	v_lshl_add_u64 v[184:185], v[184:185], 0, v[176:177]
	v_mov_b32_e32 v176, s41
	v_lshl_add_u64 v[186:187], v[184:185], 0, v[176:177]
	v_mov_b32_e32 v176, 0x78
	v_bfe_u32 v247, v181, 2, 2
	v_lshlrev_b32_e32 v247, 1, v247
	v_lshrrev_b32_e32 v247, v247, v176
	v_and_b32_e32 v247, 3, v247
	v_bfe_u32 v246, v181, 4, 2
	v_xor_b32_e32 v247, v247, v246
	v_lshlrev_b32_e32 v247, 4, v247
	v_and_b32_e32 v246, 15, v181
	v_lshl_add_u32 v246, v246, 6, v247
	s_mov_b32 s96, 0
	s_mov_b32 m0, vcc_lo
	v_lshl_add_u64 v[160:161], v[188:189], 0, s[96:97]
	global_load_lds_dwordx4 v[160:161], off
	global_load_lds_dwordx4 v[160:161], off offset:1024
	s_mov_b32 s96, 0
	v_lshl_add_u64 v[248:249], v[184:185], 0, s[96:97]
	v_lshl_add_u64 v[250:251], v[186:187], 0, s[96:97]
	global_load_dwordx4 v[128:131], v[248:249], off
	global_load_dwordx4 v[132:135], v[248:249], off offset:256
	global_load_dwordx4 v[136:139], v[250:251], off
	global_load_dwordx4 v[140:143], v[250:251], off offset:256
	s_movk_i32 s96, 0x2000
	s_add_i32 m0, vcc_lo, 8192
	v_lshl_add_u64 v[160:161], v[188:189], 0, s[96:97]
	global_load_lds_dwordx4 v[160:161], off
	global_load_lds_dwordx4 v[160:161], off offset:1024
	s_movk_i32 s96, 0x800
	v_lshl_add_u64 v[248:249], v[184:185], 0, s[96:97]
	v_lshl_add_u64 v[250:251], v[186:187], 0, s[96:97]
	global_load_dwordx4 v[144:147], v[248:249], off
	global_load_dwordx4 v[148:151], v[248:249], off offset:256
	global_load_dwordx4 v[152:155], v[250:251], off
	global_load_dwordx4 v[156:159], v[250:251], off offset:256
	v_mov_b32_e32 v0, 0
	v_mov_b32_e32 v1, 0
	v_mov_b32_e32 v2, 0
	v_mov_b32_e32 v3, 0
	v_mov_b32_e32 v4, 0
	v_mov_b32_e32 v5, 0
	v_mov_b32_e32 v6, 0
	v_mov_b32_e32 v7, 0
	v_mov_b32_e32 v8, 0
	v_mov_b32_e32 v9, 0
	v_mov_b32_e32 v10, 0
	v_mov_b32_e32 v11, 0
	v_mov_b32_e32 v12, 0
	v_mov_b32_e32 v13, 0
	v_mov_b32_e32 v14, 0
	v_mov_b32_e32 v15, 0
	v_mov_b32_e32 v16, 0
	v_mov_b32_e32 v17, 0
	v_mov_b32_e32 v18, 0
	v_mov_b32_e32 v19, 0
	v_mov_b32_e32 v20, 0
	v_mov_b32_e32 v21, 0
	v_mov_b32_e32 v22, 0
	v_mov_b32_e32 v23, 0
	v_mov_b32_e32 v24, 0
	v_mov_b32_e32 v25, 0
	v_mov_b32_e32 v26, 0
	v_mov_b32_e32 v27, 0
	v_mov_b32_e32 v28, 0
	v_mov_b32_e32 v29, 0
	v_mov_b32_e32 v30, 0
	v_mov_b32_e32 v31, 0
	v_mov_b32_e32 v32, 0
	v_mov_b32_e32 v33, 0
	v_mov_b32_e32 v34, 0
	v_mov_b32_e32 v35, 0
	v_mov_b32_e32 v36, 0
	v_mov_b32_e32 v37, 0
	v_mov_b32_e32 v38, 0
	v_mov_b32_e32 v39, 0
	v_mov_b32_e32 v40, 0
	v_mov_b32_e32 v41, 0
	v_mov_b32_e32 v42, 0
	v_mov_b32_e32 v43, 0
	v_mov_b32_e32 v44, 0
	v_mov_b32_e32 v45, 0
	v_mov_b32_e32 v46, 0
	v_mov_b32_e32 v47, 0
	v_mov_b32_e32 v48, 0
	v_mov_b32_e32 v49, 0
	v_mov_b32_e32 v50, 0
	v_mov_b32_e32 v51, 0
	v_mov_b32_e32 v52, 0
	v_mov_b32_e32 v53, 0
	v_mov_b32_e32 v54, 0
	v_mov_b32_e32 v55, 0
	v_mov_b32_e32 v56, 0
	v_mov_b32_e32 v57, 0
	v_mov_b32_e32 v58, 0
	v_mov_b32_e32 v59, 0
	v_mov_b32_e32 v60, 0
	v_mov_b32_e32 v61, 0
	v_mov_b32_e32 v62, 0
	v_mov_b32_e32 v63, 0
	v_mov_b32_e32 v64, 0
	v_mov_b32_e32 v65, 0
	v_mov_b32_e32 v66, 0
	v_mov_b32_e32 v67, 0
	v_mov_b32_e32 v68, 0
	v_mov_b32_e32 v69, 0
	v_mov_b32_e32 v70, 0
	v_mov_b32_e32 v71, 0
	v_mov_b32_e32 v72, 0
	v_mov_b32_e32 v73, 0
	v_mov_b32_e32 v74, 0
	v_mov_b32_e32 v75, 0
	v_mov_b32_e32 v76, 0
	v_mov_b32_e32 v77, 0
	v_mov_b32_e32 v78, 0
	v_mov_b32_e32 v79, 0
	v_mov_b32_e32 v80, 0
	v_mov_b32_e32 v81, 0
	v_mov_b32_e32 v82, 0
	v_mov_b32_e32 v83, 0
	v_mov_b32_e32 v84, 0
	v_mov_b32_e32 v85, 0
	v_mov_b32_e32 v86, 0
	v_mov_b32_e32 v87, 0
	v_mov_b32_e32 v88, 0
	v_mov_b32_e32 v89, 0
	v_mov_b32_e32 v90, 0
	v_mov_b32_e32 v91, 0
	v_mov_b32_e32 v92, 0
	v_mov_b32_e32 v93, 0
	v_mov_b32_e32 v94, 0
	v_mov_b32_e32 v95, 0
	v_mov_b32_e32 v96, 0
	v_mov_b32_e32 v97, 0
	v_mov_b32_e32 v98, 0
	v_mov_b32_e32 v99, 0
	v_mov_b32_e32 v100, 0
	v_mov_b32_e32 v101, 0
	v_mov_b32_e32 v102, 0
	v_mov_b32_e32 v103, 0
	v_mov_b32_e32 v104, 0
	v_mov_b32_e32 v105, 0
	v_mov_b32_e32 v106, 0
	v_mov_b32_e32 v107, 0
	v_mov_b32_e32 v108, 0
	v_mov_b32_e32 v109, 0
	v_mov_b32_e32 v110, 0
	v_mov_b32_e32 v111, 0
	v_mov_b32_e32 v112, 0
	v_mov_b32_e32 v113, 0
	v_mov_b32_e32 v114, 0
	v_mov_b32_e32 v115, 0
	v_mov_b32_e32 v116, 0
	v_mov_b32_e32 v117, 0
	v_mov_b32_e32 v118, 0
	v_mov_b32_e32 v119, 0
	v_mov_b32_e32 v120, 0
	v_mov_b32_e32 v121, 0
	v_mov_b32_e32 v122, 0
	v_mov_b32_e32 v123, 0
	v_mov_b32_e32 v124, 0
	v_mov_b32_e32 v125, 0
	v_mov_b32_e32 v126, 0
	v_mov_b32_e32 v127, 0
	s_mov_b32 s3, 0
	s_waitcnt vmcnt(4)
	s_barrier
	s_setprio 2
.Lg16_out_k:
	s_add_i32 s9, s3, 2
	s_lshl_b32 s96, s9, 13
	s_add_i32 m0, vcc_lo, 16384
	v_lshl_add_u64 v[160:161], v[188:189], 0, s[96:97]
	global_load_lds_dwordx4 v[160:161], off
	global_load_lds_dwordx4 v[160:161], off offset:1024
	ds_read_b128 v[196:199], v246 offset:0
	ds_read_b128 v[200:203], v246 offset:1024
	ds_read_b128 v[204:207], v246 offset:2048
	ds_read_b128 v[242:245], v246 offset:3072
	s_add_i32 s9, s3, 2
	s_lshl_b32 s96, s9, 11
	v_lshl_add_u64 v[248:249], v[184:185], 0, s[96:97]
	v_lshl_add_u64 v[250:251], v[186:187], 0, s[96:97]
	s_waitcnt vmcnt(8) lgkmcnt(3)
	v_mfma_f32_16x16x32_bf16 v[112:115], v[128:131], v[196:199], v[112:115]
	v_mfma_f32_16x16x32_bf16 v[120:123], v[132:135], v[196:199], v[120:123]
	v_mfma_f32_16x16x32_bf16 v[48:51], v[136:139], v[196:199], v[48:51]
	v_mfma_f32_16x16x32_bf16 v[56:59], v[140:143], v[196:199], v[56:59]
	ds_read_b128 v[196:199], v246 offset:4096
	s_waitcnt lgkmcnt(3)
	v_mfma_f32_16x16x32_bf16 v[116:119], v[128:131], v[200:203], v[116:119]
	v_mfma_f32_16x16x32_bf16 v[124:127], v[132:135], v[200:203], v[124:127]
	v_mfma_f32_16x16x32_bf16 v[52:55], v[136:139], v[200:203], v[52:55]
	v_mfma_f32_16x16x32_bf16 v[60:63], v[140:143], v[200:203], v[60:63]
	ds_read_b128 v[200:203], v246 offset:5120
	s_waitcnt lgkmcnt(3)
	v_mfma_f32_16x16x32_bf16 v[96:99], v[128:131], v[204:207], v[96:99]
	v_mfma_f32_16x16x32_bf16 v[104:107], v[132:135], v[204:207], v[104:107]
	v_mfma_f32_16x16x32_bf16 v[32:35], v[136:139], v[204:207], v[32:35]
	v_mfma_f32_16x16x32_bf16 v[40:43], v[140:143], v[204:207], v[40:43]
	ds_read_b128 v[204:207], v246 offset:6144
	s_waitcnt lgkmcnt(3)
	v_mfma_f32_16x16x32_bf16 v[100:103], v[128:131], v[242:245], v[100:103]
	v_mfma_f32_16x16x32_bf16 v[108:111], v[132:135], v[242:245], v[108:111]
	v_mfma_f32_16x16x32_bf16 v[36:39], v[136:139], v[242:245], v[36:39]
	v_mfma_f32_16x16x32_bf16 v[44:47], v[140:143], v[242:245], v[44:47]
	ds_read_b128 v[242:245], v246 offset:7168
	s_waitcnt lgkmcnt(3)
	v_mfma_f32_16x16x32_bf16 v[80:83], v[128:131], v[196:199], v[80:83]
	v_mfma_f32_16x16x32_bf16 v[88:91], v[132:135], v[196:199], v[88:91]
	v_mfma_f32_16x16x32_bf16 v[16:19], v[136:139], v[196:199], v[16:19]
	v_mfma_f32_16x16x32_bf16 v[24:27], v[140:143], v[196:199], v[24:27]
	s_waitcnt lgkmcnt(2)
	v_mfma_f32_16x16x32_bf16 v[84:87], v[128:131], v[200:203], v[84:87]
	v_mfma_f32_16x16x32_bf16 v[92:95], v[132:135], v[200:203], v[92:95]
	v_mfma_f32_16x16x32_bf16 v[20:23], v[136:139], v[200:203], v[20:23]
	v_mfma_f32_16x16x32_bf16 v[28:31], v[140:143], v[200:203], v[28:31]
	s_waitcnt lgkmcnt(1)
	v_mfma_f32_16x16x32_bf16 v[64:67], v[128:131], v[204:207], v[64:67]
	v_mfma_f32_16x16x32_bf16 v[72:75], v[132:135], v[204:207], v[72:75]
	v_mfma_f32_16x16x32_bf16 v[0:3], v[136:139], v[204:207], v[0:3]
	v_mfma_f32_16x16x32_bf16 v[8:11], v[140:143], v[204:207], v[8:11]
	s_waitcnt lgkmcnt(0)
	v_mfma_f32_16x16x32_bf16 v[68:71], v[128:131], v[242:245], v[68:71]
	v_mfma_f32_16x16x32_bf16 v[76:79], v[132:135], v[242:245], v[76:79]
	v_mfma_f32_16x16x32_bf16 v[4:7], v[136:139], v[242:245], v[4:7]
	v_mfma_f32_16x16x32_bf16 v[12:15], v[140:143], v[242:245], v[12:15]
	global_load_dwordx4 v[128:131], v[248:249], off
	global_load_dwordx4 v[132:135], v[248:249], off offset:256
	global_load_dwordx4 v[136:139], v[250:251], off
	global_load_dwordx4 v[140:143], v[250:251], off offset:256
	s_waitcnt vmcnt(10)
	s_barrier
	s_add_i32 s9, s3, 3
	s_lshl_b32 s96, s9, 13
	s_mov_b32 m0, vcc_lo
	v_lshl_add_u64 v[160:161], v[188:189], 0, s[96:97]
	global_load_lds_dwordx4 v[160:161], off
	global_load_lds_dwordx4 v[160:161], off offset:1024
	ds_read_b128 v[196:199], v246 offset:8192
	ds_read_b128 v[200:203], v246 offset:9216
	ds_read_b128 v[204:207], v246 offset:10240
	ds_read_b128 v[242:245], v246 offset:11264
	s_add_i32 s9, s3, 3
	s_lshl_b32 s96, s9, 11
	v_lshl_add_u64 v[248:249], v[184:185], 0, s[96:97]
	v_lshl_add_u64 v[250:251], v[186:187], 0, s[96:97]
	s_waitcnt vmcnt(8) lgkmcnt(3)
	v_mfma_f32_16x16x32_bf16 v[112:115], v[144:147], v[196:199], v[112:115]
	v_mfma_f32_16x16x32_bf16 v[120:123], v[148:151], v[196:199], v[120:123]
	v_mfma_f32_16x16x32_bf16 v[48:51], v[152:155], v[196:199], v[48:51]
	v_mfma_f32_16x16x32_bf16 v[56:59], v[156:159], v[196:199], v[56:59]
	ds_read_b128 v[196:199], v246 offset:12288
	s_waitcnt lgkmcnt(3)
	v_mfma_f32_16x16x32_bf16 v[116:119], v[144:147], v[200:203], v[116:119]
	v_mfma_f32_16x16x32_bf16 v[124:127], v[148:151], v[200:203], v[124:127]
	v_mfma_f32_16x16x32_bf16 v[52:55], v[152:155], v[200:203], v[52:55]
	v_mfma_f32_16x16x32_bf16 v[60:63], v[156:159], v[200:203], v[60:63]
	ds_read_b128 v[200:203], v246 offset:13312
	s_waitcnt lgkmcnt(3)
	v_mfma_f32_16x16x32_bf16 v[96:99], v[144:147], v[204:207], v[96:99]
	v_mfma_f32_16x16x32_bf16 v[104:107], v[148:151], v[204:207], v[104:107]
	v_mfma_f32_16x16x32_bf16 v[32:35], v[152:155], v[204:207], v[32:35]
	v_mfma_f32_16x16x32_bf16 v[40:43], v[156:159], v[204:207], v[40:43]
	ds_read_b128 v[204:207], v246 offset:14336
	s_waitcnt lgkmcnt(3)
	v_mfma_f32_16x16x32_bf16 v[100:103], v[144:147], v[242:245], v[100:103]
	v_mfma_f32_16x16x32_bf16 v[108:111], v[148:151], v[242:245], v[108:111]
	v_mfma_f32_16x16x32_bf16 v[36:39], v[152:155], v[242:245], v[36:39]
	v_mfma_f32_16x16x32_bf16 v[44:47], v[156:159], v[242:245], v[44:47]
	ds_read_b128 v[242:245], v246 offset:15360
	s_waitcnt lgkmcnt(3)
	v_mfma_f32_16x16x32_bf16 v[80:83], v[144:147], v[196:199], v[80:83]
	v_mfma_f32_16x16x32_bf16 v[88:91], v[148:151], v[196:199], v[88:91]
	v_mfma_f32_16x16x32_bf16 v[16:19], v[152:155], v[196:199], v[16:19]
	v_mfma_f32_16x16x32_bf16 v[24:27], v[156:159], v[196:199], v[24:27]
	s_waitcnt lgkmcnt(2)
	v_mfma_f32_16x16x32_bf16 v[84:87], v[144:147], v[200:203], v[84:87]
	v_mfma_f32_16x16x32_bf16 v[92:95], v[148:151], v[200:203], v[92:95]
	v_mfma_f32_16x16x32_bf16 v[20:23], v[152:155], v[200:203], v[20:23]
	v_mfma_f32_16x16x32_bf16 v[28:31], v[156:159], v[200:203], v[28:31]
	s_waitcnt lgkmcnt(1)
	v_mfma_f32_16x16x32_bf16 v[64:67], v[144:147], v[204:207], v[64:67]
	v_mfma_f32_16x16x32_bf16 v[72:75], v[148:151], v[204:207], v[72:75]
	v_mfma_f32_16x16x32_bf16 v[0:3], v[152:155], v[204:207], v[0:3]
	v_mfma_f32_16x16x32_bf16 v[8:11], v[156:159], v[204:207], v[8:11]
	s_waitcnt lgkmcnt(0)
	v_mfma_f32_16x16x32_bf16 v[68:71], v[144:147], v[242:245], v[68:71]
	v_mfma_f32_16x16x32_bf16 v[76:79], v[148:151], v[242:245], v[76:79]
	v_mfma_f32_16x16x32_bf16 v[4:7], v[152:155], v[242:245], v[4:7]
	v_mfma_f32_16x16x32_bf16 v[12:15], v[156:159], v[242:245], v[12:15]
	global_load_dwordx4 v[144:147], v[248:249], off
	global_load_dwordx4 v[148:151], v[248:249], off offset:256
	global_load_dwordx4 v[152:155], v[250:251], off
	global_load_dwordx4 v[156:159], v[250:251], off offset:256
	s_waitcnt vmcnt(10)
	s_barrier
	s_add_i32 s9, s3, 4
	s_lshl_b32 s96, s9, 13
	s_add_i32 m0, vcc_lo, 8192
	v_lshl_add_u64 v[160:161], v[188:189], 0, s[96:97]
	global_load_lds_dwordx4 v[160:161], off
	global_load_lds_dwordx4 v[160:161], off offset:1024
	ds_read_b128 v[196:199], v246 offset:16384
	ds_read_b128 v[200:203], v246 offset:17408
	ds_read_b128 v[204:207], v246 offset:18432
	ds_read_b128 v[242:245], v246 offset:19456
	s_add_i32 s9, s3, 4
	s_lshl_b32 s96, s9, 11
	v_lshl_add_u64 v[248:249], v[184:185], 0, s[96:97]
	v_lshl_add_u64 v[250:251], v[186:187], 0, s[96:97]
	s_waitcnt vmcnt(8) lgkmcnt(3)
	v_mfma_f32_16x16x32_bf16 v[112:115], v[128:131], v[196:199], v[112:115]
	v_mfma_f32_16x16x32_bf16 v[120:123], v[132:135], v[196:199], v[120:123]
	v_mfma_f32_16x16x32_bf16 v[48:51], v[136:139], v[196:199], v[48:51]
	v_mfma_f32_16x16x32_bf16 v[56:59], v[140:143], v[196:199], v[56:59]
	ds_read_b128 v[196:199], v246 offset:20480
	s_waitcnt lgkmcnt(3)
	v_mfma_f32_16x16x32_bf16 v[116:119], v[128:131], v[200:203], v[116:119]
	v_mfma_f32_16x16x32_bf16 v[124:127], v[132:135], v[200:203], v[124:127]
	v_mfma_f32_16x16x32_bf16 v[52:55], v[136:139], v[200:203], v[52:55]
	v_mfma_f32_16x16x32_bf16 v[60:63], v[140:143], v[200:203], v[60:63]
	ds_read_b128 v[200:203], v246 offset:21504
	s_waitcnt lgkmcnt(3)
	v_mfma_f32_16x16x32_bf16 v[96:99], v[128:131], v[204:207], v[96:99]
	v_mfma_f32_16x16x32_bf16 v[104:107], v[132:135], v[204:207], v[104:107]
	v_mfma_f32_16x16x32_bf16 v[32:35], v[136:139], v[204:207], v[32:35]
	v_mfma_f32_16x16x32_bf16 v[40:43], v[140:143], v[204:207], v[40:43]
	ds_read_b128 v[204:207], v246 offset:22528
	s_waitcnt lgkmcnt(3)
	v_mfma_f32_16x16x32_bf16 v[100:103], v[128:131], v[242:245], v[100:103]
	v_mfma_f32_16x16x32_bf16 v[108:111], v[132:135], v[242:245], v[108:111]
	v_mfma_f32_16x16x32_bf16 v[36:39], v[136:139], v[242:245], v[36:39]
	v_mfma_f32_16x16x32_bf16 v[44:47], v[140:143], v[242:245], v[44:47]
	ds_read_b128 v[242:245], v246 offset:23552
	s_waitcnt lgkmcnt(3)
	v_mfma_f32_16x16x32_bf16 v[80:83], v[128:131], v[196:199], v[80:83]
	v_mfma_f32_16x16x32_bf16 v[88:91], v[132:135], v[196:199], v[88:91]
	v_mfma_f32_16x16x32_bf16 v[16:19], v[136:139], v[196:199], v[16:19]
	v_mfma_f32_16x16x32_bf16 v[24:27], v[140:143], v[196:199], v[24:27]
	s_waitcnt lgkmcnt(2)
	v_mfma_f32_16x16x32_bf16 v[84:87], v[128:131], v[200:203], v[84:87]
	v_mfma_f32_16x16x32_bf16 v[92:95], v[132:135], v[200:203], v[92:95]
	v_mfma_f32_16x16x32_bf16 v[20:23], v[136:139], v[200:203], v[20:23]
	v_mfma_f32_16x16x32_bf16 v[28:31], v[140:143], v[200:203], v[28:31]
	s_waitcnt lgkmcnt(1)
	v_mfma_f32_16x16x32_bf16 v[64:67], v[128:131], v[204:207], v[64:67]
	v_mfma_f32_16x16x32_bf16 v[72:75], v[132:135], v[204:207], v[72:75]
	v_mfma_f32_16x16x32_bf16 v[0:3], v[136:139], v[204:207], v[0:3]
	v_mfma_f32_16x16x32_bf16 v[8:11], v[140:143], v[204:207], v[8:11]
	s_waitcnt lgkmcnt(0)
	v_mfma_f32_16x16x32_bf16 v[68:71], v[128:131], v[242:245], v[68:71]
	v_mfma_f32_16x16x32_bf16 v[76:79], v[132:135], v[242:245], v[76:79]
	v_mfma_f32_16x16x32_bf16 v[4:7], v[136:139], v[242:245], v[4:7]
	v_mfma_f32_16x16x32_bf16 v[12:15], v[140:143], v[242:245], v[12:15]
	global_load_dwordx4 v[128:131], v[248:249], off
	global_load_dwordx4 v[132:135], v[248:249], off offset:256
	global_load_dwordx4 v[136:139], v[250:251], off
	global_load_dwordx4 v[140:143], v[250:251], off offset:256
	s_waitcnt vmcnt(10)
	s_barrier
	s_add_i32 s9, s3, 5
	s_lshl_b32 s96, s9, 13
	s_add_i32 m0, vcc_lo, 16384
	v_lshl_add_u64 v[160:161], v[188:189], 0, s[96:97]
	global_load_lds_dwordx4 v[160:161], off
	global_load_lds_dwordx4 v[160:161], off offset:1024
	ds_read_b128 v[196:199], v246 offset:0
	ds_read_b128 v[200:203], v246 offset:1024
	ds_read_b128 v[204:207], v246 offset:2048
	ds_read_b128 v[242:245], v246 offset:3072
	s_add_i32 s9, s3, 5
	s_lshl_b32 s96, s9, 11
	v_lshl_add_u64 v[248:249], v[184:185], 0, s[96:97]
	v_lshl_add_u64 v[250:251], v[186:187], 0, s[96:97]
	s_waitcnt vmcnt(8) lgkmcnt(3)
	v_mfma_f32_16x16x32_bf16 v[112:115], v[144:147], v[196:199], v[112:115]
	v_mfma_f32_16x16x32_bf16 v[120:123], v[148:151], v[196:199], v[120:123]
	v_mfma_f32_16x16x32_bf16 v[48:51], v[152:155], v[196:199], v[48:51]
	v_mfma_f32_16x16x32_bf16 v[56:59], v[156:159], v[196:199], v[56:59]
	ds_read_b128 v[196:199], v246 offset:4096
	s_waitcnt lgkmcnt(3)
	v_mfma_f32_16x16x32_bf16 v[116:119], v[144:147], v[200:203], v[116:119]
	v_mfma_f32_16x16x32_bf16 v[124:127], v[148:151], v[200:203], v[124:127]
	v_mfma_f32_16x16x32_bf16 v[52:55], v[152:155], v[200:203], v[52:55]
	v_mfma_f32_16x16x32_bf16 v[60:63], v[156:159], v[200:203], v[60:63]
	ds_read_b128 v[200:203], v246 offset:5120
	s_waitcnt lgkmcnt(3)
	v_mfma_f32_16x16x32_bf16 v[96:99], v[144:147], v[204:207], v[96:99]
	v_mfma_f32_16x16x32_bf16 v[104:107], v[148:151], v[204:207], v[104:107]
	v_mfma_f32_16x16x32_bf16 v[32:35], v[152:155], v[204:207], v[32:35]
	v_mfma_f32_16x16x32_bf16 v[40:43], v[156:159], v[204:207], v[40:43]
	ds_read_b128 v[204:207], v246 offset:6144
	s_waitcnt lgkmcnt(3)
	v_mfma_f32_16x16x32_bf16 v[100:103], v[144:147], v[242:245], v[100:103]
	v_mfma_f32_16x16x32_bf16 v[108:111], v[148:151], v[242:245], v[108:111]
	v_mfma_f32_16x16x32_bf16 v[36:39], v[152:155], v[242:245], v[36:39]
	v_mfma_f32_16x16x32_bf16 v[44:47], v[156:159], v[242:245], v[44:47]
	ds_read_b128 v[242:245], v246 offset:7168
	s_waitcnt lgkmcnt(3)
	v_mfma_f32_16x16x32_bf16 v[80:83], v[144:147], v[196:199], v[80:83]
	v_mfma_f32_16x16x32_bf16 v[88:91], v[148:151], v[196:199], v[88:91]
	v_mfma_f32_16x16x32_bf16 v[16:19], v[152:155], v[196:199], v[16:19]
	v_mfma_f32_16x16x32_bf16 v[24:27], v[156:159], v[196:199], v[24:27]
	s_waitcnt lgkmcnt(2)
	v_mfma_f32_16x16x32_bf16 v[84:87], v[144:147], v[200:203], v[84:87]
	v_mfma_f32_16x16x32_bf16 v[92:95], v[148:151], v[200:203], v[92:95]
	v_mfma_f32_16x16x32_bf16 v[20:23], v[152:155], v[200:203], v[20:23]
	v_mfma_f32_16x16x32_bf16 v[28:31], v[156:159], v[200:203], v[28:31]
	s_waitcnt lgkmcnt(1)
	v_mfma_f32_16x16x32_bf16 v[64:67], v[144:147], v[204:207], v[64:67]
	v_mfma_f32_16x16x32_bf16 v[72:75], v[148:151], v[204:207], v[72:75]
	v_mfma_f32_16x16x32_bf16 v[0:3], v[152:155], v[204:207], v[0:3]
	v_mfma_f32_16x16x32_bf16 v[8:11], v[156:159], v[204:207], v[8:11]
	s_waitcnt lgkmcnt(0)
	v_mfma_f32_16x16x32_bf16 v[68:71], v[144:147], v[242:245], v[68:71]
	v_mfma_f32_16x16x32_bf16 v[76:79], v[148:151], v[242:245], v[76:79]
	v_mfma_f32_16x16x32_bf16 v[4:7], v[152:155], v[242:245], v[4:7]
	v_mfma_f32_16x16x32_bf16 v[12:15], v[156:159], v[242:245], v[12:15]
	global_load_dwordx4 v[144:147], v[248:249], off
	global_load_dwordx4 v[148:151], v[248:249], off offset:256
	global_load_dwordx4 v[152:155], v[250:251], off
	global_load_dwordx4 v[156:159], v[250:251], off offset:256
	s_waitcnt vmcnt(10)
	s_barrier
	s_add_i32 s9, s3, 6
	s_lshl_b32 s96, s9, 13
	s_mov_b32 m0, vcc_lo
	v_lshl_add_u64 v[160:161], v[188:189], 0, s[96:97]
	global_load_lds_dwordx4 v[160:161], off
	global_load_lds_dwordx4 v[160:161], off offset:1024
	ds_read_b128 v[196:199], v246 offset:8192
	ds_read_b128 v[200:203], v246 offset:9216
	ds_read_b128 v[204:207], v246 offset:10240
	ds_read_b128 v[242:245], v246 offset:11264
	s_add_i32 s9, s3, 6
	s_lshl_b32 s96, s9, 11
	v_lshl_add_u64 v[248:249], v[184:185], 0, s[96:97]
	v_lshl_add_u64 v[250:251], v[186:187], 0, s[96:97]
	s_waitcnt vmcnt(8) lgkmcnt(3)
	v_mfma_f32_16x16x32_bf16 v[112:115], v[128:131], v[196:199], v[112:115]
	v_mfma_f32_16x16x32_bf16 v[120:123], v[132:135], v[196:199], v[120:123]
	v_mfma_f32_16x16x32_bf16 v[48:51], v[136:139], v[196:199], v[48:51]
	v_mfma_f32_16x16x32_bf16 v[56:59], v[140:143], v[196:199], v[56:59]
	ds_read_b128 v[196:199], v246 offset:12288
	s_waitcnt lgkmcnt(3)
	v_mfma_f32_16x16x32_bf16 v[116:119], v[128:131], v[200:203], v[116:119]
	v_mfma_f32_16x16x32_bf16 v[124:127], v[132:135], v[200:203], v[124:127]
	v_mfma_f32_16x16x32_bf16 v[52:55], v[136:139], v[200:203], v[52:55]
	v_mfma_f32_16x16x32_bf16 v[60:63], v[140:143], v[200:203], v[60:63]
	ds_read_b128 v[200:203], v246 offset:13312
	s_waitcnt lgkmcnt(3)
	v_mfma_f32_16x16x32_bf16 v[96:99], v[128:131], v[204:207], v[96:99]
	v_mfma_f32_16x16x32_bf16 v[104:107], v[132:135], v[204:207], v[104:107]
	v_mfma_f32_16x16x32_bf16 v[32:35], v[136:139], v[204:207], v[32:35]
	v_mfma_f32_16x16x32_bf16 v[40:43], v[140:143], v[204:207], v[40:43]
	ds_read_b128 v[204:207], v246 offset:14336
	s_waitcnt lgkmcnt(3)
	v_mfma_f32_16x16x32_bf16 v[100:103], v[128:131], v[242:245], v[100:103]
	v_mfma_f32_16x16x32_bf16 v[108:111], v[132:135], v[242:245], v[108:111]
	v_mfma_f32_16x16x32_bf16 v[36:39], v[136:139], v[242:245], v[36:39]
	v_mfma_f32_16x16x32_bf16 v[44:47], v[140:143], v[242:245], v[44:47]
	ds_read_b128 v[242:245], v246 offset:15360
	s_waitcnt lgkmcnt(3)
	v_mfma_f32_16x16x32_bf16 v[80:83], v[128:131], v[196:199], v[80:83]
	v_mfma_f32_16x16x32_bf16 v[88:91], v[132:135], v[196:199], v[88:91]
	v_mfma_f32_16x16x32_bf16 v[16:19], v[136:139], v[196:199], v[16:19]
	v_mfma_f32_16x16x32_bf16 v[24:27], v[140:143], v[196:199], v[24:27]
	s_waitcnt lgkmcnt(2)
	v_mfma_f32_16x16x32_bf16 v[84:87], v[128:131], v[200:203], v[84:87]
	v_mfma_f32_16x16x32_bf16 v[92:95], v[132:135], v[200:203], v[92:95]
	v_mfma_f32_16x16x32_bf16 v[20:23], v[136:139], v[200:203], v[20:23]
	v_mfma_f32_16x16x32_bf16 v[28:31], v[140:143], v[200:203], v[28:31]
	s_waitcnt lgkmcnt(1)
	v_mfma_f32_16x16x32_bf16 v[64:67], v[128:131], v[204:207], v[64:67]
	v_mfma_f32_16x16x32_bf16 v[72:75], v[132:135], v[204:207], v[72:75]
	v_mfma_f32_16x16x32_bf16 v[0:3], v[136:139], v[204:207], v[0:3]
	v_mfma_f32_16x16x32_bf16 v[8:11], v[140:143], v[204:207], v[8:11]
	s_waitcnt lgkmcnt(0)
	v_mfma_f32_16x16x32_bf16 v[68:71], v[128:131], v[242:245], v[68:71]
	v_mfma_f32_16x16x32_bf16 v[76:79], v[132:135], v[242:245], v[76:79]
	v_mfma_f32_16x16x32_bf16 v[4:7], v[136:139], v[242:245], v[4:7]
	v_mfma_f32_16x16x32_bf16 v[12:15], v[140:143], v[242:245], v[12:15]
	global_load_dwordx4 v[128:131], v[248:249], off
	global_load_dwordx4 v[132:135], v[248:249], off offset:256
	global_load_dwordx4 v[136:139], v[250:251], off
	global_load_dwordx4 v[140:143], v[250:251], off offset:256
	s_waitcnt vmcnt(10)
	s_barrier
	s_add_i32 s9, s3, 7
	s_lshl_b32 s96, s9, 13
	s_add_i32 m0, vcc_lo, 8192
	v_lshl_add_u64 v[160:161], v[188:189], 0, s[96:97]
	global_load_lds_dwordx4 v[160:161], off
	global_load_lds_dwordx4 v[160:161], off offset:1024
	ds_read_b128 v[196:199], v246 offset:16384
	ds_read_b128 v[200:203], v246 offset:17408
	ds_read_b128 v[204:207], v246 offset:18432
	ds_read_b128 v[242:245], v246 offset:19456
	s_add_i32 s9, s3, 7
	s_lshl_b32 s96, s9, 11
	v_lshl_add_u64 v[248:249], v[184:185], 0, s[96:97]
	v_lshl_add_u64 v[250:251], v[186:187], 0, s[96:97]
	s_waitcnt vmcnt(8) lgkmcnt(3)
	v_mfma_f32_16x16x32_bf16 v[112:115], v[144:147], v[196:199], v[112:115]
	v_mfma_f32_16x16x32_bf16 v[120:123], v[148:151], v[196:199], v[120:123]
	v_mfma_f32_16x16x32_bf16 v[48:51], v[152:155], v[196:199], v[48:51]
	v_mfma_f32_16x16x32_bf16 v[56:59], v[156:159], v[196:199], v[56:59]
	ds_read_b128 v[196:199], v246 offset:20480
	s_waitcnt lgkmcnt(3)
	v_mfma_f32_16x16x32_bf16 v[116:119], v[144:147], v[200:203], v[116:119]
	v_mfma_f32_16x16x32_bf16 v[124:127], v[148:151], v[200:203], v[124:127]
	v_mfma_f32_16x16x32_bf16 v[52:55], v[152:155], v[200:203], v[52:55]
	v_mfma_f32_16x16x32_bf16 v[60:63], v[156:159], v[200:203], v[60:63]
	ds_read_b128 v[200:203], v246 offset:21504
	s_waitcnt lgkmcnt(3)
	v_mfma_f32_16x16x32_bf16 v[96:99], v[144:147], v[204:207], v[96:99]
	v_mfma_f32_16x16x32_bf16 v[104:107], v[148:151], v[204:207], v[104:107]
	v_mfma_f32_16x16x32_bf16 v[32:35], v[152:155], v[204:207], v[32:35]
	v_mfma_f32_16x16x32_bf16 v[40:43], v[156:159], v[204:207], v[40:43]
	ds_read_b128 v[204:207], v246 offset:22528
	s_waitcnt lgkmcnt(3)
	v_mfma_f32_16x16x32_bf16 v[100:103], v[144:147], v[242:245], v[100:103]
	v_mfma_f32_16x16x32_bf16 v[108:111], v[148:151], v[242:245], v[108:111]
	v_mfma_f32_16x16x32_bf16 v[36:39], v[152:155], v[242:245], v[36:39]
	v_mfma_f32_16x16x32_bf16 v[44:47], v[156:159], v[242:245], v[44:47]
	ds_read_b128 v[242:245], v246 offset:23552
	s_waitcnt lgkmcnt(3)
	v_mfma_f32_16x16x32_bf16 v[80:83], v[144:147], v[196:199], v[80:83]
	v_mfma_f32_16x16x32_bf16 v[88:91], v[148:151], v[196:199], v[88:91]
	v_mfma_f32_16x16x32_bf16 v[16:19], v[152:155], v[196:199], v[16:19]
	v_mfma_f32_16x16x32_bf16 v[24:27], v[156:159], v[196:199], v[24:27]
	s_waitcnt lgkmcnt(2)
	v_mfma_f32_16x16x32_bf16 v[84:87], v[144:147], v[200:203], v[84:87]
	v_mfma_f32_16x16x32_bf16 v[92:95], v[148:151], v[200:203], v[92:95]
	v_mfma_f32_16x16x32_bf16 v[20:23], v[152:155], v[200:203], v[20:23]
	v_mfma_f32_16x16x32_bf16 v[28:31], v[156:159], v[200:203], v[28:31]
	s_waitcnt lgkmcnt(1)
	v_mfma_f32_16x16x32_bf16 v[64:67], v[144:147], v[204:207], v[64:67]
	v_mfma_f32_16x16x32_bf16 v[72:75], v[148:151], v[204:207], v[72:75]
	v_mfma_f32_16x16x32_bf16 v[0:3], v[152:155], v[204:207], v[0:3]
	v_mfma_f32_16x16x32_bf16 v[8:11], v[156:159], v[204:207], v[8:11]
	s_waitcnt lgkmcnt(0)
	v_mfma_f32_16x16x32_bf16 v[68:71], v[144:147], v[242:245], v[68:71]
	v_mfma_f32_16x16x32_bf16 v[76:79], v[148:151], v[242:245], v[76:79]
	v_mfma_f32_16x16x32_bf16 v[4:7], v[152:155], v[242:245], v[4:7]
	v_mfma_f32_16x16x32_bf16 v[12:15], v[156:159], v[242:245], v[12:15]
	global_load_dwordx4 v[144:147], v[248:249], off
	global_load_dwordx4 v[148:151], v[248:249], off offset:256
	global_load_dwordx4 v[152:155], v[250:251], off
	global_load_dwordx4 v[156:159], v[250:251], off offset:256
	s_waitcnt vmcnt(10)
	s_barrier
	s_add_i32 s3, s3, 6
	s_cmp_lt_u32 s3, 30
	s_cbranch_scc1 .Lg16_out_k
	ds_read_b128 v[196:199], v246 offset:0
	ds_read_b128 v[200:203], v246 offset:1024
	ds_read_b128 v[204:207], v246 offset:2048
	ds_read_b128 v[242:245], v246 offset:3072
	s_waitcnt vmcnt(6) lgkmcnt(3)
	v_mfma_f32_16x16x32_bf16 v[112:115], v[128:131], v[196:199], v[112:115]
	v_mfma_f32_16x16x32_bf16 v[120:123], v[132:135], v[196:199], v[120:123]
	v_mfma_f32_16x16x32_bf16 v[48:51], v[136:139], v[196:199], v[48:51]
	v_mfma_f32_16x16x32_bf16 v[56:59], v[140:143], v[196:199], v[56:59]
	ds_read_b128 v[196:199], v246 offset:4096
	s_waitcnt lgkmcnt(3)
	v_mfma_f32_16x16x32_bf16 v[116:119], v[128:131], v[200:203], v[116:119]
	v_mfma_f32_16x16x32_bf16 v[124:127], v[132:135], v[200:203], v[124:127]
	v_mfma_f32_16x16x32_bf16 v[52:55], v[136:139], v[200:203], v[52:55]
	v_mfma_f32_16x16x32_bf16 v[60:63], v[140:143], v[200:203], v[60:63]
	ds_read_b128 v[200:203], v246 offset:5120
	s_waitcnt lgkmcnt(3)
	v_mfma_f32_16x16x32_bf16 v[96:99], v[128:131], v[204:207], v[96:99]
	v_mfma_f32_16x16x32_bf16 v[104:107], v[132:135], v[204:207], v[104:107]
	v_mfma_f32_16x16x32_bf16 v[32:35], v[136:139], v[204:207], v[32:35]
	v_mfma_f32_16x16x32_bf16 v[40:43], v[140:143], v[204:207], v[40:43]
	ds_read_b128 v[204:207], v246 offset:6144
	s_waitcnt lgkmcnt(3)
	v_mfma_f32_16x16x32_bf16 v[100:103], v[128:131], v[242:245], v[100:103]
	v_mfma_f32_16x16x32_bf16 v[108:111], v[132:135], v[242:245], v[108:111]
	v_mfma_f32_16x16x32_bf16 v[36:39], v[136:139], v[242:245], v[36:39]
	v_mfma_f32_16x16x32_bf16 v[44:47], v[140:143], v[242:245], v[44:47]
	ds_read_b128 v[242:245], v246 offset:7168
	s_waitcnt lgkmcnt(3)
	v_mfma_f32_16x16x32_bf16 v[80:83], v[128:131], v[196:199], v[80:83]
	v_mfma_f32_16x16x32_bf16 v[88:91], v[132:135], v[196:199], v[88:91]
	v_mfma_f32_16x16x32_bf16 v[16:19], v[136:139], v[196:199], v[16:19]
	v_mfma_f32_16x16x32_bf16 v[24:27], v[140:143], v[196:199], v[24:27]
	s_waitcnt lgkmcnt(2)
	v_mfma_f32_16x16x32_bf16 v[84:87], v[128:131], v[200:203], v[84:87]
	v_mfma_f32_16x16x32_bf16 v[92:95], v[132:135], v[200:203], v[92:95]
	v_mfma_f32_16x16x32_bf16 v[20:23], v[136:139], v[200:203], v[20:23]
	v_mfma_f32_16x16x32_bf16 v[28:31], v[140:143], v[200:203], v[28:31]
	s_waitcnt lgkmcnt(1)
	v_mfma_f32_16x16x32_bf16 v[64:67], v[128:131], v[204:207], v[64:67]
	v_mfma_f32_16x16x32_bf16 v[72:75], v[132:135], v[204:207], v[72:75]
	v_mfma_f32_16x16x32_bf16 v[0:3], v[136:139], v[204:207], v[0:3]
	v_mfma_f32_16x16x32_bf16 v[8:11], v[140:143], v[204:207], v[8:11]
	s_waitcnt lgkmcnt(0)
	v_mfma_f32_16x16x32_bf16 v[68:71], v[128:131], v[242:245], v[68:71]
	v_mfma_f32_16x16x32_bf16 v[76:79], v[132:135], v[242:245], v[76:79]
	v_mfma_f32_16x16x32_bf16 v[4:7], v[136:139], v[242:245], v[4:7]
	v_mfma_f32_16x16x32_bf16 v[12:15], v[140:143], v[242:245], v[12:15]
	s_waitcnt vmcnt(4)
	s_barrier
	ds_read_b128 v[196:199], v246 offset:8192
	ds_read_b128 v[200:203], v246 offset:9216
	ds_read_b128 v[204:207], v246 offset:10240
	ds_read_b128 v[242:245], v246 offset:11264
	s_waitcnt vmcnt(0) lgkmcnt(3)
	v_mfma_f32_16x16x32_bf16 v[112:115], v[144:147], v[196:199], v[112:115]
	v_mfma_f32_16x16x32_bf16 v[120:123], v[148:151], v[196:199], v[120:123]
	v_mfma_f32_16x16x32_bf16 v[48:51], v[152:155], v[196:199], v[48:51]
	v_mfma_f32_16x16x32_bf16 v[56:59], v[156:159], v[196:199], v[56:59]
	ds_read_b128 v[196:199], v246 offset:12288
	s_waitcnt lgkmcnt(3)
	v_mfma_f32_16x16x32_bf16 v[116:119], v[144:147], v[200:203], v[116:119]
	v_mfma_f32_16x16x32_bf16 v[124:127], v[148:151], v[200:203], v[124:127]
	v_mfma_f32_16x16x32_bf16 v[52:55], v[152:155], v[200:203], v[52:55]
	v_mfma_f32_16x16x32_bf16 v[60:63], v[156:159], v[200:203], v[60:63]
	ds_read_b128 v[200:203], v246 offset:13312
	s_waitcnt lgkmcnt(3)
	v_mfma_f32_16x16x32_bf16 v[96:99], v[144:147], v[204:207], v[96:99]
	v_mfma_f32_16x16x32_bf16 v[104:107], v[148:151], v[204:207], v[104:107]
	v_mfma_f32_16x16x32_bf16 v[32:35], v[152:155], v[204:207], v[32:35]
	v_mfma_f32_16x16x32_bf16 v[40:43], v[156:159], v[204:207], v[40:43]
	ds_read_b128 v[204:207], v246 offset:14336
	s_waitcnt lgkmcnt(3)
	v_mfma_f32_16x16x32_bf16 v[100:103], v[144:147], v[242:245], v[100:103]
	v_mfma_f32_16x16x32_bf16 v[108:111], v[148:151], v[242:245], v[108:111]
	v_mfma_f32_16x16x32_bf16 v[36:39], v[152:155], v[242:245], v[36:39]
	v_mfma_f32_16x16x32_bf16 v[44:47], v[156:159], v[242:245], v[44:47]
	ds_read_b128 v[242:245], v246 offset:15360
	v_permlane16_swap_b32_e32 v112, v116
	v_permlane16_swap_b32_e32 v113, v117
	v_permlane16_swap_b32_e32 v114, v118
	v_permlane16_swap_b32_e32 v115, v119
	v_permlane16_swap_b32_e32 v120, v124
	v_permlane16_swap_b32_e32 v121, v125
	v_permlane16_swap_b32_e32 v122, v126
	v_permlane16_swap_b32_e32 v123, v127
	v_permlane16_swap_b32_e32 v48, v52
	v_permlane16_swap_b32_e32 v49, v53
	v_permlane16_swap_b32_e32 v50, v54
	v_permlane16_swap_b32_e32 v51, v55
	v_permlane16_swap_b32_e32 v56, v60
	v_permlane16_swap_b32_e32 v57, v61
	v_permlane16_swap_b32_e32 v58, v62
	v_permlane16_swap_b32_e32 v59, v63
	v_permlane32_swap_b32_e32 v112, v116
	v_permlane32_swap_b32_e32 v113, v117
	v_permlane32_swap_b32_e32 v114, v118
	v_permlane32_swap_b32_e32 v115, v119
	v_permlane32_swap_b32_e32 v120, v124
	v_permlane32_swap_b32_e32 v121, v125
	v_permlane32_swap_b32_e32 v122, v126
	v_permlane32_swap_b32_e32 v123, v127
	v_permlane32_swap_b32_e32 v48, v52
	v_permlane32_swap_b32_e32 v49, v53
	v_permlane32_swap_b32_e32 v50, v54
	v_permlane32_swap_b32_e32 v51, v55
	v_permlane32_swap_b32_e32 v56, v60
	v_permlane32_swap_b32_e32 v57, v61
	v_permlane32_swap_b32_e32 v58, v62
	v_permlane32_swap_b32_e32 v59, v63
	s_waitcnt lgkmcnt(3)
	v_mfma_f32_16x16x32_bf16 v[80:83], v[144:147], v[196:199], v[80:83]
	v_mfma_f32_16x16x32_bf16 v[88:91], v[148:151], v[196:199], v[88:91]
	v_mfma_f32_16x16x32_bf16 v[16:19], v[152:155], v[196:199], v[16:19]
	v_mfma_f32_16x16x32_bf16 v[24:27], v[156:159], v[196:199], v[24:27]
	s_waitcnt lgkmcnt(2)
	v_mfma_f32_16x16x32_bf16 v[84:87], v[144:147], v[200:203], v[84:87]
	v_mfma_f32_16x16x32_bf16 v[92:95], v[148:151], v[200:203], v[92:95]
	v_mfma_f32_16x16x32_bf16 v[20:23], v[152:155], v[200:203], v[20:23]
	v_mfma_f32_16x16x32_bf16 v[28:31], v[156:159], v[200:203], v[28:31]
	v_permlane16_swap_b32_e32 v96, v100
	v_permlane16_swap_b32_e32 v97, v101
	v_permlane16_swap_b32_e32 v98, v102
	v_permlane16_swap_b32_e32 v99, v103
	v_permlane16_swap_b32_e32 v104, v108
	v_permlane16_swap_b32_e32 v105, v109
	v_permlane16_swap_b32_e32 v106, v110
	v_permlane16_swap_b32_e32 v107, v111
	v_permlane16_swap_b32_e32 v32, v36
	v_permlane16_swap_b32_e32 v33, v37
	v_permlane16_swap_b32_e32 v34, v38
	v_permlane16_swap_b32_e32 v35, v39
	v_permlane16_swap_b32_e32 v40, v44
	v_permlane16_swap_b32_e32 v41, v45
	v_permlane16_swap_b32_e32 v42, v46
	v_permlane16_swap_b32_e32 v43, v47
	v_permlane32_swap_b32_e32 v96, v100
	v_permlane32_swap_b32_e32 v97, v101
	v_permlane32_swap_b32_e32 v98, v102
	v_permlane32_swap_b32_e32 v99, v103
	v_permlane32_swap_b32_e32 v104, v108
	v_permlane32_swap_b32_e32 v105, v109
	v_permlane32_swap_b32_e32 v106, v110
	v_permlane32_swap_b32_e32 v107, v111
	v_permlane32_swap_b32_e32 v32, v36
	v_permlane32_swap_b32_e32 v33, v37
	v_permlane32_swap_b32_e32 v34, v38
	v_permlane32_swap_b32_e32 v35, v39
	v_permlane32_swap_b32_e32 v40, v44
	v_permlane32_swap_b32_e32 v41, v45
	v_permlane32_swap_b32_e32 v42, v46
	v_permlane32_swap_b32_e32 v43, v47
	s_waitcnt lgkmcnt(1)
	v_mfma_f32_16x16x32_bf16 v[64:67], v[144:147], v[204:207], v[64:67]
	v_mfma_f32_16x16x32_bf16 v[72:75], v[148:151], v[204:207], v[72:75]
	v_mfma_f32_16x16x32_bf16 v[0:3], v[152:155], v[204:207], v[0:3]
	v_mfma_f32_16x16x32_bf16 v[8:11], v[156:159], v[204:207], v[8:11]
	s_waitcnt lgkmcnt(0)
	v_mfma_f32_16x16x32_bf16 v[68:71], v[144:147], v[242:245], v[68:71]
	v_mfma_f32_16x16x32_bf16 v[76:79], v[148:151], v[242:245], v[76:79]
	v_mfma_f32_16x16x32_bf16 v[4:7], v[152:155], v[242:245], v[4:7]
	v_mfma_f32_16x16x32_bf16 v[12:15], v[156:159], v[242:245], v[12:15]
	v_permlane16_swap_b32_e32 v80, v84
	v_permlane16_swap_b32_e32 v81, v85
	v_permlane16_swap_b32_e32 v82, v86
	v_permlane16_swap_b32_e32 v83, v87
	v_permlane16_swap_b32_e32 v88, v92
	v_permlane16_swap_b32_e32 v89, v93
	v_permlane16_swap_b32_e32 v90, v94
	v_permlane16_swap_b32_e32 v91, v95
	v_permlane16_swap_b32_e32 v16, v20
	v_permlane16_swap_b32_e32 v17, v21
	v_permlane16_swap_b32_e32 v18, v22
	v_permlane16_swap_b32_e32 v19, v23
	v_permlane16_swap_b32_e32 v24, v28
	v_permlane16_swap_b32_e32 v25, v29
	v_permlane16_swap_b32_e32 v26, v30
	v_permlane16_swap_b32_e32 v27, v31
	v_permlane32_swap_b32_e32 v80, v84
	v_permlane32_swap_b32_e32 v81, v85
	v_permlane32_swap_b32_e32 v82, v86
	v_permlane32_swap_b32_e32 v83, v87
	v_permlane32_swap_b32_e32 v88, v92
	v_permlane32_swap_b32_e32 v89, v93
	v_permlane32_swap_b32_e32 v90, v94
	v_permlane32_swap_b32_e32 v91, v95
	v_permlane32_swap_b32_e32 v16, v20
	v_permlane32_swap_b32_e32 v17, v21
	v_permlane32_swap_b32_e32 v18, v22
	v_permlane32_swap_b32_e32 v19, v23
	v_permlane32_swap_b32_e32 v24, v28
	v_permlane32_swap_b32_e32 v25, v29
	v_permlane32_swap_b32_e32 v26, v30
	v_permlane32_swap_b32_e32 v27, v31
	s_barrier
	s_setprio 0
	s_nop 7
	v_permlane16_swap_b32_e32 v64, v68
	v_permlane16_swap_b32_e32 v65, v69
	v_permlane16_swap_b32_e32 v66, v70
	v_permlane16_swap_b32_e32 v67, v71
	v_permlane16_swap_b32_e32 v72, v76
	v_permlane16_swap_b32_e32 v73, v77
	v_permlane16_swap_b32_e32 v74, v78
	v_permlane16_swap_b32_e32 v75, v79
	v_permlane16_swap_b32_e32 v0, v4
	v_permlane16_swap_b32_e32 v1, v5
	v_permlane16_swap_b32_e32 v2, v6
	v_permlane16_swap_b32_e32 v3, v7
	v_permlane16_swap_b32_e32 v8, v12
	v_permlane16_swap_b32_e32 v9, v13
	v_permlane16_swap_b32_e32 v10, v14
	v_permlane16_swap_b32_e32 v11, v15
	v_permlane32_swap_b32_e32 v64, v68
	v_permlane32_swap_b32_e32 v65, v69
	v_permlane32_swap_b32_e32 v66, v70
	v_permlane32_swap_b32_e32 v67, v71
	v_permlane32_swap_b32_e32 v72, v76
	v_permlane32_swap_b32_e32 v73, v77
	v_permlane32_swap_b32_e32 v74, v78
	v_permlane32_swap_b32_e32 v75, v79
	v_permlane32_swap_b32_e32 v0, v4
	v_permlane32_swap_b32_e32 v1, v5
	v_permlane32_swap_b32_e32 v2, v6
	v_permlane32_swap_b32_e32 v3, v7
	v_permlane32_swap_b32_e32 v8, v12
	v_permlane32_swap_b32_e32 v9, v13
	v_permlane32_swap_b32_e32 v10, v14
	v_permlane32_swap_b32_e32 v11, v15
	s_waitcnt vmcnt(0)
	s_movk_i32 s3, 0x2400
	s_waitcnt vmcnt(6)
	v_lshlrev_b32_e32 v128, 2, v181
	s_waitcnt vmcnt(0)
	v_and_b32_e32 v133, 0xffffffc0, v181
	v_mul_lo_u32 v129, v237, s3
	v_lshlrev_b32_e32 v130, 2, v238
	v_and_b32_e32 v128, 60, v128
	v_lshl_add_u32 v176, s8, 8, v133
	v_mul_u32_u24_e32 v133, 0x110, v183
	v_or_b32_e32 v131, v129, v130
	v_lshl_or_b32 v132, v128, 2, v129
	v_lshl_or_b32 v128, s2, 7, v128
	v_lshlrev_b32_e32 v133, 2, v133
	v_lshrrev_b32_e32 v175, 4, v239
	s_movk_i32 s2, 0x110
	v_add_u32_e32 v147, v131, v133
	v_add3_u32 v148, v129, v133, v130
	v_mad_u32_u24 v146, v175, s2, v132
	v_readlane_b32 s2, v254, 39
	v_readlane_b32 s8, v253, 36
	v_add_u32_e32 v149, 0x800, v147
	v_add_u32_e32 v150, 0x800, v148
	v_add_u32_e32 v151, 0xa00, v148
	v_mov_b32_e32 v160, s2
	v_readlane_b32 s2, v254, 37
	v_readlane_b32 s9, v253, 37
	v_readlane_b32 s10, v253, 38
	v_readlane_b32 s11, v253, 39
	v_readlane_b32 s12, v253, 40
	v_readlane_b32 s13, v253, 41
	v_readlane_b32 s14, v253, 42
	v_readlane_b32 s15, v253, 43
	v_readlane_b32 s16, v253, 44
	v_readlane_b32 s17, v253, 45
	ds_write2_b32 v147, v112, v113 offset1:68
	ds_write2_b32 v148, v96, v97 offset0:32 offset1:100
	ds_write2_b32 v147, v114, v115 offset0:136 offset1:204
	ds_write2_b32 v148, v98, v99 offset0:168 offset1:236
	ds_write2_b32 v149, v116, v117 offset0:32 offset1:100
	ds_write2_b32 v150, v100, v101 offset0:64 offset1:132
	ds_write2_b32 v149, v118, v119 offset0:168 offset1:236
	ds_write2_b32 v151, v102, v103 offset0:72 offset1:140
	v_or_b32_e32 v102, v176, v175
	v_mov_b32_e32 v161, s2
	v_readlane_b32 s2, v254, 40
	v_readlane_b32 s18, v253, 46
	v_readlane_b32 s19, v253, 47
	v_readlane_b32 s20, v253, 48
	v_readlane_b32 s21, v253, 49
	v_readlane_b32 s22, v253, 50
	v_readlane_b32 s23, v253, 51
	s_mov_b64 s[8:9], s[16:17]
	v_cmp_gt_i32_e32 vcc, s39, v102
	v_add_u32_e32 v96, 0xffff8000, v102
	v_ashrrev_i32_e32 v97, 31, v102
	v_mov_b32_e32 v162, s2
	v_readlane_b32 s2, v254, 38
	s_mov_b64 s[10:11], s[18:19]
	v_cndmask_b32_e32 v97, 0, v97, vcc
	v_cndmask_b32_e32 v96, v96, v102, vcc
	v_mov_b32_e32 v163, s2
	v_mov_b32_e32 v164, s63
	v_mov_b32_e32 v165, s11
	v_mov_b32_e32 v166, s62
	v_mov_b32_e32 v167, s10
	v_min_i32_e32 v102, 0x8000, v102
	v_add_u32_e32 v152, 0x1000, v147
	v_add_u32_e32 v153, 0x1000, v148
	v_add_u32_e32 v154, 0x1200, v147
	v_add_u32_e32 v155, 0x1200, v148
	v_add_u32_e32 v156, 0x1800, v147
	v_add_u32_e32 v157, 0x1800, v148
	v_add_u32_e32 v158, 0x1a00, v147
	v_add_u32_e32 v159, 0x1c00, v148
	v_ashrrev_i32_e32 v129, 31, v128
	v_cndmask_b32_e32 v99, v160, v161, vcc
	v_cndmask_b32_e32 v98, v162, v163, vcc
	v_lshlrev_b64 v[96:97], 12, v[96:97]
	v_cndmask_b32_e32 v101, v164, v165, vcc
	v_cndmask_b32_e32 v100, v166, v167, vcc
	v_ashrrev_i32_e32 v102, 12, v102
	ds_write2_b32 v152, v120, v121 offset0:64 offset1:132
	ds_write2_b32 v153, v104, v105 offset0:96 offset1:164
	ds_write2_b32 v154, v122, v123 offset0:72 offset1:140
	ds_write2_b32 v155, v106, v107 offset0:104 offset1:172
	ds_write2_b32 v156, v124, v125 offset0:96 offset1:164
	ds_write2_b32 v157, v108, v109 offset0:128 offset1:196
	ds_write2_b32 v158, v126, v127 offset0:104 offset1:172
	ds_write2_b32 v159, v110, v111 offset0:8 offset1:76
	v_lshl_add_u64 v[98:99], v[98:99], 0, v[96:97]
	v_lshl_add_u64 v[100:101], v[100:101], 0, v[96:97]
	v_lshlrev_b64 v[96:97], 2, v[128:129]
	v_mul_hi_i32_i24_e32 v103, 0x6000, v102
	v_mul_i32_i24_e32 v102, 0x6000, v102
	s_waitcnt lgkmcnt(0)
	v_lshl_add_u64 v[98:99], v[98:99], 0, v[96:97]
	v_lshl_add_u64 v[102:103], s[0:1], 0, v[102:103]
	v_lshl_add_u64 v[102:103], v[102:103], 0, v[96:97]
	ds_read_b128 v[104:107], v146
	global_load_dwordx4 v[108:111], v[98:99], off
	global_load_dwordx4 v[112:115], v[102:103], off
	v_or_b32_e32 v168, 4, v175
	v_lshl_add_u64 v[100:101], v[100:101], 0, v[96:97]
	v_or_b32_e32 v169, 8, v175
	v_or_b32_e32 v170, 12, v175
	v_or_b32_e32 v171, 16, v175
	v_or_b32_e32 v172, 20, v175
	v_or_b32_e32 v173, 24, v175
	v_or_b32_e32 v174, 28, v175
	v_or_b32_e32 v181, v176, v174
	v_readlane_b32 s2, v254, 11
	s_add_i32 s4, s4, s2
	s_cmp_lt_i32 s4, s26
	s_mov_b64 s[12:13], s[20:21]
	s_mov_b64 s[14:15], s[22:23]
	s_waitcnt vmcnt(0) lgkmcnt(0)
	v_pk_fma_f32 v[104:105], v[104:105], v[112:113], v[108:109]
	v_pk_fma_f32 v[106:107], v[106:107], v[114:115], v[110:111]
	v_or_b32_e32 v110, v176, v168
	global_store_dwordx4 v[100:101], v[104:107], off
	v_cmp_gt_i32_e32 vcc, s39, v110
	s_nop 0
	v_ashrrev_i32_e32 v104, 31, v110
	v_add_u32_e32 v106, 0xffff8000, v110
	v_cndmask_b32_e32 v105, 0, v104, vcc
	v_cndmask_b32_e32 v104, v106, v110, vcc
	v_cndmask_b32_e32 v107, v160, v161, vcc
	v_cndmask_b32_e32 v106, v162, v163, vcc
	v_lshlrev_b64 v[104:105], 12, v[104:105]
	v_cndmask_b32_e32 v109, v164, v165, vcc
	v_cndmask_b32_e32 v108, v166, v167, vcc
	v_lshl_add_u64 v[106:107], v[106:107], 0, v[104:105]
	v_lshl_add_u64 v[104:105], v[108:109], 0, v[104:105]
	v_min_i32_e32 v108, 0x8000, v110
	v_ashrrev_i32_e32 v108, 12, v108
	v_mul_hi_i32_i24_e32 v109, 0x6000, v108
	v_mul_i32_i24_e32 v108, 0x6000, v108
	v_lshl_add_u64 v[106:107], v[106:107], 0, v[96:97]
	v_lshl_add_u64 v[108:109], s[0:1], 0, v[108:109]
	v_lshl_add_u64 v[108:109], v[108:109], 0, v[96:97]
	ds_read_b128 v[110:113], v146 offset:1088
	global_load_dwordx4 v[114:117], v[106:107], off
	global_load_dwordx4 v[118:121], v[108:109], off
	v_lshl_add_u64 v[104:105], v[104:105], 0, v[96:97]
	s_waitcnt vmcnt(0) lgkmcnt(0)
	v_pk_fma_f32 v[110:111], v[110:111], v[118:119], v[114:115]
	v_pk_fma_f32 v[112:113], v[112:113], v[120:121], v[116:117]
	v_or_b32_e32 v118, v176, v169
	global_store_dwordx4 v[104:105], v[110:113], off
	v_cmp_gt_i32_e32 vcc, s39, v118
	s_nop 0
	v_ashrrev_i32_e32 v110, 31, v118
	v_add_u32_e32 v112, 0xffff8000, v118
	v_cndmask_b32_e32 v111, 0, v110, vcc
	v_cndmask_b32_e32 v110, v112, v118, vcc
	v_cndmask_b32_e32 v113, v160, v161, vcc
	v_cndmask_b32_e32 v112, v162, v163, vcc
	v_lshlrev_b64 v[110:111], 12, v[110:111]
	v_lshl_add_u64 v[112:113], v[112:113], 0, v[110:111]
	v_cndmask_b32_e32 v115, v164, v165, vcc
	v_cndmask_b32_e32 v114, v166, v167, vcc
	v_lshl_add_u64 v[116:117], v[114:115], 0, v[110:111]
	v_lshl_add_u64 v[110:111], v[112:113], 0, v[96:97]
	v_min_i32_e32 v112, 0x8000, v118
	v_ashrrev_i32_e32 v112, 12, v112
	v_mul_hi_i32_i24_e32 v113, 0x6000, v112
	v_mul_i32_i24_e32 v112, 0x6000, v112
	v_lshl_add_u64 v[112:113], s[0:1], 0, v[112:113]
	v_lshl_add_u64 v[114:115], v[112:113], 0, v[96:97]
	v_lshl_add_u64 v[112:113], v[116:117], 0, v[96:97]
	ds_read_b128 v[116:119], v146 offset:2176
	global_load_dwordx4 v[120:123], v[110:111], off
	global_load_dwordx4 v[124:127], v[114:115], off
	s_waitcnt vmcnt(0) lgkmcnt(0)
	v_pk_fma_f32 v[116:117], v[116:117], v[124:125], v[120:121]
	v_pk_fma_f32 v[118:119], v[118:119], v[126:127], v[122:123]
	v_or_b32_e32 v124, v176, v170
	global_store_dwordx4 v[112:113], v[116:119], off
	v_cmp_gt_i32_e32 vcc, s39, v124
	s_nop 0
	v_ashrrev_i32_e32 v116, 31, v124
	v_add_u32_e32 v118, 0xffff8000, v124
	v_cndmask_b32_e32 v117, 0, v116, vcc
	v_cndmask_b32_e32 v116, v118, v124, vcc
	v_cndmask_b32_e32 v119, v160, v161, vcc
	v_cndmask_b32_e32 v118, v162, v163, vcc
	v_lshlrev_b64 v[116:117], 12, v[116:117]
	v_lshl_add_u64 v[118:119], v[118:119], 0, v[116:117]
	v_cndmask_b32_e32 v121, v164, v165, vcc
	v_cndmask_b32_e32 v120, v166, v167, vcc
	v_lshl_add_u64 v[122:123], v[120:121], 0, v[116:117]
	v_lshl_add_u64 v[116:117], v[118:119], 0, v[96:97]
	v_min_i32_e32 v118, 0x8000, v124
	v_ashrrev_i32_e32 v118, 12, v118
	v_mul_hi_i32_i24_e32 v119, 0x6000, v118
	v_mul_i32_i24_e32 v118, 0x6000, v118
	v_lshl_add_u64 v[118:119], s[0:1], 0, v[118:119]
	v_lshl_add_u64 v[120:121], v[118:119], 0, v[96:97]
	v_lshl_add_u64 v[118:119], v[122:123], 0, v[96:97]
	ds_read_b128 v[122:125], v146 offset:3264
	global_load_dwordx4 v[126:129], v[116:117], off
	global_load_dwordx4 v[130:133], v[120:121], off
	s_waitcnt vmcnt(0) lgkmcnt(0)
	v_pk_fma_f32 v[122:123], v[122:123], v[130:131], v[126:127]
	v_pk_fma_f32 v[124:125], v[124:125], v[132:133], v[128:129]
	v_or_b32_e32 v130, v176, v171
	global_store_dwordx4 v[118:119], v[122:125], off
	v_cmp_gt_i32_e32 vcc, s39, v130
	s_nop 0
	v_ashrrev_i32_e32 v122, 31, v130
	v_add_u32_e32 v124, 0xffff8000, v130
	v_cndmask_b32_e32 v123, 0, v122, vcc
	v_cndmask_b32_e32 v122, v124, v130, vcc
	v_cndmask_b32_e32 v125, v160, v161, vcc
	v_cndmask_b32_e32 v124, v162, v163, vcc
	v_lshlrev_b64 v[122:123], 12, v[122:123]
	v_lshl_add_u64 v[124:125], v[124:125], 0, v[122:123]
	v_cndmask_b32_e32 v127, v164, v165, vcc
	v_cndmask_b32_e32 v126, v166, v167, vcc
	v_lshl_add_u64 v[128:129], v[126:127], 0, v[122:123]
	v_lshl_add_u64 v[122:123], v[124:125], 0, v[96:97]
	v_min_i32_e32 v124, 0x8000, v130
	v_ashrrev_i32_e32 v124, 12, v124
	v_mul_hi_i32_i24_e32 v125, 0x6000, v124
	v_mul_i32_i24_e32 v124, 0x6000, v124
	v_lshl_add_u64 v[124:125], s[0:1], 0, v[124:125]
	v_lshl_add_u64 v[126:127], v[124:125], 0, v[96:97]
	v_lshl_add_u64 v[124:125], v[128:129], 0, v[96:97]
	ds_read_b128 v[128:131], v146 offset:4352
	global_load_dwordx4 v[132:135], v[122:123], off
	global_load_dwordx4 v[136:139], v[126:127], off
	s_waitcnt vmcnt(0) lgkmcnt(0)
	v_pk_fma_f32 v[128:129], v[128:129], v[136:137], v[132:133]
	v_pk_fma_f32 v[130:131], v[130:131], v[138:139], v[134:135]
	v_or_b32_e32 v136, v176, v172
	global_store_dwordx4 v[124:125], v[128:131], off
	v_cmp_gt_i32_e32 vcc, s39, v136
	s_nop 0
	v_ashrrev_i32_e32 v128, 31, v136
	v_add_u32_e32 v130, 0xffff8000, v136
	v_cndmask_b32_e32 v129, 0, v128, vcc
	v_cndmask_b32_e32 v128, v130, v136, vcc
	v_cndmask_b32_e32 v131, v160, v161, vcc
	v_cndmask_b32_e32 v130, v162, v163, vcc
	v_lshlrev_b64 v[128:129], 12, v[128:129]
	v_lshl_add_u64 v[130:131], v[130:131], 0, v[128:129]
	v_cndmask_b32_e32 v133, v164, v165, vcc
	v_cndmask_b32_e32 v132, v166, v167, vcc
	v_lshl_add_u64 v[134:135], v[132:133], 0, v[128:129]
	v_lshl_add_u64 v[128:129], v[130:131], 0, v[96:97]
	v_min_i32_e32 v130, 0x8000, v136
	v_ashrrev_i32_e32 v130, 12, v130
	v_mul_hi_i32_i24_e32 v131, 0x6000, v130
	v_mul_i32_i24_e32 v130, 0x6000, v130
	v_lshl_add_u64 v[130:131], s[0:1], 0, v[130:131]
	v_lshl_add_u64 v[132:133], v[130:131], 0, v[96:97]
	v_lshl_add_u64 v[130:131], v[134:135], 0, v[96:97]
	ds_read_b128 v[134:137], v146 offset:5440
	global_load_dwordx4 v[138:141], v[128:129], off
	global_load_dwordx4 v[142:145], v[132:133], off
	s_waitcnt vmcnt(0) lgkmcnt(0)
	v_pk_fma_f32 v[134:135], v[134:135], v[142:143], v[138:139]
	v_pk_fma_f32 v[136:137], v[136:137], v[144:145], v[140:141]
	v_or_b32_e32 v142, v176, v173
	global_store_dwordx4 v[130:131], v[134:137], off
	v_cmp_gt_i32_e32 vcc, s39, v142
	s_nop 0
	v_ashrrev_i32_e32 v134, 31, v142
	v_add_u32_e32 v136, 0xffff8000, v142
	v_cndmask_b32_e32 v135, 0, v134, vcc
	v_cndmask_b32_e32 v134, v136, v142, vcc
	v_cndmask_b32_e32 v137, v160, v161, vcc
	v_cndmask_b32_e32 v136, v162, v163, vcc
	v_lshlrev_b64 v[134:135], 12, v[134:135]
	v_lshl_add_u64 v[136:137], v[136:137], 0, v[134:135]
	v_cndmask_b32_e32 v139, v164, v165, vcc
	v_cndmask_b32_e32 v138, v166, v167, vcc
	v_lshl_add_u64 v[140:141], v[138:139], 0, v[134:135]
	v_lshl_add_u64 v[134:135], v[136:137], 0, v[96:97]
	v_min_i32_e32 v136, 0x8000, v142
	v_ashrrev_i32_e32 v136, 12, v136
	v_mul_hi_i32_i24_e32 v137, 0x6000, v136
	v_mul_i32_i24_e32 v136, 0x6000, v136
	v_lshl_add_u64 v[136:137], s[0:1], 0, v[136:137]
	v_lshl_add_u64 v[138:139], v[136:137], 0, v[96:97]
	v_lshl_add_u64 v[136:137], v[140:141], 0, v[96:97]
	ds_read_b128 v[140:143], v146 offset:6528
	global_load_dwordx4 v[184:187], v[134:135], off
	global_load_dwordx4 v[196:199], v[138:139], off
	v_cmp_gt_i32_e32 vcc, s39, v181
	s_waitcnt vmcnt(0) lgkmcnt(0)
	v_pk_fma_f32 v[140:141], v[140:141], v[196:197], v[184:185]
	v_pk_fma_f32 v[142:143], v[142:143], v[198:199], v[186:187]
	global_store_dwordx4 v[136:137], v[140:143], off
	v_cndmask_b32_e32 v145, v164, v165, vcc
	v_cndmask_b32_e32 v144, v166, v167, vcc
	v_ashrrev_i32_e32 v140, 31, v181
	v_add_u32_e32 v142, 0xffff8000, v181
	v_cndmask_b32_e32 v141, 0, v140, vcc
	v_cndmask_b32_e32 v140, v142, v181, vcc
	v_cndmask_b32_e32 v143, v160, v161, vcc
	v_cndmask_b32_e32 v142, v162, v163, vcc
	v_lshlrev_b64 v[140:141], 12, v[140:141]
	v_lshl_add_u64 v[142:143], v[142:143], 0, v[140:141]
	v_lshl_add_u64 v[184:185], v[144:145], 0, v[140:141]
	v_lshl_add_u64 v[140:141], v[142:143], 0, v[96:97]
	v_min_i32_e32 v142, 0x8000, v181
	v_ashrrev_i32_e32 v142, 12, v142
	v_mul_hi_i32_i24_e32 v143, 0x6000, v142
	v_mul_i32_i24_e32 v142, 0x6000, v142
	v_lshl_add_u64 v[142:143], s[0:1], 0, v[142:143]
	v_lshl_add_u64 v[144:145], v[142:143], 0, v[96:97]
	v_lshl_add_u64 v[142:143], v[184:185], 0, v[96:97]
	ds_read_b128 v[184:187], v146 offset:7616
	global_load_dwordx4 v[196:199], v[140:141], off
	global_load_dwordx4 v[200:203], v[144:145], off
	s_waitcnt vmcnt(0) lgkmcnt(0)
	v_pk_fma_f32 v[184:185], v[184:185], v[200:201], v[196:197]
	v_pk_fma_f32 v[186:187], v[186:187], v[202:203], v[198:199]
	global_store_dwordx4 v[142:143], v[184:187], off
	s_waitcnt lgkmcnt(0)
	ds_write2_b32 v147, v80, v81 offset1:68
	ds_write2_b32 v148, v64, v65 offset0:32 offset1:100
	ds_write2_b32 v147, v82, v83 offset0:136 offset1:204
	ds_write2_b32 v148, v66, v67 offset0:168 offset1:236
	ds_write2_b32 v149, v84, v85 offset0:32 offset1:100
	ds_write2_b32 v150, v68, v69 offset0:64 offset1:132
	ds_write2_b32 v149, v86, v87 offset0:168 offset1:236
	ds_write2_b32 v151, v70, v71 offset0:72 offset1:140
	ds_write2_b32 v152, v88, v89 offset0:64 offset1:132
	ds_write2_b32 v153, v72, v73 offset0:96 offset1:164
	ds_write2_b32 v154, v90, v91 offset0:72 offset1:140
	ds_write2_b32 v155, v74, v75 offset0:104 offset1:172
	ds_write2_b32 v156, v92, v93 offset0:96 offset1:164
	ds_write2_b32 v157, v76, v77 offset0:128 offset1:196
	ds_write2_b32 v158, v94, v95 offset0:104 offset1:172
	ds_write2_b32 v159, v78, v79 offset0:8 offset1:76
	s_waitcnt lgkmcnt(0)
	ds_read_b128 v[64:67], v146
	global_load_dwordx4 v[68:71], v[98:99], off offset:256
	global_load_dwordx4 v[72:75], v[102:103], off offset:256
	s_waitcnt vmcnt(0) lgkmcnt(0)
	v_pk_fma_f32 v[64:65], v[64:65], v[72:73], v[68:69]
	v_pk_fma_f32 v[66:67], v[66:67], v[74:75], v[70:71]
	global_store_dwordx4 v[100:101], v[64:67], off offset:256
	ds_read_b128 v[64:67], v146 offset:1088
	global_load_dwordx4 v[68:71], v[106:107], off offset:256
	global_load_dwordx4 v[72:75], v[108:109], off offset:256
	s_waitcnt vmcnt(0) lgkmcnt(0)
	v_pk_fma_f32 v[64:65], v[64:65], v[72:73], v[68:69]
	v_pk_fma_f32 v[66:67], v[66:67], v[74:75], v[70:71]
	global_store_dwordx4 v[104:105], v[64:67], off offset:256
	ds_read_b128 v[64:67], v146 offset:2176
	global_load_dwordx4 v[68:71], v[110:111], off offset:256
	global_load_dwordx4 v[72:75], v[114:115], off offset:256
	s_waitcnt vmcnt(0) lgkmcnt(0)
	v_pk_fma_f32 v[64:65], v[64:65], v[72:73], v[68:69]
	v_pk_fma_f32 v[66:67], v[66:67], v[74:75], v[70:71]
	global_store_dwordx4 v[112:113], v[64:67], off offset:256
	ds_read_b128 v[64:67], v146 offset:3264
	global_load_dwordx4 v[68:71], v[116:117], off offset:256
	global_load_dwordx4 v[72:75], v[120:121], off offset:256
	s_waitcnt vmcnt(0) lgkmcnt(0)
	v_pk_fma_f32 v[64:65], v[64:65], v[72:73], v[68:69]
	v_pk_fma_f32 v[66:67], v[66:67], v[74:75], v[70:71]
	global_store_dwordx4 v[118:119], v[64:67], off offset:256
	ds_read_b128 v[64:67], v146 offset:4352
	global_load_dwordx4 v[68:71], v[122:123], off offset:256
	global_load_dwordx4 v[72:75], v[126:127], off offset:256
	s_waitcnt vmcnt(0) lgkmcnt(0)
	v_pk_fma_f32 v[64:65], v[64:65], v[72:73], v[68:69]
	v_pk_fma_f32 v[66:67], v[66:67], v[74:75], v[70:71]
	global_store_dwordx4 v[124:125], v[64:67], off offset:256
	ds_read_b128 v[64:67], v146 offset:5440
	global_load_dwordx4 v[68:71], v[128:129], off offset:256
	global_load_dwordx4 v[72:75], v[132:133], off offset:256
	s_waitcnt vmcnt(0) lgkmcnt(0)
	v_pk_fma_f32 v[64:65], v[64:65], v[72:73], v[68:69]
	v_pk_fma_f32 v[66:67], v[66:67], v[74:75], v[70:71]
	global_store_dwordx4 v[130:131], v[64:67], off offset:256
	ds_read_b128 v[64:67], v146 offset:6528
	global_load_dwordx4 v[68:71], v[134:135], off offset:256
	global_load_dwordx4 v[72:75], v[138:139], off offset:256
	s_waitcnt vmcnt(0) lgkmcnt(0)
	v_pk_fma_f32 v[64:65], v[64:65], v[72:73], v[68:69]
	v_pk_fma_f32 v[66:67], v[66:67], v[74:75], v[70:71]
	global_store_dwordx4 v[136:137], v[64:67], off offset:256
	ds_read_b128 v[64:67], v146 offset:7616
	global_load_dwordx4 v[68:71], v[140:141], off offset:256
	global_load_dwordx4 v[72:75], v[144:145], off offset:256
	s_waitcnt vmcnt(0) lgkmcnt(0)
	v_pk_fma_f32 v[64:65], v[64:65], v[72:73], v[68:69]
	v_pk_fma_f32 v[66:67], v[66:67], v[74:75], v[70:71]
	global_store_dwordx4 v[142:143], v[64:67], off offset:256
	v_or_b32_e32 v74, 32, v176
	s_waitcnt lgkmcnt(0)
	ds_write2_b32 v147, v48, v49 offset1:68
	ds_write2_b32 v148, v32, v33 offset0:32 offset1:100
	ds_write2_b32 v147, v50, v51 offset0:136 offset1:204
	ds_write2_b32 v148, v34, v35 offset0:168 offset1:236
	ds_write2_b32 v149, v52, v53 offset0:32 offset1:100
	ds_write2_b32 v150, v36, v37 offset0:64 offset1:132
	ds_write2_b32 v149, v54, v55 offset0:168 offset1:236
	ds_write2_b32 v151, v38, v39 offset0:72 offset1:140
	ds_write2_b32 v152, v56, v57 offset0:64 offset1:132
	ds_write2_b32 v153, v40, v41 offset0:96 offset1:164
	ds_write2_b32 v154, v58, v59 offset0:72 offset1:140
	ds_write2_b32 v155, v42, v43 offset0:104 offset1:172
	ds_write2_b32 v156, v60, v61 offset0:96 offset1:164
	ds_write2_b32 v157, v44, v45 offset0:128 offset1:196
	ds_write2_b32 v158, v62, v63 offset0:104 offset1:172
	ds_write2_b32 v159, v46, v47 offset0:8 offset1:76
	v_or_b32_e32 v40, v74, v175
	v_cmp_gt_i32_e32 vcc, s39, v40
	v_ashrrev_i32_e32 v32, 31, v40
	v_add_u32_e32 v34, 0xffff8000, v40
	v_cndmask_b32_e32 v33, 0, v32, vcc
	v_cndmask_b32_e32 v32, v34, v40, vcc
	v_cndmask_b32_e32 v35, v160, v161, vcc
	v_cndmask_b32_e32 v34, v162, v163, vcc
	v_lshlrev_b64 v[32:33], 12, v[32:33]
	v_lshl_add_u64 v[34:35], v[34:35], 0, v[32:33]
	v_cndmask_b32_e32 v37, v164, v165, vcc
	v_cndmask_b32_e32 v36, v166, v167, vcc
	v_lshl_add_u64 v[38:39], v[36:37], 0, v[32:33]
	v_lshl_add_u64 v[32:33], v[34:35], 0, v[96:97]
	v_min_i32_e32 v34, 0x8000, v40
	v_ashrrev_i32_e32 v34, 12, v34
	v_mul_hi_i32_i24_e32 v35, 0x6000, v34
	v_mul_i32_i24_e32 v34, 0x6000, v34
	s_waitcnt lgkmcnt(0)
	v_lshl_add_u64 v[34:35], s[0:1], 0, v[34:35]
	v_lshl_add_u64 v[36:37], v[34:35], 0, v[96:97]
	v_lshl_add_u64 v[34:35], v[38:39], 0, v[96:97]
	ds_read_b128 v[38:41], v146
	global_load_dwordx4 v[42:45], v[32:33], off
	global_load_dwordx4 v[46:49], v[36:37], off
	v_or_b32_e32 v75, v74, v173
	s_waitcnt vmcnt(0) lgkmcnt(0)
	v_pk_fma_f32 v[38:39], v[38:39], v[46:47], v[42:43]
	v_pk_fma_f32 v[40:41], v[40:41], v[48:49], v[44:45]
	v_or_b32_e32 v46, v74, v168
	global_store_dwordx4 v[34:35], v[38:41], off
	v_cmp_gt_i32_e32 vcc, s39, v46
	s_nop 0
	v_ashrrev_i32_e32 v38, 31, v46
	v_add_u32_e32 v40, 0xffff8000, v46
	v_cndmask_b32_e32 v39, 0, v38, vcc
	v_cndmask_b32_e32 v38, v40, v46, vcc
	v_cndmask_b32_e32 v41, v160, v161, vcc
	v_cndmask_b32_e32 v40, v162, v163, vcc
	v_lshlrev_b64 v[38:39], 12, v[38:39]
	v_lshl_add_u64 v[40:41], v[40:41], 0, v[38:39]
	v_cndmask_b32_e32 v43, v164, v165, vcc
	v_cndmask_b32_e32 v42, v166, v167, vcc
	v_lshl_add_u64 v[44:45], v[42:43], 0, v[38:39]
	v_lshl_add_u64 v[38:39], v[40:41], 0, v[96:97]
	v_min_i32_e32 v40, 0x8000, v46
	v_ashrrev_i32_e32 v40, 12, v40
	v_mul_hi_i32_i24_e32 v41, 0x6000, v40
	v_mul_i32_i24_e32 v40, 0x6000, v40
	v_lshl_add_u64 v[40:41], s[0:1], 0, v[40:41]
	v_lshl_add_u64 v[42:43], v[40:41], 0, v[96:97]
	v_lshl_add_u64 v[40:41], v[44:45], 0, v[96:97]
	ds_read_b128 v[44:47], v146 offset:1088
	global_load_dwordx4 v[48:51], v[38:39], off
	global_load_dwordx4 v[52:55], v[42:43], off
	s_waitcnt vmcnt(0) lgkmcnt(0)
	v_pk_fma_f32 v[44:45], v[44:45], v[52:53], v[48:49]
	v_pk_fma_f32 v[46:47], v[46:47], v[54:55], v[50:51]
	v_or_b32_e32 v52, v74, v169
	global_store_dwordx4 v[40:41], v[44:47], off
	v_cmp_gt_i32_e32 vcc, s39, v52
	s_nop 0
	v_ashrrev_i32_e32 v44, 31, v52
	v_add_u32_e32 v46, 0xffff8000, v52
	v_cndmask_b32_e32 v45, 0, v44, vcc
	v_cndmask_b32_e32 v44, v46, v52, vcc
	v_cndmask_b32_e32 v47, v160, v161, vcc
	v_cndmask_b32_e32 v46, v162, v163, vcc
	v_lshlrev_b64 v[44:45], 12, v[44:45]
	v_lshl_add_u64 v[46:47], v[46:47], 0, v[44:45]
	v_cndmask_b32_e32 v49, v164, v165, vcc
	v_cndmask_b32_e32 v48, v166, v167, vcc
	v_lshl_add_u64 v[50:51], v[48:49], 0, v[44:45]
	v_lshl_add_u64 v[44:45], v[46:47], 0, v[96:97]
	v_min_i32_e32 v46, 0x8000, v52
	v_ashrrev_i32_e32 v46, 12, v46
	v_mul_hi_i32_i24_e32 v47, 0x6000, v46
	v_mul_i32_i24_e32 v46, 0x6000, v46
	v_lshl_add_u64 v[46:47], s[0:1], 0, v[46:47]
	v_lshl_add_u64 v[48:49], v[46:47], 0, v[96:97]
	v_lshl_add_u64 v[46:47], v[50:51], 0, v[96:97]
	ds_read_b128 v[50:53], v146 offset:2176
	global_load_dwordx4 v[54:57], v[44:45], off
	global_load_dwordx4 v[58:61], v[48:49], off
	s_waitcnt vmcnt(0) lgkmcnt(0)
	v_pk_fma_f32 v[50:51], v[50:51], v[58:59], v[54:55]
	v_pk_fma_f32 v[52:53], v[52:53], v[60:61], v[56:57]
	v_or_b32_e32 v58, v74, v170
	global_store_dwordx4 v[46:47], v[50:53], off
	v_cmp_gt_i32_e32 vcc, s39, v58
	s_nop 0
	v_ashrrev_i32_e32 v50, 31, v58
	v_add_u32_e32 v52, 0xffff8000, v58
	v_cndmask_b32_e32 v51, 0, v50, vcc
	v_cndmask_b32_e32 v50, v52, v58, vcc
	v_cndmask_b32_e32 v53, v160, v161, vcc
	v_cndmask_b32_e32 v52, v162, v163, vcc
	v_lshlrev_b64 v[50:51], 12, v[50:51]
	v_lshl_add_u64 v[52:53], v[52:53], 0, v[50:51]
	v_cndmask_b32_e32 v55, v164, v165, vcc
	v_cndmask_b32_e32 v54, v166, v167, vcc
	v_lshl_add_u64 v[56:57], v[54:55], 0, v[50:51]
	v_lshl_add_u64 v[50:51], v[52:53], 0, v[96:97]
	v_min_i32_e32 v52, 0x8000, v58
	v_ashrrev_i32_e32 v52, 12, v52
	v_mul_hi_i32_i24_e32 v53, 0x6000, v52
	v_mul_i32_i24_e32 v52, 0x6000, v52
	v_lshl_add_u64 v[52:53], s[0:1], 0, v[52:53]
	v_lshl_add_u64 v[54:55], v[52:53], 0, v[96:97]
	v_lshl_add_u64 v[52:53], v[56:57], 0, v[96:97]
	ds_read_b128 v[56:59], v146 offset:3264
	global_load_dwordx4 v[60:63], v[50:51], off
	global_load_dwordx4 v[64:67], v[54:55], off
	s_waitcnt vmcnt(0) lgkmcnt(0)
	v_pk_fma_f32 v[56:57], v[56:57], v[64:65], v[60:61]
	v_pk_fma_f32 v[58:59], v[58:59], v[66:67], v[62:63]
	v_or_b32_e32 v64, v74, v171
	global_store_dwordx4 v[52:53], v[56:59], off
	v_cmp_gt_i32_e32 vcc, s39, v64
	s_nop 0
	v_ashrrev_i32_e32 v56, 31, v64
	v_add_u32_e32 v58, 0xffff8000, v64
	v_cndmask_b32_e32 v57, 0, v56, vcc
	v_cndmask_b32_e32 v56, v58, v64, vcc
	v_cndmask_b32_e32 v59, v160, v161, vcc
	v_cndmask_b32_e32 v58, v162, v163, vcc
	v_lshlrev_b64 v[56:57], 12, v[56:57]
	v_lshl_add_u64 v[58:59], v[58:59], 0, v[56:57]
	v_cndmask_b32_e32 v61, v164, v165, vcc
	v_cndmask_b32_e32 v60, v166, v167, vcc
	v_lshl_add_u64 v[62:63], v[60:61], 0, v[56:57]
	v_lshl_add_u64 v[56:57], v[58:59], 0, v[96:97]
	v_min_i32_e32 v58, 0x8000, v64
	v_ashrrev_i32_e32 v58, 12, v58
	v_mul_hi_i32_i24_e32 v59, 0x6000, v58
	v_mul_i32_i24_e32 v58, 0x6000, v58
	v_lshl_add_u64 v[58:59], s[0:1], 0, v[58:59]
	v_lshl_add_u64 v[60:61], v[58:59], 0, v[96:97]
	v_lshl_add_u64 v[58:59], v[62:63], 0, v[96:97]
	ds_read_b128 v[62:65], v146 offset:4352
	global_load_dwordx4 v[66:69], v[56:57], off
	global_load_dwordx4 v[70:73], v[60:61], off
	s_waitcnt vmcnt(0) lgkmcnt(0)
	v_pk_fma_f32 v[62:63], v[62:63], v[70:71], v[66:67]
	v_pk_fma_f32 v[64:65], v[64:65], v[72:73], v[68:69]
	v_or_b32_e32 v70, v74, v172
	global_store_dwordx4 v[58:59], v[62:65], off
	v_cmp_gt_i32_e32 vcc, s39, v70
	s_nop 0
	v_ashrrev_i32_e32 v62, 31, v70
	v_add_u32_e32 v64, 0xffff8000, v70
	v_cndmask_b32_e32 v63, 0, v62, vcc
	v_cndmask_b32_e32 v62, v64, v70, vcc
	v_cndmask_b32_e32 v65, v160, v161, vcc
	v_cndmask_b32_e32 v64, v162, v163, vcc
	v_lshlrev_b64 v[62:63], 12, v[62:63]
	v_lshl_add_u64 v[64:65], v[64:65], 0, v[62:63]
	v_cndmask_b32_e32 v67, v164, v165, vcc
	v_cndmask_b32_e32 v66, v166, v167, vcc
	v_lshl_add_u64 v[68:69], v[66:67], 0, v[62:63]
	v_lshl_add_u64 v[62:63], v[64:65], 0, v[96:97]
	v_min_i32_e32 v64, 0x8000, v70
	v_ashrrev_i32_e32 v64, 12, v64
	v_mul_hi_i32_i24_e32 v65, 0x6000, v64
	v_mul_i32_i24_e32 v64, 0x6000, v64
	v_lshl_add_u64 v[64:65], s[0:1], 0, v[64:65]
	v_lshl_add_u64 v[66:67], v[64:65], 0, v[96:97]
	v_lshl_add_u64 v[64:65], v[68:69], 0, v[96:97]
	ds_read_b128 v[68:71], v146 offset:5440
	global_load_dwordx4 v[76:79], v[62:63], off
	global_load_dwordx4 v[80:83], v[66:67], off
	v_cmp_gt_i32_e32 vcc, s39, v75
	s_waitcnt vmcnt(0) lgkmcnt(0)
	v_pk_fma_f32 v[68:69], v[68:69], v[80:81], v[76:77]
	v_pk_fma_f32 v[70:71], v[70:71], v[82:83], v[78:79]
	global_store_dwordx4 v[64:65], v[68:71], off
	v_cndmask_b32_e32 v73, v164, v165, vcc
	v_cndmask_b32_e32 v72, v166, v167, vcc
	v_ashrrev_i32_e32 v68, 31, v75
	v_add_u32_e32 v70, 0xffff8000, v75
	v_cndmask_b32_e32 v69, 0, v68, vcc
	v_cndmask_b32_e32 v68, v70, v75, vcc
	v_cndmask_b32_e32 v71, v160, v161, vcc
	v_cndmask_b32_e32 v70, v162, v163, vcc
	v_lshlrev_b64 v[68:69], 12, v[68:69]
	v_lshl_add_u64 v[70:71], v[70:71], 0, v[68:69]
	v_lshl_add_u64 v[76:77], v[72:73], 0, v[68:69]
	v_lshl_add_u64 v[68:69], v[70:71], 0, v[96:97]
	v_min_i32_e32 v70, 0x8000, v75
	v_ashrrev_i32_e32 v70, 12, v70
	v_mul_hi_i32_i24_e32 v71, 0x6000, v70
	v_mul_i32_i24_e32 v70, 0x6000, v70
	v_lshl_add_u64 v[70:71], s[0:1], 0, v[70:71]
	v_lshl_add_u64 v[72:73], v[70:71], 0, v[96:97]
	v_lshl_add_u64 v[70:71], v[76:77], 0, v[96:97]
	ds_read_b128 v[76:79], v146 offset:6528
	global_load_dwordx4 v[80:83], v[68:69], off
	global_load_dwordx4 v[84:87], v[72:73], off
	s_waitcnt vmcnt(0) lgkmcnt(0)
	v_pk_fma_f32 v[76:77], v[76:77], v[84:85], v[80:81]
	v_pk_fma_f32 v[78:79], v[78:79], v[86:87], v[82:83]
	v_or_b32_e32 v82, v74, v174
	global_store_dwordx4 v[70:71], v[76:79], off
	v_cmp_gt_i32_e32 vcc, s39, v82
	v_ashrrev_i32_e32 v74, 31, v82
	v_add_u32_e32 v76, 0xffff8000, v82
	v_cndmask_b32_e32 v75, 0, v74, vcc
	v_cndmask_b32_e32 v74, v76, v82, vcc
	v_cndmask_b32_e32 v77, v160, v161, vcc
	v_cndmask_b32_e32 v76, v162, v163, vcc
	v_lshlrev_b64 v[74:75], 12, v[74:75]
	v_lshl_add_u64 v[76:77], v[76:77], 0, v[74:75]
	v_cndmask_b32_e32 v79, v164, v165, vcc
	v_cndmask_b32_e32 v78, v166, v167, vcc
	v_lshl_add_u64 v[80:81], v[78:79], 0, v[74:75]
	v_lshl_add_u64 v[74:75], v[76:77], 0, v[96:97]
	v_min_i32_e32 v76, 0x8000, v82
	v_ashrrev_i32_e32 v76, 12, v76
	v_mul_hi_i32_i24_e32 v77, 0x6000, v76
	v_mul_i32_i24_e32 v76, 0x6000, v76
	v_lshl_add_u64 v[76:77], s[0:1], 0, v[76:77]
	v_lshl_add_u64 v[78:79], v[76:77], 0, v[96:97]
	v_lshl_add_u64 v[76:77], v[80:81], 0, v[96:97]
	ds_read_b128 v[80:83], v146 offset:7616
	global_load_dwordx4 v[84:87], v[74:75], off
	global_load_dwordx4 v[88:91], v[78:79], off
	s_waitcnt vmcnt(0) lgkmcnt(0)
	v_pk_fma_f32 v[80:81], v[80:81], v[88:89], v[84:85]
	v_pk_fma_f32 v[82:83], v[82:83], v[90:91], v[86:87]
	global_store_dwordx4 v[76:77], v[80:83], off
	s_waitcnt lgkmcnt(0)
	ds_write2_b32 v147, v16, v17 offset1:68
	ds_write2_b32 v148, v0, v1 offset0:32 offset1:100
	ds_write2_b32 v147, v18, v19 offset0:136 offset1:204
	ds_write2_b32 v148, v2, v3 offset0:168 offset1:236
	ds_write2_b32 v149, v20, v21 offset0:32 offset1:100
	ds_write2_b32 v150, v4, v5 offset0:64 offset1:132
	ds_write2_b32 v149, v22, v23 offset0:168 offset1:236
	ds_write2_b32 v151, v6, v7 offset0:72 offset1:140
	ds_write2_b32 v152, v24, v25 offset0:64 offset1:132
	ds_write2_b32 v153, v8, v9 offset0:96 offset1:164
	ds_write2_b32 v154, v26, v27 offset0:72 offset1:140
	ds_write2_b32 v155, v10, v11 offset0:104 offset1:172
	ds_write2_b32 v156, v28, v29 offset0:96 offset1:164
	ds_write2_b32 v157, v12, v13 offset0:128 offset1:196
	ds_write2_b32 v158, v30, v31 offset0:104 offset1:172
	ds_write2_b32 v159, v14, v15 offset0:8 offset1:76
	s_waitcnt lgkmcnt(0)
	ds_read_b128 v[0:3], v146
	global_load_dwordx4 v[4:7], v[32:33], off offset:256
	global_load_dwordx4 v[8:11], v[36:37], off offset:256
	s_waitcnt vmcnt(0) lgkmcnt(0)
	v_pk_fma_f32 v[0:1], v[0:1], v[8:9], v[4:5]
	v_pk_fma_f32 v[2:3], v[2:3], v[10:11], v[6:7]
	global_store_dwordx4 v[34:35], v[0:3], off offset:256
	ds_read_b128 v[0:3], v146 offset:1088
	global_load_dwordx4 v[4:7], v[38:39], off offset:256
	global_load_dwordx4 v[8:11], v[42:43], off offset:256
	s_waitcnt vmcnt(0) lgkmcnt(0)
	v_pk_fma_f32 v[0:1], v[0:1], v[8:9], v[4:5]
	v_pk_fma_f32 v[2:3], v[2:3], v[10:11], v[6:7]
	global_store_dwordx4 v[40:41], v[0:3], off offset:256
	ds_read_b128 v[0:3], v146 offset:2176
	global_load_dwordx4 v[4:7], v[44:45], off offset:256
	global_load_dwordx4 v[8:11], v[48:49], off offset:256
	s_waitcnt vmcnt(0) lgkmcnt(0)
	v_pk_fma_f32 v[0:1], v[0:1], v[8:9], v[4:5]
	v_pk_fma_f32 v[2:3], v[2:3], v[10:11], v[6:7]
	global_store_dwordx4 v[46:47], v[0:3], off offset:256
	ds_read_b128 v[0:3], v146 offset:3264
	global_load_dwordx4 v[4:7], v[50:51], off offset:256
	global_load_dwordx4 v[8:11], v[54:55], off offset:256
	s_waitcnt vmcnt(0) lgkmcnt(0)
	v_pk_fma_f32 v[0:1], v[0:1], v[8:9], v[4:5]
	v_pk_fma_f32 v[2:3], v[2:3], v[10:11], v[6:7]
	global_store_dwordx4 v[52:53], v[0:3], off offset:256
	ds_read_b128 v[0:3], v146 offset:4352
	global_load_dwordx4 v[4:7], v[56:57], off offset:256
	global_load_dwordx4 v[8:11], v[60:61], off offset:256
	s_waitcnt vmcnt(0) lgkmcnt(0)
	v_pk_fma_f32 v[0:1], v[0:1], v[8:9], v[4:5]
	v_pk_fma_f32 v[2:3], v[2:3], v[10:11], v[6:7]
	global_store_dwordx4 v[58:59], v[0:3], off offset:256
	ds_read_b128 v[0:3], v146 offset:5440
	global_load_dwordx4 v[4:7], v[62:63], off offset:256
	global_load_dwordx4 v[8:11], v[66:67], off offset:256
	s_waitcnt vmcnt(0) lgkmcnt(0)
	v_pk_fma_f32 v[0:1], v[0:1], v[8:9], v[4:5]
	v_pk_fma_f32 v[2:3], v[2:3], v[10:11], v[6:7]
	global_store_dwordx4 v[64:65], v[0:3], off offset:256
	ds_read_b128 v[0:3], v146 offset:6528
	global_load_dwordx4 v[4:7], v[68:69], off offset:256
	global_load_dwordx4 v[8:11], v[72:73], off offset:256
	s_waitcnt vmcnt(0) lgkmcnt(0)
	v_pk_fma_f32 v[0:1], v[0:1], v[8:9], v[4:5]
	v_pk_fma_f32 v[2:3], v[2:3], v[10:11], v[6:7]
	global_store_dwordx4 v[70:71], v[0:3], off offset:256
	ds_read_b128 v[0:3], v146 offset:7616
	global_load_dwordx4 v[4:7], v[74:75], off offset:256
	global_load_dwordx4 v[8:11], v[78:79], off offset:256
	s_waitcnt vmcnt(0) lgkmcnt(0)
	v_pk_fma_f32 v[0:1], v[0:1], v[8:9], v[4:5]
	v_pk_fma_f32 v[2:3], v[2:3], v[10:11], v[6:7]
	global_store_dwordx4 v[76:77], v[0:3], off offset:256
	s_waitcnt lgkmcnt(0)
	s_barrier
	s_cbranch_scc1 .LBB0_923

.LBB0_1031:
	s_mul_hi_i32 s0, s2, 0x2e8ba2e9
	s_lshr_b32 s1, s0, 31
	s_ashr_i32 s0, s0, 6
	s_add_i32 s0, s0, s1
	s_lshl_b32 s1, s0, 3
	s_sub_i32 s7, s25, s1
	s_min_i32 s7, s7, 8
	s_abs_i32 s8, s7
	v_cvt_f32_u32_e32 v0, s8
	s_sub_i32 s11, 0, s8
	s_mulk_i32 s0, 0xfea0
	s_add_i32 s9, s0, s2
	v_rcp_iflag_f32_e32 v0, v0
	s_abs_i32 s0, s9
	s_xor_b32 s10, s9, s7
	s_ashr_i32 s10, s10, 31
	v_mul_f32_e32 v0, 0x4f7ffffe, v0
	v_cvt_u32_f32_e32 v0, v0
	v_mov_b32_e32 v237, v179
	v_readfirstlane_b32 s12, v0
	s_mul_i32 s11, s11, s12
	s_mul_hi_u32 s11, s12, s11
	s_add_i32 s12, s12, s11
	s_mul_hi_u32 s11, s0, s12
	s_mul_i32 s12, s11, s8
	s_sub_i32 s0, s0, s12
	s_add_i32 s13, s11, 1
	s_sub_i32 s12, s0, s8
	s_cmp_ge_u32 s0, s8
	s_cselect_b32 s11, s13, s11
	s_cselect_b32 s0, s12, s0
	s_add_i32 s12, s11, 1
	s_cmp_ge_u32 s0, s8
	s_cselect_b32 s0, s12, s11
	s_xor_b32 s0, s0, s10
	s_sub_i32 s0, s0, s10
	s_mul_i32 s7, s7, s0
	s_sub_i32 s7, s9, s7
	s_add_i32 s1, s1, s6
	v_ashrrev_i32_e32 v238, 6, v237
	s_add_i32 s7, s1, s7
	v_lshlrev_b32_e32 v0, 1, v238
	v_lshl_add_u32 v0, s7, 3, v0
	v_ashrrev_i32_e32 v1, 31, v0
	v_bfe_u32 v183, v237, 5, 1
	v_lshlrev_b64 v[0:1], 16, v[0:1]
	v_and_b32_e32 v239, 31, v237
	v_lshl_add_u64 v[0:1], s[64:65], 0, v[0:1]
	v_lshlrev_b32_e32 v176, 9, v183
	s_ashr_i32 s1, s0, 31
	v_lshl_add_u64 v[0:1], v[0:1], 0, v[176:177]
	v_lshlrev_b32_e32 v176, 4, v239
	v_ashrrev_i32_e32 v38, 2, v237
	s_lshl_b64 s[8:9], s[0:1], 18
	v_lshl_add_u64 v[184:185], v[0:1], 0, v[176:177]
	s_add_u32 s8, s4, s8
	v_lshlrev_b32_e32 v0, 5, v38
	v_lshlrev_b32_e32 v2, 3, v237
	s_addc_u32 s9, s5, s9
	v_ashrrev_i32_e32 v1, 31, v0
	v_and_b32_e32 v181, 24, v2
	v_lshl_add_u64 v[0:1], v[0:1], 1, s[8:9]
	v_lshlrev_b32_e32 v176, 1, v181
	v_lshl_add_u64 v[186:187], v[0:1], 0, v[176:177]
	s_movk_i32 s1, 0x2000
	v_add_co_u32_e32 v34, vcc, s1, v186
	v_mul_u32_u24_e32 v36, 40, v239
	s_nop 0
	v_addc_co_u32_e32 v35, vcc, 0, v187, vcc
	v_lshlrev_b32_e32 v37, 4, v183
	v_lshl_add_u32 v241, v36, 1, v37
	v_add_co_u32_e32 v36, vcc, s41, v184
	s_movk_i32 s8, 0x50
	s_nop 0
	v_addc_co_u32_e32 v37, vcc, 0, v185, vcc
	v_mad_u64_u32 v[188:189], s[8:9], v38, s8, v[176:177]
	v_and_b32_e32 v240, 63, v237
	v_bfe_u32 v247, v237, 4, 2
	v_lshlrev_b32_e32 v247, 1, v247
	v_mov_b32_e32 v176, 0x78
	v_lshrrev_b32_e32 v247, v247, v176
	v_and_b32_e32 v247, 3, v247
	v_and_b32_e32 v246, 3, v237
	v_xor_b32_e32 v247, v247, v246
	v_lshlrev_b32_e32 v247, 4, v247
	v_and_b32_e32 v188, 0xffffffcf, v186
	v_or_b32_e32 v188, v188, v247
	v_mov_b32_e32 v189, v187
	v_lshrrev_b32_e32 v176, 6, v237
	v_lshlrev_b32_e32 v247, 11, v176
	v_lshlrev_b32_e32 v176, 10, v176
	v_lshl_add_u64 v[188:189], v[188:189], 0, v[176:177]
	v_readfirstlane_b32 vcc_lo, v247
	v_bfe_u32 v247, v237, 4, 1
	v_lshlrev_b32_e32 v176, 9, v183
	v_lshl_add_u32 v176, v247, 8, v176
	v_lshl_add_u64 v[184:185], v[184:185], 0, v[176:177]
	v_mov_b32_e32 v176, s41
	v_lshl_add_u64 v[186:187], v[184:185], 0, v[176:177]
	v_mov_b32_e32 v176, 0x78
	v_bfe_u32 v247, v237, 2, 2
	v_lshlrev_b32_e32 v247, 1, v247
	v_lshrrev_b32_e32 v247, v247, v176
	v_and_b32_e32 v247, 3, v247
	v_bfe_u32 v246, v237, 4, 2
	v_xor_b32_e32 v247, v247, v246
	v_lshlrev_b32_e32 v247, 4, v247
	v_and_b32_e32 v246, 15, v237
	v_lshl_add_u32 v246, v246, 6, v247
	s_mov_b32 s96, 0
	s_mov_b32 m0, vcc_lo
	v_lshl_add_u64 v[160:161], v[188:189], 0, s[96:97]
	global_load_lds_dwordx4 v[160:161], off
	global_load_lds_dwordx4 v[160:161], off offset:1024
	s_mov_b32 s96, 0
	v_lshl_add_u64 v[248:249], v[184:185], 0, s[96:97]
	v_lshl_add_u64 v[250:251], v[186:187], 0, s[96:97]
	global_load_dwordx4 v[128:131], v[248:249], off
	global_load_dwordx4 v[132:135], v[248:249], off offset:256
	global_load_dwordx4 v[136:139], v[250:251], off
	global_load_dwordx4 v[140:143], v[250:251], off offset:256
	s_movk_i32 s96, 0x2000
	s_add_i32 m0, vcc_lo, 8192
	v_lshl_add_u64 v[160:161], v[188:189], 0, s[96:97]
	global_load_lds_dwordx4 v[160:161], off
	global_load_lds_dwordx4 v[160:161], off offset:1024
	s_movk_i32 s96, 0x800
	v_lshl_add_u64 v[248:249], v[184:185], 0, s[96:97]
	v_lshl_add_u64 v[250:251], v[186:187], 0, s[96:97]
	global_load_dwordx4 v[144:147], v[248:249], off
	global_load_dwordx4 v[148:151], v[248:249], off offset:256
	global_load_dwordx4 v[152:155], v[250:251], off
	global_load_dwordx4 v[156:159], v[250:251], off offset:256
	v_mov_b32_e32 v0, 0
	v_mov_b32_e32 v1, 0
	v_mov_b32_e32 v2, 0
	v_mov_b32_e32 v3, 0
	v_mov_b32_e32 v4, 0
	v_mov_b32_e32 v5, 0
	v_mov_b32_e32 v6, 0
	v_mov_b32_e32 v7, 0
	v_mov_b32_e32 v8, 0
	v_mov_b32_e32 v9, 0
	v_mov_b32_e32 v10, 0
	v_mov_b32_e32 v11, 0
	v_mov_b32_e32 v12, 0
	v_mov_b32_e32 v13, 0
	v_mov_b32_e32 v14, 0
	v_mov_b32_e32 v15, 0
	v_mov_b32_e32 v16, 0
	v_mov_b32_e32 v17, 0
	v_mov_b32_e32 v18, 0
	v_mov_b32_e32 v19, 0
	v_mov_b32_e32 v20, 0
	v_mov_b32_e32 v21, 0
	v_mov_b32_e32 v22, 0
	v_mov_b32_e32 v23, 0
	v_mov_b32_e32 v24, 0
	v_mov_b32_e32 v25, 0
	v_mov_b32_e32 v26, 0
	v_mov_b32_e32 v27, 0
	v_mov_b32_e32 v28, 0
	v_mov_b32_e32 v29, 0
	v_mov_b32_e32 v30, 0
	v_mov_b32_e32 v31, 0
	v_mov_b32_e32 v32, 0
	v_mov_b32_e32 v33, 0
	v_mov_b32_e32 v34, 0
	v_mov_b32_e32 v35, 0
	v_mov_b32_e32 v36, 0
	v_mov_b32_e32 v37, 0
	v_mov_b32_e32 v38, 0
	v_mov_b32_e32 v39, 0
	v_mov_b32_e32 v40, 0
	v_mov_b32_e32 v41, 0
	v_mov_b32_e32 v42, 0
	v_mov_b32_e32 v43, 0
	v_mov_b32_e32 v44, 0
	v_mov_b32_e32 v45, 0
	v_mov_b32_e32 v46, 0
	v_mov_b32_e32 v47, 0
	v_mov_b32_e32 v48, 0
	v_mov_b32_e32 v49, 0
	v_mov_b32_e32 v50, 0
	v_mov_b32_e32 v51, 0
	v_mov_b32_e32 v52, 0
	v_mov_b32_e32 v53, 0
	v_mov_b32_e32 v54, 0
	v_mov_b32_e32 v55, 0
	v_mov_b32_e32 v56, 0
	v_mov_b32_e32 v57, 0
	v_mov_b32_e32 v58, 0
	v_mov_b32_e32 v59, 0
	v_mov_b32_e32 v60, 0
	v_mov_b32_e32 v61, 0
	v_mov_b32_e32 v62, 0
	v_mov_b32_e32 v63, 0
	v_mov_b32_e32 v64, 0
	v_mov_b32_e32 v65, 0
	v_mov_b32_e32 v66, 0
	v_mov_b32_e32 v67, 0
	v_mov_b32_e32 v68, 0
	v_mov_b32_e32 v69, 0
	v_mov_b32_e32 v70, 0
	v_mov_b32_e32 v71, 0
	v_mov_b32_e32 v72, 0
	v_mov_b32_e32 v73, 0
	v_mov_b32_e32 v74, 0
	v_mov_b32_e32 v75, 0
	v_mov_b32_e32 v76, 0
	v_mov_b32_e32 v77, 0
	v_mov_b32_e32 v78, 0
	v_mov_b32_e32 v79, 0
	v_mov_b32_e32 v80, 0
	v_mov_b32_e32 v81, 0
	v_mov_b32_e32 v82, 0
	v_mov_b32_e32 v83, 0
	v_mov_b32_e32 v84, 0
	v_mov_b32_e32 v85, 0
	v_mov_b32_e32 v86, 0
	v_mov_b32_e32 v87, 0
	v_mov_b32_e32 v88, 0
	v_mov_b32_e32 v89, 0
	v_mov_b32_e32 v90, 0
	v_mov_b32_e32 v91, 0
	v_mov_b32_e32 v92, 0
	v_mov_b32_e32 v93, 0
	v_mov_b32_e32 v94, 0
	v_mov_b32_e32 v95, 0
	v_mov_b32_e32 v96, 0
	v_mov_b32_e32 v97, 0
	v_mov_b32_e32 v98, 0
	v_mov_b32_e32 v99, 0
	v_mov_b32_e32 v100, 0
	v_mov_b32_e32 v101, 0
	v_mov_b32_e32 v102, 0
	v_mov_b32_e32 v103, 0
	v_mov_b32_e32 v104, 0
	v_mov_b32_e32 v105, 0
	v_mov_b32_e32 v106, 0
	v_mov_b32_e32 v107, 0
	v_mov_b32_e32 v108, 0
	v_mov_b32_e32 v109, 0
	v_mov_b32_e32 v110, 0
	v_mov_b32_e32 v111, 0
	v_mov_b32_e32 v112, 0
	v_mov_b32_e32 v113, 0
	v_mov_b32_e32 v114, 0
	v_mov_b32_e32 v115, 0
	v_mov_b32_e32 v116, 0
	v_mov_b32_e32 v117, 0
	v_mov_b32_e32 v118, 0
	v_mov_b32_e32 v119, 0
	v_mov_b32_e32 v120, 0
	v_mov_b32_e32 v121, 0
	v_mov_b32_e32 v122, 0
	v_mov_b32_e32 v123, 0
	v_mov_b32_e32 v124, 0
	v_mov_b32_e32 v125, 0
	v_mov_b32_e32 v126, 0
	v_mov_b32_e32 v127, 0
	s_mov_b32 s1, 0
	s_waitcnt vmcnt(4)
	s_barrier
	s_setprio 2
.Lg16_gu_k:
	s_add_i32 s8, s1, 2
	s_lshl_b32 s96, s8, 13
	s_add_i32 m0, vcc_lo, 16384
	v_lshl_add_u64 v[160:161], v[188:189], 0, s[96:97]
	global_load_lds_dwordx4 v[160:161], off
	global_load_lds_dwordx4 v[160:161], off offset:1024
	ds_read_b128 v[196:199], v246 offset:0
	ds_read_b128 v[200:203], v246 offset:1024
	ds_read_b128 v[204:207], v246 offset:2048
	ds_read_b128 v[242:245], v246 offset:3072
	s_add_i32 s8, s1, 2
	s_lshl_b32 s96, s8, 11
	v_lshl_add_u64 v[248:249], v[184:185], 0, s[96:97]
	v_lshl_add_u64 v[250:251], v[186:187], 0, s[96:97]
	s_waitcnt vmcnt(8) lgkmcnt(3)
	v_mfma_f32_16x16x32_bf16 v[112:115], v[128:131], v[196:199], v[112:115]
	v_mfma_f32_16x16x32_bf16 v[120:123], v[132:135], v[196:199], v[120:123]
	v_mfma_f32_16x16x32_bf16 v[80:83], v[136:139], v[196:199], v[80:83]
	v_mfma_f32_16x16x32_bf16 v[88:91], v[140:143], v[196:199], v[88:91]
	ds_read_b128 v[196:199], v246 offset:4096
	s_waitcnt lgkmcnt(3)
	v_mfma_f32_16x16x32_bf16 v[116:119], v[128:131], v[200:203], v[116:119]
	v_mfma_f32_16x16x32_bf16 v[124:127], v[132:135], v[200:203], v[124:127]
	v_mfma_f32_16x16x32_bf16 v[84:87], v[136:139], v[200:203], v[84:87]
	v_mfma_f32_16x16x32_bf16 v[92:95], v[140:143], v[200:203], v[92:95]
	ds_read_b128 v[200:203], v246 offset:5120
	s_waitcnt lgkmcnt(3)
	v_mfma_f32_16x16x32_bf16 v[96:99], v[128:131], v[204:207], v[96:99]
	v_mfma_f32_16x16x32_bf16 v[104:107], v[132:135], v[204:207], v[104:107]
	v_mfma_f32_16x16x32_bf16 v[64:67], v[136:139], v[204:207], v[64:67]
	v_mfma_f32_16x16x32_bf16 v[72:75], v[140:143], v[204:207], v[72:75]
	ds_read_b128 v[204:207], v246 offset:6144
	s_waitcnt lgkmcnt(3)
	v_mfma_f32_16x16x32_bf16 v[100:103], v[128:131], v[242:245], v[100:103]
	v_mfma_f32_16x16x32_bf16 v[108:111], v[132:135], v[242:245], v[108:111]
	v_mfma_f32_16x16x32_bf16 v[68:71], v[136:139], v[242:245], v[68:71]
	v_mfma_f32_16x16x32_bf16 v[76:79], v[140:143], v[242:245], v[76:79]
	ds_read_b128 v[242:245], v246 offset:7168
	s_waitcnt lgkmcnt(3)
	v_mfma_f32_16x16x32_bf16 v[48:51], v[128:131], v[196:199], v[48:51]
	v_mfma_f32_16x16x32_bf16 v[56:59], v[132:135], v[196:199], v[56:59]
	v_mfma_f32_16x16x32_bf16 v[16:19], v[136:139], v[196:199], v[16:19]
	v_mfma_f32_16x16x32_bf16 v[24:27], v[140:143], v[196:199], v[24:27]
	s_waitcnt lgkmcnt(2)
	v_mfma_f32_16x16x32_bf16 v[52:55], v[128:131], v[200:203], v[52:55]
	v_mfma_f32_16x16x32_bf16 v[60:63], v[132:135], v[200:203], v[60:63]
	v_mfma_f32_16x16x32_bf16 v[20:23], v[136:139], v[200:203], v[20:23]
	v_mfma_f32_16x16x32_bf16 v[28:31], v[140:143], v[200:203], v[28:31]
	s_waitcnt lgkmcnt(1)
	v_mfma_f32_16x16x32_bf16 v[32:35], v[128:131], v[204:207], v[32:35]
	v_mfma_f32_16x16x32_bf16 v[40:43], v[132:135], v[204:207], v[40:43]
	v_mfma_f32_16x16x32_bf16 v[0:3], v[136:139], v[204:207], v[0:3]
	v_mfma_f32_16x16x32_bf16 v[8:11], v[140:143], v[204:207], v[8:11]
	s_waitcnt lgkmcnt(0)
	v_mfma_f32_16x16x32_bf16 v[36:39], v[128:131], v[242:245], v[36:39]
	v_mfma_f32_16x16x32_bf16 v[44:47], v[132:135], v[242:245], v[44:47]
	v_mfma_f32_16x16x32_bf16 v[4:7], v[136:139], v[242:245], v[4:7]
	v_mfma_f32_16x16x32_bf16 v[12:15], v[140:143], v[242:245], v[12:15]
	global_load_dwordx4 v[128:131], v[248:249], off
	global_load_dwordx4 v[132:135], v[248:249], off offset:256
	global_load_dwordx4 v[136:139], v[250:251], off
	global_load_dwordx4 v[140:143], v[250:251], off offset:256
	s_waitcnt vmcnt(10)
	s_barrier
	s_add_i32 s8, s1, 3
	s_lshl_b32 s96, s8, 13
	s_mov_b32 m0, vcc_lo
	v_lshl_add_u64 v[160:161], v[188:189], 0, s[96:97]
	global_load_lds_dwordx4 v[160:161], off
	global_load_lds_dwordx4 v[160:161], off offset:1024
	ds_read_b128 v[196:199], v246 offset:8192
	ds_read_b128 v[200:203], v246 offset:9216
	ds_read_b128 v[204:207], v246 offset:10240
	ds_read_b128 v[242:245], v246 offset:11264
	s_add_i32 s8, s1, 3
	s_lshl_b32 s96, s8, 11
	v_lshl_add_u64 v[248:249], v[184:185], 0, s[96:97]
	v_lshl_add_u64 v[250:251], v[186:187], 0, s[96:97]
	s_waitcnt vmcnt(8) lgkmcnt(3)
	v_mfma_f32_16x16x32_bf16 v[112:115], v[144:147], v[196:199], v[112:115]
	v_mfma_f32_16x16x32_bf16 v[120:123], v[148:151], v[196:199], v[120:123]
	v_mfma_f32_16x16x32_bf16 v[80:83], v[152:155], v[196:199], v[80:83]
	v_mfma_f32_16x16x32_bf16 v[88:91], v[156:159], v[196:199], v[88:91]
	ds_read_b128 v[196:199], v246 offset:12288
	s_waitcnt lgkmcnt(3)
	v_mfma_f32_16x16x32_bf16 v[116:119], v[144:147], v[200:203], v[116:119]
	v_mfma_f32_16x16x32_bf16 v[124:127], v[148:151], v[200:203], v[124:127]
	v_mfma_f32_16x16x32_bf16 v[84:87], v[152:155], v[200:203], v[84:87]
	v_mfma_f32_16x16x32_bf16 v[92:95], v[156:159], v[200:203], v[92:95]
	ds_read_b128 v[200:203], v246 offset:13312
	s_waitcnt lgkmcnt(3)
	v_mfma_f32_16x16x32_bf16 v[96:99], v[144:147], v[204:207], v[96:99]
	v_mfma_f32_16x16x32_bf16 v[104:107], v[148:151], v[204:207], v[104:107]
	v_mfma_f32_16x16x32_bf16 v[64:67], v[152:155], v[204:207], v[64:67]
	v_mfma_f32_16x16x32_bf16 v[72:75], v[156:159], v[204:207], v[72:75]
	ds_read_b128 v[204:207], v246 offset:14336
	s_waitcnt lgkmcnt(3)
	v_mfma_f32_16x16x32_bf16 v[100:103], v[144:147], v[242:245], v[100:103]
	v_mfma_f32_16x16x32_bf16 v[108:111], v[148:151], v[242:245], v[108:111]
	v_mfma_f32_16x16x32_bf16 v[68:71], v[152:155], v[242:245], v[68:71]
	v_mfma_f32_16x16x32_bf16 v[76:79], v[156:159], v[242:245], v[76:79]
	ds_read_b128 v[242:245], v246 offset:15360
	s_waitcnt lgkmcnt(3)
	v_mfma_f32_16x16x32_bf16 v[48:51], v[144:147], v[196:199], v[48:51]
	v_mfma_f32_16x16x32_bf16 v[56:59], v[148:151], v[196:199], v[56:59]
	v_mfma_f32_16x16x32_bf16 v[16:19], v[152:155], v[196:199], v[16:19]
	v_mfma_f32_16x16x32_bf16 v[24:27], v[156:159], v[196:199], v[24:27]
	s_waitcnt lgkmcnt(2)
	v_mfma_f32_16x16x32_bf16 v[52:55], v[144:147], v[200:203], v[52:55]
	v_mfma_f32_16x16x32_bf16 v[60:63], v[148:151], v[200:203], v[60:63]
	v_mfma_f32_16x16x32_bf16 v[20:23], v[152:155], v[200:203], v[20:23]
	v_mfma_f32_16x16x32_bf16 v[28:31], v[156:159], v[200:203], v[28:31]
	s_waitcnt lgkmcnt(1)
	v_mfma_f32_16x16x32_bf16 v[32:35], v[144:147], v[204:207], v[32:35]
	v_mfma_f32_16x16x32_bf16 v[40:43], v[148:151], v[204:207], v[40:43]
	v_mfma_f32_16x16x32_bf16 v[0:3], v[152:155], v[204:207], v[0:3]
	v_mfma_f32_16x16x32_bf16 v[8:11], v[156:159], v[204:207], v[8:11]
	s_waitcnt lgkmcnt(0)
	v_mfma_f32_16x16x32_bf16 v[36:39], v[144:147], v[242:245], v[36:39]
	v_mfma_f32_16x16x32_bf16 v[44:47], v[148:151], v[242:245], v[44:47]
	v_mfma_f32_16x16x32_bf16 v[4:7], v[152:155], v[242:245], v[4:7]
	v_mfma_f32_16x16x32_bf16 v[12:15], v[156:159], v[242:245], v[12:15]
	global_load_dwordx4 v[144:147], v[248:249], off
	global_load_dwordx4 v[148:151], v[248:249], off offset:256
	global_load_dwordx4 v[152:155], v[250:251], off
	global_load_dwordx4 v[156:159], v[250:251], off offset:256
	s_waitcnt vmcnt(10)
	s_barrier
	s_add_i32 s8, s1, 4
	s_lshl_b32 s96, s8, 13
	s_add_i32 m0, vcc_lo, 8192
	v_lshl_add_u64 v[160:161], v[188:189], 0, s[96:97]
	global_load_lds_dwordx4 v[160:161], off
	global_load_lds_dwordx4 v[160:161], off offset:1024
	ds_read_b128 v[196:199], v246 offset:16384
	ds_read_b128 v[200:203], v246 offset:17408
	ds_read_b128 v[204:207], v246 offset:18432
	ds_read_b128 v[242:245], v246 offset:19456
	s_add_i32 s8, s1, 4
	s_lshl_b32 s96, s8, 11
	v_lshl_add_u64 v[248:249], v[184:185], 0, s[96:97]
	v_lshl_add_u64 v[250:251], v[186:187], 0, s[96:97]
	s_waitcnt vmcnt(8) lgkmcnt(3)
	v_mfma_f32_16x16x32_bf16 v[112:115], v[128:131], v[196:199], v[112:115]
	v_mfma_f32_16x16x32_bf16 v[120:123], v[132:135], v[196:199], v[120:123]
	v_mfma_f32_16x16x32_bf16 v[80:83], v[136:139], v[196:199], v[80:83]
	v_mfma_f32_16x16x32_bf16 v[88:91], v[140:143], v[196:199], v[88:91]
	ds_read_b128 v[196:199], v246 offset:20480
	s_waitcnt lgkmcnt(3)
	v_mfma_f32_16x16x32_bf16 v[116:119], v[128:131], v[200:203], v[116:119]
	v_mfma_f32_16x16x32_bf16 v[124:127], v[132:135], v[200:203], v[124:127]
	v_mfma_f32_16x16x32_bf16 v[84:87], v[136:139], v[200:203], v[84:87]
	v_mfma_f32_16x16x32_bf16 v[92:95], v[140:143], v[200:203], v[92:95]
	ds_read_b128 v[200:203], v246 offset:21504
	s_waitcnt lgkmcnt(3)
	v_mfma_f32_16x16x32_bf16 v[96:99], v[128:131], v[204:207], v[96:99]
	v_mfma_f32_16x16x32_bf16 v[104:107], v[132:135], v[204:207], v[104:107]
	v_mfma_f32_16x16x32_bf16 v[64:67], v[136:139], v[204:207], v[64:67]
	v_mfma_f32_16x16x32_bf16 v[72:75], v[140:143], v[204:207], v[72:75]
	ds_read_b128 v[204:207], v246 offset:22528
	s_waitcnt lgkmcnt(3)
	v_mfma_f32_16x16x32_bf16 v[100:103], v[128:131], v[242:245], v[100:103]
	v_mfma_f32_16x16x32_bf16 v[108:111], v[132:135], v[242:245], v[108:111]
	v_mfma_f32_16x16x32_bf16 v[68:71], v[136:139], v[242:245], v[68:71]
	v_mfma_f32_16x16x32_bf16 v[76:79], v[140:143], v[242:245], v[76:79]
	ds_read_b128 v[242:245], v246 offset:23552
	s_waitcnt lgkmcnt(3)
	v_mfma_f32_16x16x32_bf16 v[48:51], v[128:131], v[196:199], v[48:51]
	v_mfma_f32_16x16x32_bf16 v[56:59], v[132:135], v[196:199], v[56:59]
	v_mfma_f32_16x16x32_bf16 v[16:19], v[136:139], v[196:199], v[16:19]
	v_mfma_f32_16x16x32_bf16 v[24:27], v[140:143], v[196:199], v[24:27]
	s_waitcnt lgkmcnt(2)
	v_mfma_f32_16x16x32_bf16 v[52:55], v[128:131], v[200:203], v[52:55]
	v_mfma_f32_16x16x32_bf16 v[60:63], v[132:135], v[200:203], v[60:63]
	v_mfma_f32_16x16x32_bf16 v[20:23], v[136:139], v[200:203], v[20:23]
	v_mfma_f32_16x16x32_bf16 v[28:31], v[140:143], v[200:203], v[28:31]
	s_waitcnt lgkmcnt(1)
	v_mfma_f32_16x16x32_bf16 v[32:35], v[128:131], v[204:207], v[32:35]
	v_mfma_f32_16x16x32_bf16 v[40:43], v[132:135], v[204:207], v[40:43]
	v_mfma_f32_16x16x32_bf16 v[0:3], v[136:139], v[204:207], v[0:3]
	v_mfma_f32_16x16x32_bf16 v[8:11], v[140:143], v[204:207], v[8:11]
	s_waitcnt lgkmcnt(0)
	v_mfma_f32_16x16x32_bf16 v[36:39], v[128:131], v[242:245], v[36:39]
	v_mfma_f32_16x16x32_bf16 v[44:47], v[132:135], v[242:245], v[44:47]
	v_mfma_f32_16x16x32_bf16 v[4:7], v[136:139], v[242:245], v[4:7]
	v_mfma_f32_16x16x32_bf16 v[12:15], v[140:143], v[242:245], v[12:15]
	global_load_dwordx4 v[128:131], v[248:249], off
	global_load_dwordx4 v[132:135], v[248:249], off offset:256
	global_load_dwordx4 v[136:139], v[250:251], off
	global_load_dwordx4 v[140:143], v[250:251], off offset:256
	s_waitcnt vmcnt(10)
	s_barrier
	s_add_i32 s8, s1, 5
	s_lshl_b32 s96, s8, 13
	s_add_i32 m0, vcc_lo, 16384
	v_lshl_add_u64 v[160:161], v[188:189], 0, s[96:97]
	global_load_lds_dwordx4 v[160:161], off
	global_load_lds_dwordx4 v[160:161], off offset:1024
	ds_read_b128 v[196:199], v246 offset:0
	ds_read_b128 v[200:203], v246 offset:1024
	ds_read_b128 v[204:207], v246 offset:2048
	ds_read_b128 v[242:245], v246 offset:3072
	s_add_i32 s8, s1, 5
	s_lshl_b32 s96, s8, 11
	v_lshl_add_u64 v[248:249], v[184:185], 0, s[96:97]
	v_lshl_add_u64 v[250:251], v[186:187], 0, s[96:97]
	s_waitcnt vmcnt(8) lgkmcnt(3)
	v_mfma_f32_16x16x32_bf16 v[112:115], v[144:147], v[196:199], v[112:115]
	v_mfma_f32_16x16x32_bf16 v[120:123], v[148:151], v[196:199], v[120:123]
	v_mfma_f32_16x16x32_bf16 v[80:83], v[152:155], v[196:199], v[80:83]
	v_mfma_f32_16x16x32_bf16 v[88:91], v[156:159], v[196:199], v[88:91]
	ds_read_b128 v[196:199], v246 offset:4096
	s_waitcnt lgkmcnt(3)
	v_mfma_f32_16x16x32_bf16 v[116:119], v[144:147], v[200:203], v[116:119]
	v_mfma_f32_16x16x32_bf16 v[124:127], v[148:151], v[200:203], v[124:127]
	v_mfma_f32_16x16x32_bf16 v[84:87], v[152:155], v[200:203], v[84:87]
	v_mfma_f32_16x16x32_bf16 v[92:95], v[156:159], v[200:203], v[92:95]
	ds_read_b128 v[200:203], v246 offset:5120
	s_waitcnt lgkmcnt(3)
	v_mfma_f32_16x16x32_bf16 v[96:99], v[144:147], v[204:207], v[96:99]
	v_mfma_f32_16x16x32_bf16 v[104:107], v[148:151], v[204:207], v[104:107]
	v_mfma_f32_16x16x32_bf16 v[64:67], v[152:155], v[204:207], v[64:67]
	v_mfma_f32_16x16x32_bf16 v[72:75], v[156:159], v[204:207], v[72:75]
	ds_read_b128 v[204:207], v246 offset:6144
	s_waitcnt lgkmcnt(3)
	v_mfma_f32_16x16x32_bf16 v[100:103], v[144:147], v[242:245], v[100:103]
	v_mfma_f32_16x16x32_bf16 v[108:111], v[148:151], v[242:245], v[108:111]
	v_mfma_f32_16x16x32_bf16 v[68:71], v[152:155], v[242:245], v[68:71]
	v_mfma_f32_16x16x32_bf16 v[76:79], v[156:159], v[242:245], v[76:79]
	ds_read_b128 v[242:245], v246 offset:7168
	s_waitcnt lgkmcnt(3)
	v_mfma_f32_16x16x32_bf16 v[48:51], v[144:147], v[196:199], v[48:51]
	v_mfma_f32_16x16x32_bf16 v[56:59], v[148:151], v[196:199], v[56:59]
	v_mfma_f32_16x16x32_bf16 v[16:19], v[152:155], v[196:199], v[16:19]
	v_mfma_f32_16x16x32_bf16 v[24:27], v[156:159], v[196:199], v[24:27]
	s_waitcnt lgkmcnt(2)
	v_mfma_f32_16x16x32_bf16 v[52:55], v[144:147], v[200:203], v[52:55]
	v_mfma_f32_16x16x32_bf16 v[60:63], v[148:151], v[200:203], v[60:63]
	v_mfma_f32_16x16x32_bf16 v[20:23], v[152:155], v[200:203], v[20:23]
	v_mfma_f32_16x16x32_bf16 v[28:31], v[156:159], v[200:203], v[28:31]
	s_waitcnt lgkmcnt(1)
	v_mfma_f32_16x16x32_bf16 v[32:35], v[144:147], v[204:207], v[32:35]
	v_mfma_f32_16x16x32_bf16 v[40:43], v[148:151], v[204:207], v[40:43]
	v_mfma_f32_16x16x32_bf16 v[0:3], v[152:155], v[204:207], v[0:3]
	v_mfma_f32_16x16x32_bf16 v[8:11], v[156:159], v[204:207], v[8:11]
	s_waitcnt lgkmcnt(0)
	v_mfma_f32_16x16x32_bf16 v[36:39], v[144:147], v[242:245], v[36:39]
	v_mfma_f32_16x16x32_bf16 v[44:47], v[148:151], v[242:245], v[44:47]
	v_mfma_f32_16x16x32_bf16 v[4:7], v[152:155], v[242:245], v[4:7]
	v_mfma_f32_16x16x32_bf16 v[12:15], v[156:159], v[242:245], v[12:15]
	global_load_dwordx4 v[144:147], v[248:249], off
	global_load_dwordx4 v[148:151], v[248:249], off offset:256
	global_load_dwordx4 v[152:155], v[250:251], off
	global_load_dwordx4 v[156:159], v[250:251], off offset:256
	s_waitcnt vmcnt(10)
	s_barrier
	s_add_i32 s8, s1, 6
	s_lshl_b32 s96, s8, 13
	s_mov_b32 m0, vcc_lo
	v_lshl_add_u64 v[160:161], v[188:189], 0, s[96:97]
	global_load_lds_dwordx4 v[160:161], off
	global_load_lds_dwordx4 v[160:161], off offset:1024
	ds_read_b128 v[196:199], v246 offset:8192
	ds_read_b128 v[200:203], v246 offset:9216
	ds_read_b128 v[204:207], v246 offset:10240
	ds_read_b128 v[242:245], v246 offset:11264
	s_add_i32 s8, s1, 6
	s_lshl_b32 s96, s8, 11
	v_lshl_add_u64 v[248:249], v[184:185], 0, s[96:97]
	v_lshl_add_u64 v[250:251], v[186:187], 0, s[96:97]
	s_waitcnt vmcnt(8) lgkmcnt(3)
	v_mfma_f32_16x16x32_bf16 v[112:115], v[128:131], v[196:199], v[112:115]
	v_mfma_f32_16x16x32_bf16 v[120:123], v[132:135], v[196:199], v[120:123]
	v_mfma_f32_16x16x32_bf16 v[80:83], v[136:139], v[196:199], v[80:83]
	v_mfma_f32_16x16x32_bf16 v[88:91], v[140:143], v[196:199], v[88:91]
	ds_read_b128 v[196:199], v246 offset:12288
	s_waitcnt lgkmcnt(3)
	v_mfma_f32_16x16x32_bf16 v[116:119], v[128:131], v[200:203], v[116:119]
	v_mfma_f32_16x16x32_bf16 v[124:127], v[132:135], v[200:203], v[124:127]
	v_mfma_f32_16x16x32_bf16 v[84:87], v[136:139], v[200:203], v[84:87]
	v_mfma_f32_16x16x32_bf16 v[92:95], v[140:143], v[200:203], v[92:95]
	ds_read_b128 v[200:203], v246 offset:13312
	s_waitcnt lgkmcnt(3)
	v_mfma_f32_16x16x32_bf16 v[96:99], v[128:131], v[204:207], v[96:99]
	v_mfma_f32_16x16x32_bf16 v[104:107], v[132:135], v[204:207], v[104:107]
	v_mfma_f32_16x16x32_bf16 v[64:67], v[136:139], v[204:207], v[64:67]
	v_mfma_f32_16x16x32_bf16 v[72:75], v[140:143], v[204:207], v[72:75]
	ds_read_b128 v[204:207], v246 offset:14336
	s_waitcnt lgkmcnt(3)
	v_mfma_f32_16x16x32_bf16 v[100:103], v[128:131], v[242:245], v[100:103]
	v_mfma_f32_16x16x32_bf16 v[108:111], v[132:135], v[242:245], v[108:111]
	v_mfma_f32_16x16x32_bf16 v[68:71], v[136:139], v[242:245], v[68:71]
	v_mfma_f32_16x16x32_bf16 v[76:79], v[140:143], v[242:245], v[76:79]
	ds_read_b128 v[242:245], v246 offset:15360
	s_waitcnt lgkmcnt(3)
	v_mfma_f32_16x16x32_bf16 v[48:51], v[128:131], v[196:199], v[48:51]
	v_mfma_f32_16x16x32_bf16 v[56:59], v[132:135], v[196:199], v[56:59]
	v_mfma_f32_16x16x32_bf16 v[16:19], v[136:139], v[196:199], v[16:19]
	v_mfma_f32_16x16x32_bf16 v[24:27], v[140:143], v[196:199], v[24:27]
	s_waitcnt lgkmcnt(2)
	v_mfma_f32_16x16x32_bf16 v[52:55], v[128:131], v[200:203], v[52:55]
	v_mfma_f32_16x16x32_bf16 v[60:63], v[132:135], v[200:203], v[60:63]
	v_mfma_f32_16x16x32_bf16 v[20:23], v[136:139], v[200:203], v[20:23]
	v_mfma_f32_16x16x32_bf16 v[28:31], v[140:143], v[200:203], v[28:31]
	s_waitcnt lgkmcnt(1)
	v_mfma_f32_16x16x32_bf16 v[32:35], v[128:131], v[204:207], v[32:35]
	v_mfma_f32_16x16x32_bf16 v[40:43], v[132:135], v[204:207], v[40:43]
	v_mfma_f32_16x16x32_bf16 v[0:3], v[136:139], v[204:207], v[0:3]
	v_mfma_f32_16x16x32_bf16 v[8:11], v[140:143], v[204:207], v[8:11]
	s_waitcnt lgkmcnt(0)
	v_mfma_f32_16x16x32_bf16 v[36:39], v[128:131], v[242:245], v[36:39]
	v_mfma_f32_16x16x32_bf16 v[44:47], v[132:135], v[242:245], v[44:47]
	v_mfma_f32_16x16x32_bf16 v[4:7], v[136:139], v[242:245], v[4:7]
	v_mfma_f32_16x16x32_bf16 v[12:15], v[140:143], v[242:245], v[12:15]
	global_load_dwordx4 v[128:131], v[248:249], off
	global_load_dwordx4 v[132:135], v[248:249], off offset:256
	global_load_dwordx4 v[136:139], v[250:251], off
	global_load_dwordx4 v[140:143], v[250:251], off offset:256
	s_waitcnt vmcnt(10)
	s_barrier
	s_add_i32 s8, s1, 7
	s_lshl_b32 s96, s8, 13
	s_add_i32 m0, vcc_lo, 8192
	v_lshl_add_u64 v[160:161], v[188:189], 0, s[96:97]
	global_load_lds_dwordx4 v[160:161], off
	global_load_lds_dwordx4 v[160:161], off offset:1024
	ds_read_b128 v[196:199], v246 offset:16384
	ds_read_b128 v[200:203], v246 offset:17408
	ds_read_b128 v[204:207], v246 offset:18432
	ds_read_b128 v[242:245], v246 offset:19456
	s_add_i32 s8, s1, 7
	s_lshl_b32 s96, s8, 11
	v_lshl_add_u64 v[248:249], v[184:185], 0, s[96:97]
	v_lshl_add_u64 v[250:251], v[186:187], 0, s[96:97]
	s_waitcnt vmcnt(8) lgkmcnt(3)
	v_mfma_f32_16x16x32_bf16 v[112:115], v[144:147], v[196:199], v[112:115]
	v_mfma_f32_16x16x32_bf16 v[120:123], v[148:151], v[196:199], v[120:123]
	v_mfma_f32_16x16x32_bf16 v[80:83], v[152:155], v[196:199], v[80:83]
	v_mfma_f32_16x16x32_bf16 v[88:91], v[156:159], v[196:199], v[88:91]
	ds_read_b128 v[196:199], v246 offset:20480
	s_waitcnt lgkmcnt(3)
	v_mfma_f32_16x16x32_bf16 v[116:119], v[144:147], v[200:203], v[116:119]
	v_mfma_f32_16x16x32_bf16 v[124:127], v[148:151], v[200:203], v[124:127]
	v_mfma_f32_16x16x32_bf16 v[84:87], v[152:155], v[200:203], v[84:87]
	v_mfma_f32_16x16x32_bf16 v[92:95], v[156:159], v[200:203], v[92:95]
	ds_read_b128 v[200:203], v246 offset:21504
	s_waitcnt lgkmcnt(3)
	v_mfma_f32_16x16x32_bf16 v[96:99], v[144:147], v[204:207], v[96:99]
	v_mfma_f32_16x16x32_bf16 v[104:107], v[148:151], v[204:207], v[104:107]
	v_mfma_f32_16x16x32_bf16 v[64:67], v[152:155], v[204:207], v[64:67]
	v_mfma_f32_16x16x32_bf16 v[72:75], v[156:159], v[204:207], v[72:75]
	ds_read_b128 v[204:207], v246 offset:22528
	s_waitcnt lgkmcnt(3)
	v_mfma_f32_16x16x32_bf16 v[100:103], v[144:147], v[242:245], v[100:103]
	v_mfma_f32_16x16x32_bf16 v[108:111], v[148:151], v[242:245], v[108:111]
	v_mfma_f32_16x16x32_bf16 v[68:71], v[152:155], v[242:245], v[68:71]
	v_mfma_f32_16x16x32_bf16 v[76:79], v[156:159], v[242:245], v[76:79]
	ds_read_b128 v[242:245], v246 offset:23552
	s_waitcnt lgkmcnt(3)
	v_mfma_f32_16x16x32_bf16 v[48:51], v[144:147], v[196:199], v[48:51]
	v_mfma_f32_16x16x32_bf16 v[56:59], v[148:151], v[196:199], v[56:59]
	v_mfma_f32_16x16x32_bf16 v[16:19], v[152:155], v[196:199], v[16:19]
	v_mfma_f32_16x16x32_bf16 v[24:27], v[156:159], v[196:199], v[24:27]
	s_waitcnt lgkmcnt(2)
	v_mfma_f32_16x16x32_bf16 v[52:55], v[144:147], v[200:203], v[52:55]
	v_mfma_f32_16x16x32_bf16 v[60:63], v[148:151], v[200:203], v[60:63]
	v_mfma_f32_16x16x32_bf16 v[20:23], v[152:155], v[200:203], v[20:23]
	v_mfma_f32_16x16x32_bf16 v[28:31], v[156:159], v[200:203], v[28:31]
	s_waitcnt lgkmcnt(1)
	v_mfma_f32_16x16x32_bf16 v[32:35], v[144:147], v[204:207], v[32:35]
	v_mfma_f32_16x16x32_bf16 v[40:43], v[148:151], v[204:207], v[40:43]
	v_mfma_f32_16x16x32_bf16 v[0:3], v[152:155], v[204:207], v[0:3]
	v_mfma_f32_16x16x32_bf16 v[8:11], v[156:159], v[204:207], v[8:11]
	s_waitcnt lgkmcnt(0)
	v_mfma_f32_16x16x32_bf16 v[36:39], v[144:147], v[242:245], v[36:39]
	v_mfma_f32_16x16x32_bf16 v[44:47], v[148:151], v[242:245], v[44:47]
	v_mfma_f32_16x16x32_bf16 v[4:7], v[152:155], v[242:245], v[4:7]
	v_mfma_f32_16x16x32_bf16 v[12:15], v[156:159], v[242:245], v[12:15]
	global_load_dwordx4 v[144:147], v[248:249], off
	global_load_dwordx4 v[148:151], v[248:249], off offset:256
	global_load_dwordx4 v[152:155], v[250:251], off
	global_load_dwordx4 v[156:159], v[250:251], off offset:256
	s_waitcnt vmcnt(10)
	s_barrier
	s_add_i32 s1, s1, 6
	s_cmp_lt_u32 s1, 30
	s_cbranch_scc1 .Lg16_gu_k
	ds_read_b128 v[196:199], v246 offset:0
	ds_read_b128 v[200:203], v246 offset:1024
	ds_read_b128 v[204:207], v246 offset:2048
	ds_read_b128 v[242:245], v246 offset:3072
	s_waitcnt vmcnt(6) lgkmcnt(3)
	v_mfma_f32_16x16x32_bf16 v[112:115], v[128:131], v[196:199], v[112:115]
	v_mfma_f32_16x16x32_bf16 v[120:123], v[132:135], v[196:199], v[120:123]
	v_mfma_f32_16x16x32_bf16 v[80:83], v[136:139], v[196:199], v[80:83]
	v_mfma_f32_16x16x32_bf16 v[88:91], v[140:143], v[196:199], v[88:91]
	ds_read_b128 v[196:199], v246 offset:4096
	s_waitcnt lgkmcnt(3)
	v_mfma_f32_16x16x32_bf16 v[116:119], v[128:131], v[200:203], v[116:119]
	v_mfma_f32_16x16x32_bf16 v[124:127], v[132:135], v[200:203], v[124:127]
	v_mfma_f32_16x16x32_bf16 v[84:87], v[136:139], v[200:203], v[84:87]
	v_mfma_f32_16x16x32_bf16 v[92:95], v[140:143], v[200:203], v[92:95]
	ds_read_b128 v[200:203], v246 offset:5120
	s_waitcnt lgkmcnt(3)
	v_mfma_f32_16x16x32_bf16 v[96:99], v[128:131], v[204:207], v[96:99]
	v_mfma_f32_16x16x32_bf16 v[104:107], v[132:135], v[204:207], v[104:107]
	v_mfma_f32_16x16x32_bf16 v[64:67], v[136:139], v[204:207], v[64:67]
	v_mfma_f32_16x16x32_bf16 v[72:75], v[140:143], v[204:207], v[72:75]
	ds_read_b128 v[204:207], v246 offset:6144
	s_waitcnt lgkmcnt(3)
	v_mfma_f32_16x16x32_bf16 v[100:103], v[128:131], v[242:245], v[100:103]
	v_mfma_f32_16x16x32_bf16 v[108:111], v[132:135], v[242:245], v[108:111]
	v_mfma_f32_16x16x32_bf16 v[68:71], v[136:139], v[242:245], v[68:71]
	v_mfma_f32_16x16x32_bf16 v[76:79], v[140:143], v[242:245], v[76:79]
	ds_read_b128 v[242:245], v246 offset:7168
	s_waitcnt lgkmcnt(3)
	v_mfma_f32_16x16x32_bf16 v[48:51], v[128:131], v[196:199], v[48:51]
	v_mfma_f32_16x16x32_bf16 v[56:59], v[132:135], v[196:199], v[56:59]
	v_mfma_f32_16x16x32_bf16 v[16:19], v[136:139], v[196:199], v[16:19]
	v_mfma_f32_16x16x32_bf16 v[24:27], v[140:143], v[196:199], v[24:27]
	s_waitcnt lgkmcnt(2)
	v_mfma_f32_16x16x32_bf16 v[52:55], v[128:131], v[200:203], v[52:55]
	v_mfma_f32_16x16x32_bf16 v[60:63], v[132:135], v[200:203], v[60:63]
	v_mfma_f32_16x16x32_bf16 v[20:23], v[136:139], v[200:203], v[20:23]
	v_mfma_f32_16x16x32_bf16 v[28:31], v[140:143], v[200:203], v[28:31]
	s_waitcnt lgkmcnt(1)
	v_mfma_f32_16x16x32_bf16 v[32:35], v[128:131], v[204:207], v[32:35]
	v_mfma_f32_16x16x32_bf16 v[40:43], v[132:135], v[204:207], v[40:43]
	v_mfma_f32_16x16x32_bf16 v[0:3], v[136:139], v[204:207], v[0:3]
	v_mfma_f32_16x16x32_bf16 v[8:11], v[140:143], v[204:207], v[8:11]
	s_waitcnt lgkmcnt(0)
	v_mfma_f32_16x16x32_bf16 v[36:39], v[128:131], v[242:245], v[36:39]
	v_mfma_f32_16x16x32_bf16 v[44:47], v[132:135], v[242:245], v[44:47]
	v_mfma_f32_16x16x32_bf16 v[4:7], v[136:139], v[242:245], v[4:7]
	v_mfma_f32_16x16x32_bf16 v[12:15], v[140:143], v[242:245], v[12:15]
	s_waitcnt vmcnt(4)
	s_barrier
	ds_read_b128 v[196:199], v246 offset:8192
	ds_read_b128 v[200:203], v246 offset:9216
	ds_read_b128 v[204:207], v246 offset:10240
	ds_read_b128 v[242:245], v246 offset:11264
	s_waitcnt vmcnt(0) lgkmcnt(3)
	v_mfma_f32_16x16x32_bf16 v[112:115], v[144:147], v[196:199], v[112:115]
	v_mfma_f32_16x16x32_bf16 v[120:123], v[148:151], v[196:199], v[120:123]
	v_mfma_f32_16x16x32_bf16 v[80:83], v[152:155], v[196:199], v[80:83]
	v_mfma_f32_16x16x32_bf16 v[88:91], v[156:159], v[196:199], v[88:91]
	ds_read_b128 v[196:199], v246 offset:12288
	s_waitcnt lgkmcnt(3)
	v_mfma_f32_16x16x32_bf16 v[116:119], v[144:147], v[200:203], v[116:119]
	v_mfma_f32_16x16x32_bf16 v[124:127], v[148:151], v[200:203], v[124:127]
	v_mfma_f32_16x16x32_bf16 v[84:87], v[152:155], v[200:203], v[84:87]
	v_mfma_f32_16x16x32_bf16 v[92:95], v[156:159], v[200:203], v[92:95]
	ds_read_b128 v[200:203], v246 offset:13312
	s_waitcnt lgkmcnt(3)
	v_mfma_f32_16x16x32_bf16 v[96:99], v[144:147], v[204:207], v[96:99]
	v_mfma_f32_16x16x32_bf16 v[104:107], v[148:151], v[204:207], v[104:107]
	v_mfma_f32_16x16x32_bf16 v[64:67], v[152:155], v[204:207], v[64:67]
	v_mfma_f32_16x16x32_bf16 v[72:75], v[156:159], v[204:207], v[72:75]
	ds_read_b128 v[204:207], v246 offset:14336
	s_waitcnt lgkmcnt(3)
	v_mfma_f32_16x16x32_bf16 v[100:103], v[144:147], v[242:245], v[100:103]
	v_mfma_f32_16x16x32_bf16 v[108:111], v[148:151], v[242:245], v[108:111]
	v_mfma_f32_16x16x32_bf16 v[68:71], v[152:155], v[242:245], v[68:71]
	v_mfma_f32_16x16x32_bf16 v[76:79], v[156:159], v[242:245], v[76:79]
	ds_read_b128 v[242:245], v246 offset:15360
	v_permlane16_swap_b32_e32 v112, v116
	v_permlane16_swap_b32_e32 v113, v117
	v_permlane16_swap_b32_e32 v114, v118
	v_permlane16_swap_b32_e32 v115, v119
	v_permlane16_swap_b32_e32 v120, v124
	v_permlane16_swap_b32_e32 v121, v125
	v_permlane16_swap_b32_e32 v122, v126
	v_permlane16_swap_b32_e32 v123, v127
	v_permlane16_swap_b32_e32 v80, v84
	v_permlane16_swap_b32_e32 v81, v85
	v_permlane16_swap_b32_e32 v82, v86
	v_permlane16_swap_b32_e32 v83, v87
	v_permlane16_swap_b32_e32 v88, v92
	v_permlane16_swap_b32_e32 v89, v93
	v_permlane16_swap_b32_e32 v90, v94
	v_permlane16_swap_b32_e32 v91, v95
	v_permlane32_swap_b32_e32 v112, v116
	v_permlane32_swap_b32_e32 v113, v117
	v_permlane32_swap_b32_e32 v114, v118
	v_permlane32_swap_b32_e32 v115, v119
	v_permlane32_swap_b32_e32 v120, v124
	v_permlane32_swap_b32_e32 v121, v125
	v_permlane32_swap_b32_e32 v122, v126
	v_permlane32_swap_b32_e32 v123, v127
	v_permlane32_swap_b32_e32 v80, v84
	v_permlane32_swap_b32_e32 v81, v85
	v_permlane32_swap_b32_e32 v82, v86
	v_permlane32_swap_b32_e32 v83, v87
	v_permlane32_swap_b32_e32 v88, v92
	v_permlane32_swap_b32_e32 v89, v93
	v_permlane32_swap_b32_e32 v90, v94
	v_permlane32_swap_b32_e32 v91, v95
	s_waitcnt lgkmcnt(3)
	v_mfma_f32_16x16x32_bf16 v[48:51], v[144:147], v[196:199], v[48:51]
	v_mfma_f32_16x16x32_bf16 v[56:59], v[148:151], v[196:199], v[56:59]
	v_mfma_f32_16x16x32_bf16 v[16:19], v[152:155], v[196:199], v[16:19]
	v_mfma_f32_16x16x32_bf16 v[24:27], v[156:159], v[196:199], v[24:27]
	s_waitcnt lgkmcnt(2)
	v_mfma_f32_16x16x32_bf16 v[52:55], v[144:147], v[200:203], v[52:55]
	v_mfma_f32_16x16x32_bf16 v[60:63], v[148:151], v[200:203], v[60:63]
	v_mfma_f32_16x16x32_bf16 v[20:23], v[152:155], v[200:203], v[20:23]
	v_mfma_f32_16x16x32_bf16 v[28:31], v[156:159], v[200:203], v[28:31]
	v_permlane16_swap_b32_e32 v96, v100
	v_permlane16_swap_b32_e32 v97, v101
	v_permlane16_swap_b32_e32 v98, v102
	v_permlane16_swap_b32_e32 v99, v103
	v_permlane16_swap_b32_e32 v104, v108
	v_permlane16_swap_b32_e32 v105, v109
	v_permlane16_swap_b32_e32 v106, v110
	v_permlane16_swap_b32_e32 v107, v111
	v_permlane16_swap_b32_e32 v64, v68
	v_permlane16_swap_b32_e32 v65, v69
	v_permlane16_swap_b32_e32 v66, v70
	v_permlane16_swap_b32_e32 v67, v71
	v_permlane16_swap_b32_e32 v72, v76
	v_permlane16_swap_b32_e32 v73, v77
	v_permlane16_swap_b32_e32 v74, v78
	v_permlane16_swap_b32_e32 v75, v79
	v_permlane32_swap_b32_e32 v96, v100
	v_permlane32_swap_b32_e32 v97, v101
	v_permlane32_swap_b32_e32 v98, v102
	v_permlane32_swap_b32_e32 v99, v103
	v_permlane32_swap_b32_e32 v104, v108
	v_permlane32_swap_b32_e32 v105, v109
	v_permlane32_swap_b32_e32 v106, v110
	v_permlane32_swap_b32_e32 v107, v111
	v_permlane32_swap_b32_e32 v64, v68
	v_permlane32_swap_b32_e32 v65, v69
	v_permlane32_swap_b32_e32 v66, v70
	v_permlane32_swap_b32_e32 v67, v71
	v_permlane32_swap_b32_e32 v72, v76
	v_permlane32_swap_b32_e32 v73, v77
	v_permlane32_swap_b32_e32 v74, v78
	v_permlane32_swap_b32_e32 v75, v79
	s_waitcnt lgkmcnt(1)
	v_mfma_f32_16x16x32_bf16 v[32:35], v[144:147], v[204:207], v[32:35]
	v_mfma_f32_16x16x32_bf16 v[40:43], v[148:151], v[204:207], v[40:43]
	v_mfma_f32_16x16x32_bf16 v[0:3], v[152:155], v[204:207], v[0:3]
	v_mfma_f32_16x16x32_bf16 v[8:11], v[156:159], v[204:207], v[8:11]
	s_waitcnt lgkmcnt(0)
	v_mfma_f32_16x16x32_bf16 v[36:39], v[144:147], v[242:245], v[36:39]
	v_mfma_f32_16x16x32_bf16 v[44:47], v[148:151], v[242:245], v[44:47]
	v_mfma_f32_16x16x32_bf16 v[4:7], v[152:155], v[242:245], v[4:7]
	v_mfma_f32_16x16x32_bf16 v[12:15], v[156:159], v[242:245], v[12:15]
	v_permlane16_swap_b32_e32 v48, v52
	v_permlane16_swap_b32_e32 v49, v53
	v_permlane16_swap_b32_e32 v50, v54
	v_permlane16_swap_b32_e32 v51, v55
	v_permlane16_swap_b32_e32 v56, v60
	v_permlane16_swap_b32_e32 v57, v61
	v_permlane16_swap_b32_e32 v58, v62
	v_permlane16_swap_b32_e32 v59, v63
	v_permlane16_swap_b32_e32 v16, v20
	v_permlane16_swap_b32_e32 v17, v21
	v_permlane16_swap_b32_e32 v18, v22
	v_permlane16_swap_b32_e32 v19, v23
	v_permlane16_swap_b32_e32 v24, v28
	v_permlane16_swap_b32_e32 v25, v29
	v_permlane16_swap_b32_e32 v26, v30
	v_permlane16_swap_b32_e32 v27, v31
	v_permlane32_swap_b32_e32 v48, v52
	v_permlane32_swap_b32_e32 v49, v53
	v_permlane32_swap_b32_e32 v50, v54
	v_permlane32_swap_b32_e32 v51, v55
	v_permlane32_swap_b32_e32 v56, v60
	v_permlane32_swap_b32_e32 v57, v61
	v_permlane32_swap_b32_e32 v58, v62
	v_permlane32_swap_b32_e32 v59, v63
	v_permlane32_swap_b32_e32 v16, v20
	v_permlane32_swap_b32_e32 v17, v21
	v_permlane32_swap_b32_e32 v18, v22
	v_permlane32_swap_b32_e32 v19, v23
	v_permlane32_swap_b32_e32 v24, v28
	v_permlane32_swap_b32_e32 v25, v29
	v_permlane32_swap_b32_e32 v26, v30
	v_permlane32_swap_b32_e32 v27, v31
	s_barrier
	s_setprio 0
	s_nop 7
	v_permlane16_swap_b32_e32 v32, v36
	v_permlane16_swap_b32_e32 v33, v37
	v_permlane16_swap_b32_e32 v34, v38
	v_permlane16_swap_b32_e32 v35, v39
	v_permlane16_swap_b32_e32 v40, v44
	v_permlane16_swap_b32_e32 v41, v45
	v_permlane16_swap_b32_e32 v42, v46
	v_permlane16_swap_b32_e32 v43, v47
	v_permlane16_swap_b32_e32 v0, v4
	v_permlane16_swap_b32_e32 v1, v5
	v_permlane16_swap_b32_e32 v2, v6
	v_permlane16_swap_b32_e32 v3, v7
	v_permlane16_swap_b32_e32 v8, v12
	v_permlane16_swap_b32_e32 v9, v13
	v_permlane16_swap_b32_e32 v10, v14
	v_permlane16_swap_b32_e32 v11, v15
	v_permlane32_swap_b32_e32 v32, v36
	v_permlane32_swap_b32_e32 v33, v37
	v_permlane32_swap_b32_e32 v34, v38
	v_permlane32_swap_b32_e32 v35, v39
	v_permlane32_swap_b32_e32 v40, v44
	v_permlane32_swap_b32_e32 v41, v45
	v_permlane32_swap_b32_e32 v42, v46
	v_permlane32_swap_b32_e32 v43, v47
	v_permlane32_swap_b32_e32 v0, v4
	v_permlane32_swap_b32_e32 v1, v5
	v_permlane32_swap_b32_e32 v2, v6
	v_permlane32_swap_b32_e32 v3, v7
	v_permlane32_swap_b32_e32 v8, v12
	v_permlane32_swap_b32_e32 v9, v13
	v_permlane32_swap_b32_e32 v10, v14
	v_permlane32_swap_b32_e32 v11, v15
	s_waitcnt vmcnt(0)
	s_waitcnt vmcnt(0)
	v_mul_f32_e32 v133, 0xbfb8aa3b, v112
	v_exp_f32_e32 v133, v133
	s_movk_i32 s1, 0x2400
	v_mul_lo_u32 v128, v238, s1
	v_lshl_or_b32 v131, s0, 6, v181
	v_add_f32_e32 v133, 1.0, v133
	v_lshl_or_b32 v132, v239, 1, v128
	v_and_b32_e32 v129, 0xffffffc0, v237
	v_lshl_or_b32 v128, v181, 1, v128
	v_rcp_f32_e32 v135, v133
	s_nop 0
	v_mul_f32_e32 v112, v112, v135
	v_mul_f32_e32 v96, v96, v112
	v_cvt_pk_bf16_f32 v112, v96, s0
	s_movk_i32 s0, 0x240
	v_mad_u32_u24 v96, v183, s0, v132
	ds_write_b16 v96, v112
	v_mul_f32_e32 v112, 0xbfb8aa3b, v113
	v_exp_f32_e32 v112, v112
	v_lshl_add_u32 v130, s7, 8, v129
	v_lshrrev_b32_e32 v129, 2, v240
	v_mad_u32_u24 v128, v129, s42, v128
	v_add_f32_e32 v112, 1.0, v112
	v_rcp_f32_e32 v133, v112
	s_nop 0
	v_mul_f32_e32 v112, v113, v133
	v_mul_f32_e32 v97, v97, v112
	v_cvt_pk_bf16_f32 v97, v97, s0
	ds_write_b16 v96, v97 offset:144
	v_mul_f32_e32 v97, 0xbfb8aa3b, v114
	v_exp_f32_e32 v97, v97
	s_nop 0
	v_add_f32_e32 v97, 1.0, v97
	v_rcp_f32_e32 v113, v97
	s_nop 0
	v_mul_f32_e32 v97, v114, v113
	v_mul_f32_e32 v97, v98, v97
	v_cvt_pk_bf16_f32 v97, v97, s0
	ds_write_b16 v96, v97 offset:288
	v_mul_f32_e32 v97, 0xbfb8aa3b, v115
	v_exp_f32_e32 v97, v97
	s_nop 0
	v_add_f32_e32 v97, 1.0, v97
	v_rcp_f32_e32 v112, v97
	s_nop 0
	v_mul_f32_e32 v97, v115, v112
	v_mul_f32_e32 v97, v99, v97
	v_cvt_pk_bf16_f32 v97, v97, s0
	ds_write_b16 v96, v97 offset:432
	v_mul_f32_e32 v97, 0xbfb8aa3b, v116
	v_exp_f32_e32 v97, v97
	s_nop 0
	v_add_f32_e32 v97, 1.0, v97
	v_rcp_f32_e32 v99, v97
	s_nop 0
	v_mul_f32_e32 v97, v116, v99
	v_mul_f32_e32 v97, v100, v97
	v_cvt_pk_bf16_f32 v97, v97, s0
	ds_write_b16 v96, v97 offset:1152
	v_mul_f32_e32 v97, 0xbfb8aa3b, v117
	v_exp_f32_e32 v97, v97
	s_nop 0
	v_add_f32_e32 v97, 1.0, v97
	v_rcp_f32_e32 v99, v97
	s_nop 0
	v_mul_f32_e32 v97, v117, v99
	v_mul_f32_e32 v97, v101, v97
	v_cvt_pk_bf16_f32 v97, v97, s0
	ds_write_b16 v96, v97 offset:1296
	v_mul_f32_e32 v97, 0xbfb8aa3b, v118
	v_exp_f32_e32 v97, v97
	s_nop 0
	v_add_f32_e32 v97, 1.0, v97
	v_rcp_f32_e32 v99, v97
	s_nop 0
	v_mul_f32_e32 v97, v118, v99
	v_mul_f32_e32 v97, v102, v97
	v_cvt_pk_bf16_f32 v97, v97, s0
	ds_write_b16 v96, v97 offset:1440
	v_mul_f32_e32 v97, 0xbfb8aa3b, v119
	v_exp_f32_e32 v97, v97
	s_nop 0
	v_add_f32_e32 v97, 1.0, v97
	v_rcp_f32_e32 v99, v97
	s_nop 0
	v_mul_f32_e32 v97, v119, v99
	v_mul_f32_e32 v97, v103, v97
	v_cvt_pk_bf16_f32 v97, v97, s0
	ds_write_b16 v96, v97 offset:1584
	v_mul_f32_e32 v97, 0xbfb8aa3b, v120
	v_exp_f32_e32 v97, v97
	s_nop 0
	v_add_f32_e32 v97, 1.0, v97
	v_rcp_f32_e32 v99, v97
	s_nop 0
	v_mul_f32_e32 v97, v120, v99
	v_mul_f32_e32 v97, v104, v97
	v_cvt_pk_bf16_f32 v97, v97, s0
	ds_write_b16 v96, v97 offset:2304
	v_mul_f32_e32 v97, 0xbfb8aa3b, v121
	v_exp_f32_e32 v97, v97
	s_nop 0
	v_add_f32_e32 v97, 1.0, v97
	v_rcp_f32_e32 v99, v97
	s_nop 0
	v_mul_f32_e32 v97, v121, v99
	v_mul_f32_e32 v97, v105, v97
	v_cvt_pk_bf16_f32 v97, v97, s0
	ds_write_b16 v96, v97 offset:2448
	v_mul_f32_e32 v97, 0xbfb8aa3b, v122
	v_exp_f32_e32 v97, v97
	s_nop 0
	v_add_f32_e32 v97, 1.0, v97
	v_rcp_f32_e32 v99, v97
	s_nop 0
	v_mul_f32_e32 v97, v122, v99
	v_mul_f32_e32 v97, v106, v97
	v_cvt_pk_bf16_f32 v97, v97, s0
	ds_write_b16 v96, v97 offset:2592
	v_mul_f32_e32 v97, 0xbfb8aa3b, v123
	v_exp_f32_e32 v97, v97
	s_nop 0
	v_add_f32_e32 v97, 1.0, v97
	v_rcp_f32_e32 v99, v97
	s_nop 0
	v_mul_f32_e32 v97, v123, v99
	v_mul_f32_e32 v97, v107, v97
	v_cvt_pk_bf16_f32 v97, v97, s0
	ds_write_b16 v96, v97 offset:2736
	v_mul_f32_e32 v97, 0xbfb8aa3b, v124
	v_exp_f32_e32 v97, v97
	s_nop 0
	v_add_f32_e32 v97, 1.0, v97
	v_rcp_f32_e32 v99, v97
	s_nop 0
	v_mul_f32_e32 v97, v124, v99
	v_mul_f32_e32 v97, v108, v97
	v_cvt_pk_bf16_f32 v97, v97, s0
	ds_write_b16 v96, v97 offset:3456
	v_mul_f32_e32 v97, 0xbfb8aa3b, v125
	v_exp_f32_e32 v97, v97
	s_nop 0
	v_add_f32_e32 v97, 1.0, v97
	v_rcp_f32_e32 v99, v97
	s_nop 0
	v_mul_f32_e32 v97, v125, v99
	v_mul_f32_e32 v97, v109, v97
	v_cvt_pk_bf16_f32 v97, v97, s0
	ds_write_b16 v96, v97 offset:3600
	v_mul_f32_e32 v97, 0xbfb8aa3b, v126
	v_exp_f32_e32 v97, v97
	s_nop 0
	v_add_f32_e32 v97, 1.0, v97
	v_rcp_f32_e32 v99, v97
	s_nop 0
	v_mul_f32_e32 v97, v126, v99
	v_mul_f32_e32 v97, v110, v97
	v_cvt_pk_bf16_f32 v97, v97, s0
	ds_write_b16 v96, v97 offset:3744
	v_mul_f32_e32 v97, 0xbfb8aa3b, v127
	v_exp_f32_e32 v97, v97
	s_nop 0
	v_add_f32_e32 v97, 1.0, v97
	v_rcp_f32_e32 v99, v97
	s_nop 0
	v_mul_f32_e32 v97, v127, v99
	v_mul_f32_e32 v97, v111, v97
	v_cvt_pk_bf16_f32 v97, v97, s0
	ds_write_b16 v96, v97 offset:3888
	v_mul_f32_e32 v97, 0xbfb8aa3b, v80
	v_exp_f32_e32 v97, v97
	s_nop 0
	v_add_f32_e32 v97, 1.0, v97
	v_rcp_f32_e32 v99, v97
	s_nop 0
	v_mul_f32_e32 v80, v80, v99
	v_mul_f32_e32 v64, v64, v80
	v_cvt_pk_bf16_f32 v64, v64, s0
	ds_write_b16 v96, v64 offset:4608
	v_mul_f32_e32 v64, 0xbfb8aa3b, v81
	v_exp_f32_e32 v64, v64
	s_nop 0
	v_add_f32_e32 v64, 1.0, v64
	v_rcp_f32_e32 v97, v64
	s_nop 0
	v_mul_f32_e32 v64, v81, v97
	v_mul_f32_e32 v64, v65, v64
	v_cvt_pk_bf16_f32 v64, v64, s0
	ds_write_b16 v96, v64 offset:4752
	v_mul_f32_e32 v64, 0xbfb8aa3b, v82
	v_exp_f32_e32 v64, v64
	s_nop 0
	v_add_f32_e32 v64, 1.0, v64
	v_rcp_f32_e32 v80, v64
	s_nop 0
	v_mul_f32_e32 v64, v82, v80
	v_mul_f32_e32 v64, v66, v64
	v_cvt_pk_bf16_f32 v64, v64, s0
	ds_write_b16 v96, v64 offset:4896
	v_mul_f32_e32 v64, 0xbfb8aa3b, v83
	v_exp_f32_e32 v64, v64
	s_nop 0
	v_add_f32_e32 v64, 1.0, v64
	v_rcp_f32_e32 v66, v64
	s_nop 0
	v_mul_f32_e32 v64, v83, v66
	v_mul_f32_e32 v64, v67, v64
	v_cvt_pk_bf16_f32 v64, v64, s0
	ds_write_b16 v96, v64 offset:5040
	v_mul_f32_e32 v64, 0xbfb8aa3b, v84
	v_exp_f32_e32 v64, v64
	s_nop 0
	v_add_f32_e32 v64, 1.0, v64
	v_rcp_f32_e32 v66, v64
	s_nop 0
	v_mul_f32_e32 v64, v84, v66
	v_mul_f32_e32 v64, v68, v64
	v_cvt_pk_bf16_f32 v64, v64, s0
	ds_write_b16 v96, v64 offset:5760
	v_mul_f32_e32 v64, 0xbfb8aa3b, v85
	v_exp_f32_e32 v64, v64
	s_nop 0
	v_add_f32_e32 v64, 1.0, v64
	v_rcp_f32_e32 v66, v64
	s_nop 0
	v_mul_f32_e32 v64, v85, v66
	v_mul_f32_e32 v64, v69, v64
	v_cvt_pk_bf16_f32 v64, v64, s0
	ds_write_b16 v96, v64 offset:5904
	v_mul_f32_e32 v64, 0xbfb8aa3b, v86
	v_exp_f32_e32 v64, v64
	s_nop 0
	v_add_f32_e32 v64, 1.0, v64
	v_rcp_f32_e32 v66, v64
	s_nop 0
	v_mul_f32_e32 v64, v86, v66
	v_mul_f32_e32 v64, v70, v64
	v_cvt_pk_bf16_f32 v64, v64, s0
	ds_write_b16 v96, v64 offset:6048
	v_mul_f32_e32 v64, 0xbfb8aa3b, v87
	v_exp_f32_e32 v64, v64
	s_nop 0
	v_add_f32_e32 v64, 1.0, v64
	v_rcp_f32_e32 v66, v64
	s_nop 0
	v_mul_f32_e32 v64, v87, v66
	v_mul_f32_e32 v64, v71, v64
	v_cvt_pk_bf16_f32 v64, v64, s0
	ds_write_b16 v96, v64 offset:6192
	v_mul_f32_e32 v64, 0xbfb8aa3b, v88
	v_exp_f32_e32 v64, v64
	v_ashrrev_i32_e32 v71, 5, v130
	v_or_b32_e32 v70, 1, v71
	v_add_f32_e32 v64, 1.0, v64
	v_rcp_f32_e32 v66, v64
	s_nop 0
	v_mul_f32_e32 v64, v88, v66
	v_mul_f32_e32 v64, v72, v64
	v_cvt_pk_bf16_f32 v64, v64, s0
	ds_write_b16 v96, v64 offset:6912
	v_mul_f32_e32 v64, 0xbfb8aa3b, v89
	v_exp_f32_e32 v64, v64
	s_nop 0
	v_add_f32_e32 v64, 1.0, v64
	v_rcp_f32_e32 v66, v64
	s_nop 0
	v_mul_f32_e32 v64, v89, v66
	v_mul_f32_e32 v64, v73, v64
	v_cvt_pk_bf16_f32 v64, v64, s0
	ds_write_b16 v96, v64 offset:7056
	v_mul_f32_e32 v64, 0xbfb8aa3b, v90
	v_exp_f32_e32 v64, v64
	s_nop 0
	v_add_f32_e32 v64, 1.0, v64
	v_rcp_f32_e32 v66, v64
	s_nop 0
	v_mul_f32_e32 v64, v90, v66
	v_mul_f32_e32 v64, v74, v64
	v_cvt_pk_bf16_f32 v64, v64, s0
	ds_write_b16 v96, v64 offset:7200
	v_mul_f32_e32 v64, 0xbfb8aa3b, v91
	v_exp_f32_e32 v64, v64
	s_nop 0
	v_add_f32_e32 v64, 1.0, v64
	v_rcp_f32_e32 v66, v64
	s_nop 0
	v_mul_f32_e32 v64, v91, v66
	v_mul_f32_e32 v64, v75, v64
	v_cvt_pk_bf16_f32 v64, v64, s0
	ds_write_b16 v96, v64 offset:7344
	v_mul_f32_e32 v64, 0xbfb8aa3b, v92
	v_exp_f32_e32 v64, v64
	s_nop 0
	v_add_f32_e32 v64, 1.0, v64
	v_rcp_f32_e32 v66, v64
	s_nop 0
	v_mul_f32_e32 v64, v92, v66
	v_mul_f32_e32 v64, v76, v64
	v_cvt_pk_bf16_f32 v64, v64, s0
	ds_write_b16 v96, v64 offset:8064
	v_mul_f32_e32 v64, 0xbfb8aa3b, v93
	v_exp_f32_e32 v64, v64
	s_nop 0
	v_add_f32_e32 v64, 1.0, v64
	v_rcp_f32_e32 v66, v64
	s_nop 0
	v_mul_f32_e32 v64, v93, v66
	v_mul_f32_e32 v64, v77, v64
	v_cvt_pk_bf16_f32 v64, v64, s0
	ds_write_b16 v96, v64 offset:8208
	v_mul_f32_e32 v64, 0xbfb8aa3b, v94
	v_exp_f32_e32 v64, v64
	s_nop 0
	v_add_f32_e32 v64, 1.0, v64
	v_rcp_f32_e32 v66, v64
	s_nop 0
	v_mul_f32_e32 v64, v94, v66
	v_mul_f32_e32 v64, v78, v64
	v_cvt_pk_bf16_f32 v64, v64, s0
	ds_write_b16 v96, v64 offset:8352
	v_mul_f32_e32 v64, 0xbfb8aa3b, v95
	v_exp_f32_e32 v64, v64
	s_nop 0
	v_add_f32_e32 v64, 1.0, v64
	v_rcp_f32_e32 v66, v64
	s_nop 0
	v_mul_f32_e32 v64, v95, v66
	v_mul_f32_e32 v64, v79, v64
	v_cvt_pk_bf16_f32 v64, v64, s0
	ds_write_b16 v96, v64 offset:8496
	v_ashrrev_i32_e32 v68, 4, v131
	s_waitcnt lgkmcnt(0)
	v_ashrrev_i32_e32 v69, 31, v68
	ds_read_b128 v[72:75], v128
	v_mad_i64_i32 v[64:65], s[0:1], v71, s23, v[68:69]
	v_lshlrev_b64 v[64:65], 10, v[64:65]
	v_lshlrev_b32_e32 v66, 6, v181
	v_lshl_add_u64 v[64:65], s[66:67], 0, v[64:65]
	v_and_b32_e32 v176, 0x200, v66
	v_lshl_add_u64 v[76:77], v[64:65], 0, v[176:177]
	v_lshlrev_b32_e32 v66, 4, v129
	v_mov_b32_e32 v67, v177
	v_lshl_add_u64 v[64:65], v[76:77], 0, v[66:67]
	s_waitcnt lgkmcnt(0)
	global_store_dwordx4 v[64:65], v[72:75], off
	ds_read_b128 v[72:75], v128 offset:2304
	v_or_b32_e32 v64, 0x100, v66
	v_mov_b32_e32 v65, v177
	v_lshl_add_u64 v[76:77], v[76:77], 0, v[64:65]
	s_waitcnt lgkmcnt(0)
	global_store_dwordx4 v[76:77], v[72:75], off
	ds_read_b128 v[72:75], v128 offset:4608
	v_mad_i64_i32 v[76:77], s[0:1], v70, s23, v[68:69]
	v_lshlrev_b64 v[76:77], 10, v[76:77]
	v_lshl_add_u64 v[76:77], s[66:67], 0, v[76:77]
	v_lshl_add_u64 v[76:77], v[76:77], 0, v[176:177]
	v_lshl_add_u64 v[78:79], v[76:77], 0, v[66:67]
	v_mul_f32_e32 v69, 0xbfb8aa3b, v48
	s_waitcnt lgkmcnt(0)
	global_store_dwordx4 v[78:79], v[72:75], off
	ds_read_b128 v[72:75], v128 offset:6912
	v_exp_f32_e32 v69, v69
	v_lshl_add_u64 v[76:77], v[76:77], 0, v[64:65]
	v_add_f32_e32 v69, 1.0, v69
	s_waitcnt lgkmcnt(0)
	global_store_dwordx4 v[76:77], v[72:75], off
	s_waitcnt lgkmcnt(0)
	s_nop 1
	v_rcp_f32_e32 v73, v69
	s_nop 0
	v_mul_f32_e32 v48, v48, v73
	v_mul_f32_e32 v32, v32, v48
	v_cvt_pk_bf16_f32 v32, v32, s0
	ds_write_b16 v96, v32
	v_mul_f32_e32 v32, 0xbfb8aa3b, v49
	v_exp_f32_e32 v32, v32
	s_nop 0
	v_add_f32_e32 v32, 1.0, v32
	v_rcp_f32_e32 v69, v32
	s_nop 0
	v_mul_f32_e32 v32, v49, v69
	v_mul_f32_e32 v32, v33, v32
	v_cvt_pk_bf16_f32 v32, v32, s0
	ds_write_b16 v96, v32 offset:144
	v_mul_f32_e32 v32, 0xbfb8aa3b, v50
	v_exp_f32_e32 v32, v32
	s_nop 0
	v_add_f32_e32 v32, 1.0, v32
	v_rcp_f32_e32 v48, v32
	s_nop 0
	v_mul_f32_e32 v32, v50, v48
	v_mul_f32_e32 v32, v34, v32
	v_cvt_pk_bf16_f32 v32, v32, s0
	ds_write_b16 v96, v32 offset:288
	v_mul_f32_e32 v32, 0xbfb8aa3b, v51
	v_exp_f32_e32 v32, v32
	s_nop 0
	v_add_f32_e32 v32, 1.0, v32
	v_rcp_f32_e32 v34, v32
	s_nop 0
	v_mul_f32_e32 v32, v51, v34
	v_mul_f32_e32 v32, v35, v32
	v_cvt_pk_bf16_f32 v32, v32, s0
	ds_write_b16 v96, v32 offset:432
	v_mul_f32_e32 v32, 0xbfb8aa3b, v52
	v_exp_f32_e32 v32, v32
	s_nop 0
	v_add_f32_e32 v32, 1.0, v32
	v_rcp_f32_e32 v34, v32
	s_nop 0
	v_mul_f32_e32 v32, v52, v34
	v_mul_f32_e32 v32, v36, v32
	v_cvt_pk_bf16_f32 v32, v32, s0
	ds_write_b16 v96, v32 offset:1152
	v_mul_f32_e32 v32, 0xbfb8aa3b, v53
	v_exp_f32_e32 v32, v32
	s_nop 0
	v_add_f32_e32 v32, 1.0, v32
	v_rcp_f32_e32 v34, v32
	s_nop 0
	v_mul_f32_e32 v32, v53, v34
	v_mul_f32_e32 v32, v37, v32
	v_cvt_pk_bf16_f32 v32, v32, s0
	ds_write_b16 v96, v32 offset:1296
	v_mul_f32_e32 v32, 0xbfb8aa3b, v54
	v_exp_f32_e32 v32, v32
	s_nop 0
	v_add_f32_e32 v32, 1.0, v32
	v_rcp_f32_e32 v34, v32
	s_nop 0
	v_mul_f32_e32 v32, v54, v34
	v_mul_f32_e32 v32, v38, v32
	v_cvt_pk_bf16_f32 v32, v32, s0
	ds_write_b16 v96, v32 offset:1440
	v_mul_f32_e32 v32, 0xbfb8aa3b, v55
	v_exp_f32_e32 v32, v32
	s_nop 0
	v_add_f32_e32 v32, 1.0, v32
	v_rcp_f32_e32 v34, v32
	s_nop 0
	v_mul_f32_e32 v32, v55, v34
	v_mul_f32_e32 v32, v39, v32
	v_cvt_pk_bf16_f32 v32, v32, s0
	ds_write_b16 v96, v32 offset:1584
	v_mul_f32_e32 v32, 0xbfb8aa3b, v56
	v_exp_f32_e32 v32, v32
	s_nop 0
	v_add_f32_e32 v32, 1.0, v32
	v_rcp_f32_e32 v34, v32
	s_nop 0
	v_mul_f32_e32 v32, v56, v34
	v_mul_f32_e32 v32, v40, v32
	v_cvt_pk_bf16_f32 v32, v32, s0
	ds_write_b16 v96, v32 offset:2304
	v_mul_f32_e32 v32, 0xbfb8aa3b, v57
	v_exp_f32_e32 v32, v32
	s_nop 0
	v_add_f32_e32 v32, 1.0, v32
	v_rcp_f32_e32 v34, v32
	s_nop 0
	v_mul_f32_e32 v32, v57, v34
	v_mul_f32_e32 v32, v41, v32
	v_cvt_pk_bf16_f32 v32, v32, s0
	ds_write_b16 v96, v32 offset:2448
	v_mul_f32_e32 v32, 0xbfb8aa3b, v58
	v_exp_f32_e32 v32, v32
	s_nop 0
	v_add_f32_e32 v32, 1.0, v32
	v_rcp_f32_e32 v34, v32
	s_nop 0
	v_mul_f32_e32 v32, v58, v34
	v_mul_f32_e32 v32, v42, v32
	v_cvt_pk_bf16_f32 v32, v32, s0
	ds_write_b16 v96, v32 offset:2592
	v_mul_f32_e32 v32, 0xbfb8aa3b, v59
	v_exp_f32_e32 v32, v32
	s_nop 0
	v_add_f32_e32 v32, 1.0, v32
	v_rcp_f32_e32 v34, v32
	s_nop 0
	v_mul_f32_e32 v32, v59, v34
	v_mul_f32_e32 v32, v43, v32
	v_cvt_pk_bf16_f32 v32, v32, s0
	ds_write_b16 v96, v32 offset:2736
	v_mul_f32_e32 v32, 0xbfb8aa3b, v60
	v_exp_f32_e32 v32, v32
	s_nop 0
	v_add_f32_e32 v32, 1.0, v32
	v_rcp_f32_e32 v34, v32
	s_nop 0
	v_mul_f32_e32 v32, v60, v34
	v_mul_f32_e32 v32, v44, v32
	v_cvt_pk_bf16_f32 v32, v32, s0
	ds_write_b16 v96, v32 offset:3456
	v_mul_f32_e32 v32, 0xbfb8aa3b, v61
	v_exp_f32_e32 v32, v32
	s_nop 0
	v_add_f32_e32 v32, 1.0, v32
	v_rcp_f32_e32 v34, v32
	s_nop 0
	v_mul_f32_e32 v32, v61, v34
	v_mul_f32_e32 v32, v45, v32
	v_cvt_pk_bf16_f32 v32, v32, s0
	ds_write_b16 v96, v32 offset:3600
	v_mul_f32_e32 v32, 0xbfb8aa3b, v62
	v_exp_f32_e32 v32, v32
	s_nop 0
	v_add_f32_e32 v32, 1.0, v32
	v_rcp_f32_e32 v34, v32
	s_nop 0
	v_mul_f32_e32 v32, v62, v34
	v_mul_f32_e32 v32, v46, v32
	v_cvt_pk_bf16_f32 v32, v32, s0
	ds_write_b16 v96, v32 offset:3744
	v_mul_f32_e32 v32, 0xbfb8aa3b, v63
	v_exp_f32_e32 v32, v32
	s_nop 0
	v_add_f32_e32 v32, 1.0, v32
	v_rcp_f32_e32 v34, v32
	s_nop 0
	v_mul_f32_e32 v32, v63, v34
	v_mul_f32_e32 v32, v47, v32
	v_cvt_pk_bf16_f32 v32, v32, s0
	ds_write_b16 v96, v32 offset:3888
	v_mul_f32_e32 v32, 0xbfb8aa3b, v16
	v_exp_f32_e32 v32, v32
	s_nop 0
	v_add_f32_e32 v32, 1.0, v32
	v_rcp_f32_e32 v34, v32
	s_nop 0
	v_mul_f32_e32 v16, v16, v34
	v_mul_f32_e32 v0, v0, v16
	v_cvt_pk_bf16_f32 v0, v0, s0
	ds_write_b16 v96, v0 offset:4608
	v_mul_f32_e32 v0, 0xbfb8aa3b, v17
	v_exp_f32_e32 v0, v0
	s_nop 0
	v_add_f32_e32 v0, 1.0, v0
	v_rcp_f32_e32 v32, v0
	s_nop 0
	v_mul_f32_e32 v0, v17, v32
	v_mul_f32_e32 v0, v1, v0
	v_cvt_pk_bf16_f32 v0, v0, s0
	ds_write_b16 v96, v0 offset:4752
	v_mul_f32_e32 v0, 0xbfb8aa3b, v18
	v_exp_f32_e32 v0, v0
	s_nop 0
	v_add_f32_e32 v0, 1.0, v0
	v_rcp_f32_e32 v16, v0
	s_nop 0
	v_mul_f32_e32 v0, v18, v16
	v_mul_f32_e32 v0, v2, v0
	v_cvt_pk_bf16_f32 v0, v0, s0
	ds_write_b16 v96, v0 offset:4896
	v_mul_f32_e32 v0, 0xbfb8aa3b, v19
	v_exp_f32_e32 v0, v0
	s_nop 0
	v_add_f32_e32 v0, 1.0, v0
	v_rcp_f32_e32 v2, v0
	s_nop 0
	v_mul_f32_e32 v0, v19, v2
	v_mul_f32_e32 v0, v3, v0
	v_cvt_pk_bf16_f32 v0, v0, s0
	ds_write_b16 v96, v0 offset:5040
	v_mul_f32_e32 v0, 0xbfb8aa3b, v20
	v_exp_f32_e32 v0, v0
	s_nop 0
	v_add_f32_e32 v0, 1.0, v0
	v_rcp_f32_e32 v2, v0
	s_nop 0
	v_mul_f32_e32 v0, v20, v2
	v_mul_f32_e32 v0, v4, v0
	v_cvt_pk_bf16_f32 v0, v0, s0
	ds_write_b16 v96, v0 offset:5760
	v_mul_f32_e32 v0, 0xbfb8aa3b, v21
	v_exp_f32_e32 v0, v0
	s_nop 0
	v_add_f32_e32 v0, 1.0, v0
	v_rcp_f32_e32 v2, v0
	s_nop 0
	v_mul_f32_e32 v0, v21, v2
	v_mul_f32_e32 v0, v5, v0
	v_cvt_pk_bf16_f32 v0, v0, s0
	ds_write_b16 v96, v0 offset:5904
	v_mul_f32_e32 v0, 0xbfb8aa3b, v22
	v_exp_f32_e32 v0, v0
	s_nop 0
	v_add_f32_e32 v0, 1.0, v0
	v_rcp_f32_e32 v2, v0
	s_nop 0
	v_mul_f32_e32 v0, v22, v2
	v_mul_f32_e32 v0, v6, v0
	v_cvt_pk_bf16_f32 v0, v0, s0
	ds_write_b16 v96, v0 offset:6048
	v_mul_f32_e32 v0, 0xbfb8aa3b, v23
	v_exp_f32_e32 v0, v0
	s_nop 0
	v_add_f32_e32 v0, 1.0, v0
	v_rcp_f32_e32 v2, v0
	s_nop 0
	v_mul_f32_e32 v0, v23, v2
	v_mul_f32_e32 v0, v7, v0
	v_cvt_pk_bf16_f32 v0, v0, s0
	ds_write_b16 v96, v0 offset:6192
	v_mul_f32_e32 v0, 0xbfb8aa3b, v24
	v_exp_f32_e32 v0, v0
	s_nop 0
	v_add_f32_e32 v0, 1.0, v0
	v_rcp_f32_e32 v2, v0
	s_nop 0
	v_mul_f32_e32 v0, v24, v2
	v_mul_f32_e32 v0, v8, v0
	v_cvt_pk_bf16_f32 v0, v0, s0
	ds_write_b16 v96, v0 offset:6912
	v_mul_f32_e32 v0, 0xbfb8aa3b, v25
	v_exp_f32_e32 v0, v0
	s_nop 0
	v_add_f32_e32 v0, 1.0, v0
	v_rcp_f32_e32 v2, v0
	s_nop 0
	v_mul_f32_e32 v0, v25, v2
	v_mul_f32_e32 v0, v9, v0
	v_cvt_pk_bf16_f32 v0, v0, s0
	ds_write_b16 v96, v0 offset:7056
	v_mul_f32_e32 v0, 0xbfb8aa3b, v26
	v_exp_f32_e32 v0, v0
	s_nop 0
	v_add_f32_e32 v0, 1.0, v0
	v_rcp_f32_e32 v2, v0
	s_nop 0
	v_mul_f32_e32 v0, v26, v2
	v_mul_f32_e32 v0, v10, v0
	v_cvt_pk_bf16_f32 v0, v0, s0
	ds_write_b16 v96, v0 offset:7200
	v_mul_f32_e32 v0, 0xbfb8aa3b, v27
	v_exp_f32_e32 v0, v0
	s_nop 0
	v_add_f32_e32 v0, 1.0, v0
	v_rcp_f32_e32 v2, v0
	s_nop 0
	v_mul_f32_e32 v0, v27, v2
	v_mul_f32_e32 v0, v11, v0
	v_cvt_pk_bf16_f32 v0, v0, s0
	ds_write_b16 v96, v0 offset:7344
	v_mul_f32_e32 v0, 0xbfb8aa3b, v28
	v_exp_f32_e32 v0, v0
	s_nop 0
	v_add_f32_e32 v0, 1.0, v0
	v_rcp_f32_e32 v2, v0
	s_nop 0
	v_mul_f32_e32 v0, v28, v2
	v_mul_f32_e32 v0, v12, v0
	v_cvt_pk_bf16_f32 v0, v0, s0
	ds_write_b16 v96, v0 offset:8064
	v_mul_f32_e32 v0, 0xbfb8aa3b, v29
	v_exp_f32_e32 v0, v0
	s_nop 0
	v_add_f32_e32 v0, 1.0, v0
	v_rcp_f32_e32 v2, v0
	s_nop 0
	v_mul_f32_e32 v0, v29, v2
	v_mul_f32_e32 v0, v13, v0
	v_cvt_pk_bf16_f32 v0, v0, s0
	ds_write_b16 v96, v0 offset:8208
	v_mul_f32_e32 v0, 0xbfb8aa3b, v30
	v_exp_f32_e32 v0, v0
	s_nop 0
	v_add_f32_e32 v0, 1.0, v0
	v_rcp_f32_e32 v2, v0
	s_nop 0
	v_mul_f32_e32 v0, v30, v2
	v_mul_f32_e32 v0, v14, v0
	v_cvt_pk_bf16_f32 v0, v0, s0
	ds_write_b16 v96, v0 offset:8352
	v_mul_f32_e32 v0, 0xbfb8aa3b, v31
	v_exp_f32_e32 v0, v0
	s_nop 0
	v_add_f32_e32 v0, 1.0, v0
	v_rcp_f32_e32 v2, v0
	s_nop 0
	v_mul_f32_e32 v0, v31, v2
	v_mul_f32_e32 v0, v15, v0
	v_cvt_pk_bf16_f32 v0, v0, s0
	ds_write_b16 v96, v0 offset:8496
	v_or_b32_e32 v4, 2, v68
	s_waitcnt lgkmcnt(0)
	v_ashrrev_i32_e32 v5, 31, v4
	ds_read_b128 v[0:3], v128
	v_mad_i64_i32 v[6:7], s[0:1], v71, s23, v[4:5]
	v_lshlrev_b64 v[6:7], 10, v[6:7]
	v_lshl_add_u64 v[6:7], s[66:67], 0, v[6:7]
	v_lshl_add_u64 v[6:7], v[6:7], 0, v[176:177]
	v_lshl_add_u64 v[8:9], v[6:7], 0, v[66:67]
	s_waitcnt lgkmcnt(0)
	global_store_dwordx4 v[8:9], v[0:3], off
	ds_read_b128 v[0:3], v128 offset:2304
	v_lshl_add_u64 v[6:7], v[6:7], 0, v[64:65]
	v_mad_i64_i32 v[4:5], s[0:1], v70, s23, v[4:5]
	v_lshlrev_b64 v[4:5], 10, v[4:5]
	s_waitcnt lgkmcnt(0)
	global_store_dwordx4 v[6:7], v[0:3], off
	ds_read_b128 v[0:3], v128 offset:4608
	v_lshl_add_u64 v[4:5], s[66:67], 0, v[4:5]
	v_lshl_add_u64 v[4:5], v[4:5], 0, v[176:177]
	v_lshl_add_u64 v[6:7], v[4:5], 0, v[66:67]
	v_lshl_add_u64 v[4:5], v[4:5], 0, v[64:65]
	s_waitcnt lgkmcnt(0)
	global_store_dwordx4 v[6:7], v[0:3], off
	ds_read_b128 v[0:3], v128 offset:6912
	v_readlane_b32 s0, v254, 11
	s_add_i32 s2, s2, s0
	s_cmp_lt_i32 s2, s3
	s_waitcnt lgkmcnt(0)
	global_store_dwordx4 v[4:5], v[0:3], off
	s_waitcnt lgkmcnt(0)
	s_barrier
	s_cbranch_scc1 .LBB0_1031

.LBB0_1086:
	s_ashr_i32 s6, s2, 31
	s_lshr_b32 s6, s6, 26
	s_add_i32 s6, s2, s6
	s_ashr_i32 s7, s6, 6
	s_lshl_b32 s7, s7, 3
	s_sub_i32 s8, s25, s7
	s_min_i32 s8, s8, 8
	s_abs_i32 s9, s8
	v_cvt_f32_u32_e32 v0, s9
	s_sub_i32 s12, 0, s9
	s_andn2_b32 s6, s6, 63
	s_sub_i32 s10, s2, s6
	v_rcp_iflag_f32_e32 v0, v0
	s_abs_i32 s6, s10
	s_xor_b32 s11, s10, s8
	s_ashr_i32 s11, s11, 31
	v_mul_f32_e32 v0, 0x4f7ffffe, v0
	v_cvt_u32_f32_e32 v0, v0
	v_mov_b32_e32 v181, v179
	v_readfirstlane_b32 s13, v0
	s_mul_i32 s12, s12, s13
	s_mul_hi_u32 s12, s13, s12
	s_add_i32 s13, s13, s12
	s_mul_hi_u32 s12, s6, s13
	s_mul_i32 s13, s12, s9
	s_sub_i32 s6, s6, s13
	s_add_i32 s14, s12, 1
	s_sub_i32 s13, s6, s9
	s_cmp_ge_u32 s6, s9
	s_cselect_b32 s12, s14, s12
	s_cselect_b32 s6, s13, s6
	s_add_i32 s13, s12, 1
	s_cmp_ge_u32 s6, s9
	s_cselect_b32 s6, s13, s12
	s_xor_b32 s6, s6, s11
	s_sub_i32 s6, s6, s11
	s_mul_i32 s8, s8, s6
	s_add_i32 s7, s7, s5
	s_sub_i32 s8, s10, s8
	v_ashrrev_i32_e32 v237, 6, v181
	s_add_i32 s7, s7, s8
	v_lshlrev_b32_e32 v0, 1, v237
	v_bfe_u32 v183, v181, 5, 1
	v_lshl_add_u32 v2, s7, 3, v0
	v_mov_b64_e32 v[0:1], s[66:67]
	v_and_b32_e32 v238, 31, v181
	v_mad_i64_i32 v[0:1], s[8:9], v2, s24, v[0:1]
	v_lshlrev_b32_e32 v176, 9, v183
	v_lshl_add_u64 v[0:1], v[0:1], 0, v[176:177]
	v_lshlrev_b32_e32 v176, 4, v238
	v_ashrrev_i32_e32 v38, 2, v181
	s_mul_i32 s8, s6, 0xb0000
	v_lshl_add_u64 v[184:185], v[0:1], 0, v[176:177]
	s_mul_hi_i32 s9, s6, 0xb0000
	s_add_u32 s8, s3, s8
	v_lshlrev_b32_e32 v0, 5, v38
	s_addc_u32 s9, s4, s9
	v_ashrrev_i32_e32 v1, 31, v0
	v_lshlrev_b32_e32 v2, 4, v181
	v_lshl_add_u64 v[0:1], v[0:1], 1, s[8:9]
	v_and_b32_e32 v176, 48, v2
	v_lshl_add_u64 v[186:187], v[0:1], 0, v[176:177]
	s_movk_i32 s8, 0x2000
	v_add_co_u32_e32 v34, vcc, s8, v186
	v_mul_u32_u24_e32 v36, 40, v238
	s_nop 0
	v_addc_co_u32_e32 v35, vcc, 0, v187, vcc
	v_lshlrev_b32_e32 v37, 4, v183
	v_lshl_add_u32 v240, v36, 1, v37
	v_add_co_u32_e32 v36, vcc, s24, v184
	s_movk_i32 s9, 0x50
	s_nop 0
	v_addc_co_u32_e32 v37, vcc, 0, v185, vcc
	v_and_b32_e32 v239, 63, v181
	v_bfe_u32 v247, v181, 4, 2
	v_lshlrev_b32_e32 v247, 1, v247
	v_mov_b32_e32 v176, 0x78
	v_lshrrev_b32_e32 v247, v247, v176
	v_and_b32_e32 v247, 3, v247
	v_and_b32_e32 v246, 3, v181
	v_xor_b32_e32 v247, v247, v246
	v_lshlrev_b32_e32 v247, 4, v247
	v_and_b32_e32 v188, 0xffffffcf, v186
	v_or_b32_e32 v188, v188, v247
	v_mov_b32_e32 v189, v187
	v_lshrrev_b32_e32 v176, 6, v181
	v_lshlrev_b32_e32 v247, 11, v176
	v_lshlrev_b32_e32 v176, 10, v176
	v_lshl_add_u64 v[188:189], v[188:189], 0, v[176:177]
	v_readfirstlane_b32 vcc_lo, v247
	v_bfe_u32 v247, v181, 4, 1
	v_lshlrev_b32_e32 v176, 9, v183
	v_lshl_add_u32 v176, v247, 8, v176
	v_lshl_add_u64 v[184:185], v[184:185], 0, v[176:177]
	v_mov_b32_e32 v176, s24
	v_lshl_add_u64 v[186:187], v[184:185], 0, v[176:177]
	v_mov_b32_e32 v176, 0x78
	v_bfe_u32 v247, v181, 2, 2
	v_lshlrev_b32_e32 v247, 1, v247
	v_lshrrev_b32_e32 v247, v247, v176
	v_and_b32_e32 v247, 3, v247
	v_bfe_u32 v246, v181, 4, 2
	v_xor_b32_e32 v247, v247, v246
	v_lshlrev_b32_e32 v247, 4, v247
	v_and_b32_e32 v246, 15, v181
	v_lshl_add_u32 v246, v246, 6, v247
	s_mov_b32 s96, 0
	s_mov_b32 m0, vcc_lo
	v_lshl_add_u64 v[160:161], v[188:189], 0, s[96:97]
	global_load_lds_dwordx4 v[160:161], off
	global_load_lds_dwordx4 v[160:161], off offset:1024
	s_mov_b32 s96, 0
	v_lshl_add_u64 v[248:249], v[184:185], 0, s[96:97]
	v_lshl_add_u64 v[250:251], v[186:187], 0, s[96:97]
	global_load_dwordx4 v[128:131], v[248:249], off
	global_load_dwordx4 v[132:135], v[248:249], off offset:256
	global_load_dwordx4 v[136:139], v[250:251], off
	global_load_dwordx4 v[140:143], v[250:251], off offset:256
	s_movk_i32 s96, 0x2000
	s_add_i32 m0, vcc_lo, 8192
	v_lshl_add_u64 v[160:161], v[188:189], 0, s[96:97]
	global_load_lds_dwordx4 v[160:161], off
	global_load_lds_dwordx4 v[160:161], off offset:1024
	s_movk_i32 s96, 0x800
	v_lshl_add_u64 v[248:249], v[184:185], 0, s[96:97]
	v_lshl_add_u64 v[250:251], v[186:187], 0, s[96:97]
	global_load_dwordx4 v[144:147], v[248:249], off
	global_load_dwordx4 v[148:151], v[248:249], off offset:256
	global_load_dwordx4 v[152:155], v[250:251], off
	global_load_dwordx4 v[156:159], v[250:251], off offset:256
	v_mov_b32_e32 v0, 0
	v_mov_b32_e32 v1, 0
	v_mov_b32_e32 v2, 0
	v_mov_b32_e32 v3, 0
	v_mov_b32_e32 v4, 0
	v_mov_b32_e32 v5, 0
	v_mov_b32_e32 v6, 0
	v_mov_b32_e32 v7, 0
	v_mov_b32_e32 v8, 0
	v_mov_b32_e32 v9, 0
	v_mov_b32_e32 v10, 0
	v_mov_b32_e32 v11, 0
	v_mov_b32_e32 v12, 0
	v_mov_b32_e32 v13, 0
	v_mov_b32_e32 v14, 0
	v_mov_b32_e32 v15, 0
	v_mov_b32_e32 v16, 0
	v_mov_b32_e32 v17, 0
	v_mov_b32_e32 v18, 0
	v_mov_b32_e32 v19, 0
	v_mov_b32_e32 v20, 0
	v_mov_b32_e32 v21, 0
	v_mov_b32_e32 v22, 0
	v_mov_b32_e32 v23, 0
	v_mov_b32_e32 v24, 0
	v_mov_b32_e32 v25, 0
	v_mov_b32_e32 v26, 0
	v_mov_b32_e32 v27, 0
	v_mov_b32_e32 v28, 0
	v_mov_b32_e32 v29, 0
	v_mov_b32_e32 v30, 0
	v_mov_b32_e32 v31, 0
	v_mov_b32_e32 v32, 0
	v_mov_b32_e32 v33, 0
	v_mov_b32_e32 v34, 0
	v_mov_b32_e32 v35, 0
	v_mov_b32_e32 v36, 0
	v_mov_b32_e32 v37, 0
	v_mov_b32_e32 v38, 0
	v_mov_b32_e32 v39, 0
	v_mov_b32_e32 v40, 0
	v_mov_b32_e32 v41, 0
	v_mov_b32_e32 v42, 0
	v_mov_b32_e32 v43, 0
	v_mov_b32_e32 v44, 0
	v_mov_b32_e32 v45, 0
	v_mov_b32_e32 v46, 0
	v_mov_b32_e32 v47, 0
	v_mov_b32_e32 v48, 0
	v_mov_b32_e32 v49, 0
	v_mov_b32_e32 v50, 0
	v_mov_b32_e32 v51, 0
	v_mov_b32_e32 v52, 0
	v_mov_b32_e32 v53, 0
	v_mov_b32_e32 v54, 0
	v_mov_b32_e32 v55, 0
	v_mov_b32_e32 v56, 0
	v_mov_b32_e32 v57, 0
	v_mov_b32_e32 v58, 0
	v_mov_b32_e32 v59, 0
	v_mov_b32_e32 v60, 0
	v_mov_b32_e32 v61, 0
	v_mov_b32_e32 v62, 0
	v_mov_b32_e32 v63, 0
	v_mov_b32_e32 v64, 0
	v_mov_b32_e32 v65, 0
	v_mov_b32_e32 v66, 0
	v_mov_b32_e32 v67, 0
	v_mov_b32_e32 v68, 0
	v_mov_b32_e32 v69, 0
	v_mov_b32_e32 v70, 0
	v_mov_b32_e32 v71, 0
	v_mov_b32_e32 v72, 0
	v_mov_b32_e32 v73, 0
	v_mov_b32_e32 v74, 0
	v_mov_b32_e32 v75, 0
	v_mov_b32_e32 v76, 0
	v_mov_b32_e32 v77, 0
	v_mov_b32_e32 v78, 0
	v_mov_b32_e32 v79, 0
	v_mov_b32_e32 v80, 0
	v_mov_b32_e32 v81, 0
	v_mov_b32_e32 v82, 0
	v_mov_b32_e32 v83, 0
	v_mov_b32_e32 v84, 0
	v_mov_b32_e32 v85, 0
	v_mov_b32_e32 v86, 0
	v_mov_b32_e32 v87, 0
	v_mov_b32_e32 v88, 0
	v_mov_b32_e32 v89, 0
	v_mov_b32_e32 v90, 0
	v_mov_b32_e32 v91, 0
	v_mov_b32_e32 v92, 0
	v_mov_b32_e32 v93, 0
	v_mov_b32_e32 v94, 0
	v_mov_b32_e32 v95, 0
	v_mov_b32_e32 v96, 0
	v_mov_b32_e32 v97, 0
	v_mov_b32_e32 v98, 0
	v_mov_b32_e32 v99, 0
	v_mov_b32_e32 v100, 0
	v_mov_b32_e32 v101, 0
	v_mov_b32_e32 v102, 0
	v_mov_b32_e32 v103, 0
	v_mov_b32_e32 v104, 0
	v_mov_b32_e32 v105, 0
	v_mov_b32_e32 v106, 0
	v_mov_b32_e32 v107, 0
	v_mov_b32_e32 v108, 0
	v_mov_b32_e32 v109, 0
	v_mov_b32_e32 v110, 0
	v_mov_b32_e32 v111, 0
	v_mov_b32_e32 v112, 0
	v_mov_b32_e32 v113, 0
	v_mov_b32_e32 v114, 0
	v_mov_b32_e32 v115, 0
	v_mov_b32_e32 v116, 0
	v_mov_b32_e32 v117, 0
	v_mov_b32_e32 v118, 0
	v_mov_b32_e32 v119, 0
	v_mov_b32_e32 v120, 0
	v_mov_b32_e32 v121, 0
	v_mov_b32_e32 v122, 0
	v_mov_b32_e32 v123, 0
	v_mov_b32_e32 v124, 0
	v_mov_b32_e32 v125, 0
	v_mov_b32_e32 v126, 0
	v_mov_b32_e32 v127, 0
	s_mov_b32 s8, 0
	s_waitcnt vmcnt(4)
	s_barrier
	s_setprio 2
.Lg16_down_k:
	s_add_i32 s9, s8, 2
	s_lshl_b32 s96, s9, 13
	s_add_i32 m0, vcc_lo, 16384
	v_lshl_add_u64 v[160:161], v[188:189], 0, s[96:97]
	global_load_lds_dwordx4 v[160:161], off
	global_load_lds_dwordx4 v[160:161], off offset:1024
	ds_read_b128 v[196:199], v246 offset:0
	ds_read_b128 v[200:203], v246 offset:1024
	ds_read_b128 v[204:207], v246 offset:2048
	ds_read_b128 v[242:245], v246 offset:3072
	s_add_i32 s9, s8, 2
	s_lshl_b32 s96, s9, 11
	v_lshl_add_u64 v[248:249], v[184:185], 0, s[96:97]
	v_lshl_add_u64 v[250:251], v[186:187], 0, s[96:97]
	s_waitcnt vmcnt(8) lgkmcnt(3)
	v_mfma_f32_16x16x32_bf16 v[112:115], v[128:131], v[196:199], v[112:115]
	v_mfma_f32_16x16x32_bf16 v[120:123], v[132:135], v[196:199], v[120:123]
	v_mfma_f32_16x16x32_bf16 v[48:51], v[136:139], v[196:199], v[48:51]
	v_mfma_f32_16x16x32_bf16 v[56:59], v[140:143], v[196:199], v[56:59]
	ds_read_b128 v[196:199], v246 offset:4096
	s_waitcnt lgkmcnt(3)
	v_mfma_f32_16x16x32_bf16 v[116:119], v[128:131], v[200:203], v[116:119]
	v_mfma_f32_16x16x32_bf16 v[124:127], v[132:135], v[200:203], v[124:127]
	v_mfma_f32_16x16x32_bf16 v[52:55], v[136:139], v[200:203], v[52:55]
	v_mfma_f32_16x16x32_bf16 v[60:63], v[140:143], v[200:203], v[60:63]
	ds_read_b128 v[200:203], v246 offset:5120
	s_waitcnt lgkmcnt(3)
	v_mfma_f32_16x16x32_bf16 v[96:99], v[128:131], v[204:207], v[96:99]
	v_mfma_f32_16x16x32_bf16 v[104:107], v[132:135], v[204:207], v[104:107]
	v_mfma_f32_16x16x32_bf16 v[32:35], v[136:139], v[204:207], v[32:35]
	v_mfma_f32_16x16x32_bf16 v[40:43], v[140:143], v[204:207], v[40:43]
	ds_read_b128 v[204:207], v246 offset:6144
	s_waitcnt lgkmcnt(3)
	v_mfma_f32_16x16x32_bf16 v[100:103], v[128:131], v[242:245], v[100:103]
	v_mfma_f32_16x16x32_bf16 v[108:111], v[132:135], v[242:245], v[108:111]
	v_mfma_f32_16x16x32_bf16 v[36:39], v[136:139], v[242:245], v[36:39]
	v_mfma_f32_16x16x32_bf16 v[44:47], v[140:143], v[242:245], v[44:47]
	ds_read_b128 v[242:245], v246 offset:7168
	s_waitcnt lgkmcnt(3)
	v_mfma_f32_16x16x32_bf16 v[80:83], v[128:131], v[196:199], v[80:83]
	v_mfma_f32_16x16x32_bf16 v[88:91], v[132:135], v[196:199], v[88:91]
	v_mfma_f32_16x16x32_bf16 v[16:19], v[136:139], v[196:199], v[16:19]
	v_mfma_f32_16x16x32_bf16 v[24:27], v[140:143], v[196:199], v[24:27]
	s_waitcnt lgkmcnt(2)
	v_mfma_f32_16x16x32_bf16 v[84:87], v[128:131], v[200:203], v[84:87]
	v_mfma_f32_16x16x32_bf16 v[92:95], v[132:135], v[200:203], v[92:95]
	v_mfma_f32_16x16x32_bf16 v[20:23], v[136:139], v[200:203], v[20:23]
	v_mfma_f32_16x16x32_bf16 v[28:31], v[140:143], v[200:203], v[28:31]
	s_waitcnt lgkmcnt(1)
	v_mfma_f32_16x16x32_bf16 v[64:67], v[128:131], v[204:207], v[64:67]
	v_mfma_f32_16x16x32_bf16 v[72:75], v[132:135], v[204:207], v[72:75]
	v_mfma_f32_16x16x32_bf16 v[0:3], v[136:139], v[204:207], v[0:3]
	v_mfma_f32_16x16x32_bf16 v[8:11], v[140:143], v[204:207], v[8:11]
	s_waitcnt lgkmcnt(0)
	v_mfma_f32_16x16x32_bf16 v[68:71], v[128:131], v[242:245], v[68:71]
	v_mfma_f32_16x16x32_bf16 v[76:79], v[132:135], v[242:245], v[76:79]
	v_mfma_f32_16x16x32_bf16 v[4:7], v[136:139], v[242:245], v[4:7]
	v_mfma_f32_16x16x32_bf16 v[12:15], v[140:143], v[242:245], v[12:15]
	global_load_dwordx4 v[128:131], v[248:249], off
	global_load_dwordx4 v[132:135], v[248:249], off offset:256
	global_load_dwordx4 v[136:139], v[250:251], off
	global_load_dwordx4 v[140:143], v[250:251], off offset:256
	s_waitcnt vmcnt(10)
	s_barrier
	s_add_i32 s9, s8, 3
	s_lshl_b32 s96, s9, 13
	s_mov_b32 m0, vcc_lo
	v_lshl_add_u64 v[160:161], v[188:189], 0, s[96:97]
	global_load_lds_dwordx4 v[160:161], off
	global_load_lds_dwordx4 v[160:161], off offset:1024
	ds_read_b128 v[196:199], v246 offset:8192
	ds_read_b128 v[200:203], v246 offset:9216
	ds_read_b128 v[204:207], v246 offset:10240
	ds_read_b128 v[242:245], v246 offset:11264
	s_add_i32 s9, s8, 3
	s_lshl_b32 s96, s9, 11
	v_lshl_add_u64 v[248:249], v[184:185], 0, s[96:97]
	v_lshl_add_u64 v[250:251], v[186:187], 0, s[96:97]
	s_waitcnt vmcnt(8) lgkmcnt(3)
	v_mfma_f32_16x16x32_bf16 v[112:115], v[144:147], v[196:199], v[112:115]
	v_mfma_f32_16x16x32_bf16 v[120:123], v[148:151], v[196:199], v[120:123]
	v_mfma_f32_16x16x32_bf16 v[48:51], v[152:155], v[196:199], v[48:51]
	v_mfma_f32_16x16x32_bf16 v[56:59], v[156:159], v[196:199], v[56:59]
	ds_read_b128 v[196:199], v246 offset:12288
	s_waitcnt lgkmcnt(3)
	v_mfma_f32_16x16x32_bf16 v[116:119], v[144:147], v[200:203], v[116:119]
	v_mfma_f32_16x16x32_bf16 v[124:127], v[148:151], v[200:203], v[124:127]
	v_mfma_f32_16x16x32_bf16 v[52:55], v[152:155], v[200:203], v[52:55]
	v_mfma_f32_16x16x32_bf16 v[60:63], v[156:159], v[200:203], v[60:63]
	ds_read_b128 v[200:203], v246 offset:13312
	s_waitcnt lgkmcnt(3)
	v_mfma_f32_16x16x32_bf16 v[96:99], v[144:147], v[204:207], v[96:99]
	v_mfma_f32_16x16x32_bf16 v[104:107], v[148:151], v[204:207], v[104:107]
	v_mfma_f32_16x16x32_bf16 v[32:35], v[152:155], v[204:207], v[32:35]
	v_mfma_f32_16x16x32_bf16 v[40:43], v[156:159], v[204:207], v[40:43]
	ds_read_b128 v[204:207], v246 offset:14336
	s_waitcnt lgkmcnt(3)
	v_mfma_f32_16x16x32_bf16 v[100:103], v[144:147], v[242:245], v[100:103]
	v_mfma_f32_16x16x32_bf16 v[108:111], v[148:151], v[242:245], v[108:111]
	v_mfma_f32_16x16x32_bf16 v[36:39], v[152:155], v[242:245], v[36:39]
	v_mfma_f32_16x16x32_bf16 v[44:47], v[156:159], v[242:245], v[44:47]
	ds_read_b128 v[242:245], v246 offset:15360
	s_waitcnt lgkmcnt(3)
	v_mfma_f32_16x16x32_bf16 v[80:83], v[144:147], v[196:199], v[80:83]
	v_mfma_f32_16x16x32_bf16 v[88:91], v[148:151], v[196:199], v[88:91]
	v_mfma_f32_16x16x32_bf16 v[16:19], v[152:155], v[196:199], v[16:19]
	v_mfma_f32_16x16x32_bf16 v[24:27], v[156:159], v[196:199], v[24:27]
	s_waitcnt lgkmcnt(2)
	v_mfma_f32_16x16x32_bf16 v[84:87], v[144:147], v[200:203], v[84:87]
	v_mfma_f32_16x16x32_bf16 v[92:95], v[148:151], v[200:203], v[92:95]
	v_mfma_f32_16x16x32_bf16 v[20:23], v[152:155], v[200:203], v[20:23]
	v_mfma_f32_16x16x32_bf16 v[28:31], v[156:159], v[200:203], v[28:31]
	s_waitcnt lgkmcnt(1)
	v_mfma_f32_16x16x32_bf16 v[64:67], v[144:147], v[204:207], v[64:67]
	v_mfma_f32_16x16x32_bf16 v[72:75], v[148:151], v[204:207], v[72:75]
	v_mfma_f32_16x16x32_bf16 v[0:3], v[152:155], v[204:207], v[0:3]
	v_mfma_f32_16x16x32_bf16 v[8:11], v[156:159], v[204:207], v[8:11]
	s_waitcnt lgkmcnt(0)
	v_mfma_f32_16x16x32_bf16 v[68:71], v[144:147], v[242:245], v[68:71]
	v_mfma_f32_16x16x32_bf16 v[76:79], v[148:151], v[242:245], v[76:79]
	v_mfma_f32_16x16x32_bf16 v[4:7], v[152:155], v[242:245], v[4:7]
	v_mfma_f32_16x16x32_bf16 v[12:15], v[156:159], v[242:245], v[12:15]
	global_load_dwordx4 v[144:147], v[248:249], off
	global_load_dwordx4 v[148:151], v[248:249], off offset:256
	global_load_dwordx4 v[152:155], v[250:251], off
	global_load_dwordx4 v[156:159], v[250:251], off offset:256
	s_waitcnt vmcnt(10)
	s_barrier
	s_add_i32 s9, s8, 4
	s_lshl_b32 s96, s9, 13
	s_add_i32 m0, vcc_lo, 8192
	v_lshl_add_u64 v[160:161], v[188:189], 0, s[96:97]
	global_load_lds_dwordx4 v[160:161], off
	global_load_lds_dwordx4 v[160:161], off offset:1024
	ds_read_b128 v[196:199], v246 offset:16384
	ds_read_b128 v[200:203], v246 offset:17408
	ds_read_b128 v[204:207], v246 offset:18432
	ds_read_b128 v[242:245], v246 offset:19456
	s_add_i32 s9, s8, 4
	s_lshl_b32 s96, s9, 11
	v_lshl_add_u64 v[248:249], v[184:185], 0, s[96:97]
	v_lshl_add_u64 v[250:251], v[186:187], 0, s[96:97]
	s_waitcnt vmcnt(8) lgkmcnt(3)
	v_mfma_f32_16x16x32_bf16 v[112:115], v[128:131], v[196:199], v[112:115]
	v_mfma_f32_16x16x32_bf16 v[120:123], v[132:135], v[196:199], v[120:123]
	v_mfma_f32_16x16x32_bf16 v[48:51], v[136:139], v[196:199], v[48:51]
	v_mfma_f32_16x16x32_bf16 v[56:59], v[140:143], v[196:199], v[56:59]
	ds_read_b128 v[196:199], v246 offset:20480
	s_waitcnt lgkmcnt(3)
	v_mfma_f32_16x16x32_bf16 v[116:119], v[128:131], v[200:203], v[116:119]
	v_mfma_f32_16x16x32_bf16 v[124:127], v[132:135], v[200:203], v[124:127]
	v_mfma_f32_16x16x32_bf16 v[52:55], v[136:139], v[200:203], v[52:55]
	v_mfma_f32_16x16x32_bf16 v[60:63], v[140:143], v[200:203], v[60:63]
	ds_read_b128 v[200:203], v246 offset:21504
	s_waitcnt lgkmcnt(3)
	v_mfma_f32_16x16x32_bf16 v[96:99], v[128:131], v[204:207], v[96:99]
	v_mfma_f32_16x16x32_bf16 v[104:107], v[132:135], v[204:207], v[104:107]
	v_mfma_f32_16x16x32_bf16 v[32:35], v[136:139], v[204:207], v[32:35]
	v_mfma_f32_16x16x32_bf16 v[40:43], v[140:143], v[204:207], v[40:43]
	ds_read_b128 v[204:207], v246 offset:22528
	s_waitcnt lgkmcnt(3)
	v_mfma_f32_16x16x32_bf16 v[100:103], v[128:131], v[242:245], v[100:103]
	v_mfma_f32_16x16x32_bf16 v[108:111], v[132:135], v[242:245], v[108:111]
	v_mfma_f32_16x16x32_bf16 v[36:39], v[136:139], v[242:245], v[36:39]
	v_mfma_f32_16x16x32_bf16 v[44:47], v[140:143], v[242:245], v[44:47]
	ds_read_b128 v[242:245], v246 offset:23552
	s_waitcnt lgkmcnt(3)
	v_mfma_f32_16x16x32_bf16 v[80:83], v[128:131], v[196:199], v[80:83]
	v_mfma_f32_16x16x32_bf16 v[88:91], v[132:135], v[196:199], v[88:91]
	v_mfma_f32_16x16x32_bf16 v[16:19], v[136:139], v[196:199], v[16:19]
	v_mfma_f32_16x16x32_bf16 v[24:27], v[140:143], v[196:199], v[24:27]
	s_waitcnt lgkmcnt(2)
	v_mfma_f32_16x16x32_bf16 v[84:87], v[128:131], v[200:203], v[84:87]
	v_mfma_f32_16x16x32_bf16 v[92:95], v[132:135], v[200:203], v[92:95]
	v_mfma_f32_16x16x32_bf16 v[20:23], v[136:139], v[200:203], v[20:23]
	v_mfma_f32_16x16x32_bf16 v[28:31], v[140:143], v[200:203], v[28:31]
	s_waitcnt lgkmcnt(1)
	v_mfma_f32_16x16x32_bf16 v[64:67], v[128:131], v[204:207], v[64:67]
	v_mfma_f32_16x16x32_bf16 v[72:75], v[132:135], v[204:207], v[72:75]
	v_mfma_f32_16x16x32_bf16 v[0:3], v[136:139], v[204:207], v[0:3]
	v_mfma_f32_16x16x32_bf16 v[8:11], v[140:143], v[204:207], v[8:11]
	s_waitcnt lgkmcnt(0)
	v_mfma_f32_16x16x32_bf16 v[68:71], v[128:131], v[242:245], v[68:71]
	v_mfma_f32_16x16x32_bf16 v[76:79], v[132:135], v[242:245], v[76:79]
	v_mfma_f32_16x16x32_bf16 v[4:7], v[136:139], v[242:245], v[4:7]
	v_mfma_f32_16x16x32_bf16 v[12:15], v[140:143], v[242:245], v[12:15]
	global_load_dwordx4 v[128:131], v[248:249], off
	global_load_dwordx4 v[132:135], v[248:249], off offset:256
	global_load_dwordx4 v[136:139], v[250:251], off
	global_load_dwordx4 v[140:143], v[250:251], off offset:256
	s_waitcnt vmcnt(10)
	s_barrier
	s_add_i32 s9, s8, 5
	s_lshl_b32 s96, s9, 13
	s_add_i32 m0, vcc_lo, 16384
	v_lshl_add_u64 v[160:161], v[188:189], 0, s[96:97]
	global_load_lds_dwordx4 v[160:161], off
	global_load_lds_dwordx4 v[160:161], off offset:1024
	ds_read_b128 v[196:199], v246 offset:0
	ds_read_b128 v[200:203], v246 offset:1024
	ds_read_b128 v[204:207], v246 offset:2048
	ds_read_b128 v[242:245], v246 offset:3072
	s_add_i32 s9, s8, 5
	s_lshl_b32 s96, s9, 11
	v_lshl_add_u64 v[248:249], v[184:185], 0, s[96:97]
	v_lshl_add_u64 v[250:251], v[186:187], 0, s[96:97]
	s_waitcnt vmcnt(8) lgkmcnt(3)
	v_mfma_f32_16x16x32_bf16 v[112:115], v[144:147], v[196:199], v[112:115]
	v_mfma_f32_16x16x32_bf16 v[120:123], v[148:151], v[196:199], v[120:123]
	v_mfma_f32_16x16x32_bf16 v[48:51], v[152:155], v[196:199], v[48:51]
	v_mfma_f32_16x16x32_bf16 v[56:59], v[156:159], v[196:199], v[56:59]
	ds_read_b128 v[196:199], v246 offset:4096
	s_waitcnt lgkmcnt(3)
	v_mfma_f32_16x16x32_bf16 v[116:119], v[144:147], v[200:203], v[116:119]
	v_mfma_f32_16x16x32_bf16 v[124:127], v[148:151], v[200:203], v[124:127]
	v_mfma_f32_16x16x32_bf16 v[52:55], v[152:155], v[200:203], v[52:55]
	v_mfma_f32_16x16x32_bf16 v[60:63], v[156:159], v[200:203], v[60:63]
	ds_read_b128 v[200:203], v246 offset:5120
	s_waitcnt lgkmcnt(3)
	v_mfma_f32_16x16x32_bf16 v[96:99], v[144:147], v[204:207], v[96:99]
	v_mfma_f32_16x16x32_bf16 v[104:107], v[148:151], v[204:207], v[104:107]
	v_mfma_f32_16x16x32_bf16 v[32:35], v[152:155], v[204:207], v[32:35]
	v_mfma_f32_16x16x32_bf16 v[40:43], v[156:159], v[204:207], v[40:43]
	ds_read_b128 v[204:207], v246 offset:6144
	s_waitcnt lgkmcnt(3)
	v_mfma_f32_16x16x32_bf16 v[100:103], v[144:147], v[242:245], v[100:103]
	v_mfma_f32_16x16x32_bf16 v[108:111], v[148:151], v[242:245], v[108:111]
	v_mfma_f32_16x16x32_bf16 v[36:39], v[152:155], v[242:245], v[36:39]
	v_mfma_f32_16x16x32_bf16 v[44:47], v[156:159], v[242:245], v[44:47]
	ds_read_b128 v[242:245], v246 offset:7168
	s_waitcnt lgkmcnt(3)
	v_mfma_f32_16x16x32_bf16 v[80:83], v[144:147], v[196:199], v[80:83]
	v_mfma_f32_16x16x32_bf16 v[88:91], v[148:151], v[196:199], v[88:91]
	v_mfma_f32_16x16x32_bf16 v[16:19], v[152:155], v[196:199], v[16:19]
	v_mfma_f32_16x16x32_bf16 v[24:27], v[156:159], v[196:199], v[24:27]
	s_waitcnt lgkmcnt(2)
	v_mfma_f32_16x16x32_bf16 v[84:87], v[144:147], v[200:203], v[84:87]
	v_mfma_f32_16x16x32_bf16 v[92:95], v[148:151], v[200:203], v[92:95]
	v_mfma_f32_16x16x32_bf16 v[20:23], v[152:155], v[200:203], v[20:23]
	v_mfma_f32_16x16x32_bf16 v[28:31], v[156:159], v[200:203], v[28:31]
	s_waitcnt lgkmcnt(1)
	v_mfma_f32_16x16x32_bf16 v[64:67], v[144:147], v[204:207], v[64:67]
	v_mfma_f32_16x16x32_bf16 v[72:75], v[148:151], v[204:207], v[72:75]
	v_mfma_f32_16x16x32_bf16 v[0:3], v[152:155], v[204:207], v[0:3]
	v_mfma_f32_16x16x32_bf16 v[8:11], v[156:159], v[204:207], v[8:11]
	s_waitcnt lgkmcnt(0)
	v_mfma_f32_16x16x32_bf16 v[68:71], v[144:147], v[242:245], v[68:71]
	v_mfma_f32_16x16x32_bf16 v[76:79], v[148:151], v[242:245], v[76:79]
	v_mfma_f32_16x16x32_bf16 v[4:7], v[152:155], v[242:245], v[4:7]
	v_mfma_f32_16x16x32_bf16 v[12:15], v[156:159], v[242:245], v[12:15]
	global_load_dwordx4 v[144:147], v[248:249], off
	global_load_dwordx4 v[148:151], v[248:249], off offset:256
	global_load_dwordx4 v[152:155], v[250:251], off
	global_load_dwordx4 v[156:159], v[250:251], off offset:256
	s_waitcnt vmcnt(10)
	s_barrier
	s_add_i32 s9, s8, 6
	s_lshl_b32 s96, s9, 13
	s_mov_b32 m0, vcc_lo
	v_lshl_add_u64 v[160:161], v[188:189], 0, s[96:97]
	global_load_lds_dwordx4 v[160:161], off
	global_load_lds_dwordx4 v[160:161], off offset:1024
	ds_read_b128 v[196:199], v246 offset:8192
	ds_read_b128 v[200:203], v246 offset:9216
	ds_read_b128 v[204:207], v246 offset:10240
	ds_read_b128 v[242:245], v246 offset:11264
	s_add_i32 s9, s8, 6
	s_lshl_b32 s96, s9, 11
	v_lshl_add_u64 v[248:249], v[184:185], 0, s[96:97]
	v_lshl_add_u64 v[250:251], v[186:187], 0, s[96:97]
	s_waitcnt vmcnt(8) lgkmcnt(3)
	v_mfma_f32_16x16x32_bf16 v[112:115], v[128:131], v[196:199], v[112:115]
	v_mfma_f32_16x16x32_bf16 v[120:123], v[132:135], v[196:199], v[120:123]
	v_mfma_f32_16x16x32_bf16 v[48:51], v[136:139], v[196:199], v[48:51]
	v_mfma_f32_16x16x32_bf16 v[56:59], v[140:143], v[196:199], v[56:59]
	ds_read_b128 v[196:199], v246 offset:12288
	s_waitcnt lgkmcnt(3)
	v_mfma_f32_16x16x32_bf16 v[116:119], v[128:131], v[200:203], v[116:119]
	v_mfma_f32_16x16x32_bf16 v[124:127], v[132:135], v[200:203], v[124:127]
	v_mfma_f32_16x16x32_bf16 v[52:55], v[136:139], v[200:203], v[52:55]
	v_mfma_f32_16x16x32_bf16 v[60:63], v[140:143], v[200:203], v[60:63]
	ds_read_b128 v[200:203], v246 offset:13312
	s_waitcnt lgkmcnt(3)
	v_mfma_f32_16x16x32_bf16 v[96:99], v[128:131], v[204:207], v[96:99]
	v_mfma_f32_16x16x32_bf16 v[104:107], v[132:135], v[204:207], v[104:107]
	v_mfma_f32_16x16x32_bf16 v[32:35], v[136:139], v[204:207], v[32:35]
	v_mfma_f32_16x16x32_bf16 v[40:43], v[140:143], v[204:207], v[40:43]
	ds_read_b128 v[204:207], v246 offset:14336
	s_waitcnt lgkmcnt(3)
	v_mfma_f32_16x16x32_bf16 v[100:103], v[128:131], v[242:245], v[100:103]
	v_mfma_f32_16x16x32_bf16 v[108:111], v[132:135], v[242:245], v[108:111]
	v_mfma_f32_16x16x32_bf16 v[36:39], v[136:139], v[242:245], v[36:39]
	v_mfma_f32_16x16x32_bf16 v[44:47], v[140:143], v[242:245], v[44:47]
	ds_read_b128 v[242:245], v246 offset:15360
	s_waitcnt lgkmcnt(3)
	v_mfma_f32_16x16x32_bf16 v[80:83], v[128:131], v[196:199], v[80:83]
	v_mfma_f32_16x16x32_bf16 v[88:91], v[132:135], v[196:199], v[88:91]
	v_mfma_f32_16x16x32_bf16 v[16:19], v[136:139], v[196:199], v[16:19]
	v_mfma_f32_16x16x32_bf16 v[24:27], v[140:143], v[196:199], v[24:27]
	s_waitcnt lgkmcnt(2)
	v_mfma_f32_16x16x32_bf16 v[84:87], v[128:131], v[200:203], v[84:87]
	v_mfma_f32_16x16x32_bf16 v[92:95], v[132:135], v[200:203], v[92:95]
	v_mfma_f32_16x16x32_bf16 v[20:23], v[136:139], v[200:203], v[20:23]
	v_mfma_f32_16x16x32_bf16 v[28:31], v[140:143], v[200:203], v[28:31]
	s_waitcnt lgkmcnt(1)
	v_mfma_f32_16x16x32_bf16 v[64:67], v[128:131], v[204:207], v[64:67]
	v_mfma_f32_16x16x32_bf16 v[72:75], v[132:135], v[204:207], v[72:75]
	v_mfma_f32_16x16x32_bf16 v[0:3], v[136:139], v[204:207], v[0:3]
	v_mfma_f32_16x16x32_bf16 v[8:11], v[140:143], v[204:207], v[8:11]
	s_waitcnt lgkmcnt(0)
	v_mfma_f32_16x16x32_bf16 v[68:71], v[128:131], v[242:245], v[68:71]
	v_mfma_f32_16x16x32_bf16 v[76:79], v[132:135], v[242:245], v[76:79]
	v_mfma_f32_16x16x32_bf16 v[4:7], v[136:139], v[242:245], v[4:7]
	v_mfma_f32_16x16x32_bf16 v[12:15], v[140:143], v[242:245], v[12:15]
	global_load_dwordx4 v[128:131], v[248:249], off
	global_load_dwordx4 v[132:135], v[248:249], off offset:256
	global_load_dwordx4 v[136:139], v[250:251], off
	global_load_dwordx4 v[140:143], v[250:251], off offset:256
	s_waitcnt vmcnt(10)
	s_barrier
	s_add_i32 s9, s8, 7
	s_lshl_b32 s96, s9, 13
	s_add_i32 m0, vcc_lo, 8192
	v_lshl_add_u64 v[160:161], v[188:189], 0, s[96:97]
	global_load_lds_dwordx4 v[160:161], off
	global_load_lds_dwordx4 v[160:161], off offset:1024
	ds_read_b128 v[196:199], v246 offset:16384
	ds_read_b128 v[200:203], v246 offset:17408
	ds_read_b128 v[204:207], v246 offset:18432
	ds_read_b128 v[242:245], v246 offset:19456
	s_add_i32 s9, s8, 7
	s_lshl_b32 s96, s9, 11
	v_lshl_add_u64 v[248:249], v[184:185], 0, s[96:97]
	v_lshl_add_u64 v[250:251], v[186:187], 0, s[96:97]
	s_waitcnt vmcnt(8) lgkmcnt(3)
	v_mfma_f32_16x16x32_bf16 v[112:115], v[144:147], v[196:199], v[112:115]
	v_mfma_f32_16x16x32_bf16 v[120:123], v[148:151], v[196:199], v[120:123]
	v_mfma_f32_16x16x32_bf16 v[48:51], v[152:155], v[196:199], v[48:51]
	v_mfma_f32_16x16x32_bf16 v[56:59], v[156:159], v[196:199], v[56:59]
	ds_read_b128 v[196:199], v246 offset:20480
	s_waitcnt lgkmcnt(3)
	v_mfma_f32_16x16x32_bf16 v[116:119], v[144:147], v[200:203], v[116:119]
	v_mfma_f32_16x16x32_bf16 v[124:127], v[148:151], v[200:203], v[124:127]
	v_mfma_f32_16x16x32_bf16 v[52:55], v[152:155], v[200:203], v[52:55]
	v_mfma_f32_16x16x32_bf16 v[60:63], v[156:159], v[200:203], v[60:63]
	ds_read_b128 v[200:203], v246 offset:21504
	s_waitcnt lgkmcnt(3)
	v_mfma_f32_16x16x32_bf16 v[96:99], v[144:147], v[204:207], v[96:99]
	v_mfma_f32_16x16x32_bf16 v[104:107], v[148:151], v[204:207], v[104:107]
	v_mfma_f32_16x16x32_bf16 v[32:35], v[152:155], v[204:207], v[32:35]
	v_mfma_f32_16x16x32_bf16 v[40:43], v[156:159], v[204:207], v[40:43]
	ds_read_b128 v[204:207], v246 offset:22528
	s_waitcnt lgkmcnt(3)
	v_mfma_f32_16x16x32_bf16 v[100:103], v[144:147], v[242:245], v[100:103]
	v_mfma_f32_16x16x32_bf16 v[108:111], v[148:151], v[242:245], v[108:111]
	v_mfma_f32_16x16x32_bf16 v[36:39], v[152:155], v[242:245], v[36:39]
	v_mfma_f32_16x16x32_bf16 v[44:47], v[156:159], v[242:245], v[44:47]
	ds_read_b128 v[242:245], v246 offset:23552
	s_waitcnt lgkmcnt(3)
	v_mfma_f32_16x16x32_bf16 v[80:83], v[144:147], v[196:199], v[80:83]
	v_mfma_f32_16x16x32_bf16 v[88:91], v[148:151], v[196:199], v[88:91]
	v_mfma_f32_16x16x32_bf16 v[16:19], v[152:155], v[196:199], v[16:19]
	v_mfma_f32_16x16x32_bf16 v[24:27], v[156:159], v[196:199], v[24:27]
	s_waitcnt lgkmcnt(2)
	v_mfma_f32_16x16x32_bf16 v[84:87], v[144:147], v[200:203], v[84:87]
	v_mfma_f32_16x16x32_bf16 v[92:95], v[148:151], v[200:203], v[92:95]
	v_mfma_f32_16x16x32_bf16 v[20:23], v[152:155], v[200:203], v[20:23]
	v_mfma_f32_16x16x32_bf16 v[28:31], v[156:159], v[200:203], v[28:31]
	s_waitcnt lgkmcnt(1)
	v_mfma_f32_16x16x32_bf16 v[64:67], v[144:147], v[204:207], v[64:67]
	v_mfma_f32_16x16x32_bf16 v[72:75], v[148:151], v[204:207], v[72:75]
	v_mfma_f32_16x16x32_bf16 v[0:3], v[152:155], v[204:207], v[0:3]
	v_mfma_f32_16x16x32_bf16 v[8:11], v[156:159], v[204:207], v[8:11]
	s_waitcnt lgkmcnt(0)
	v_mfma_f32_16x16x32_bf16 v[68:71], v[144:147], v[242:245], v[68:71]
	v_mfma_f32_16x16x32_bf16 v[76:79], v[148:151], v[242:245], v[76:79]
	v_mfma_f32_16x16x32_bf16 v[4:7], v[152:155], v[242:245], v[4:7]
	v_mfma_f32_16x16x32_bf16 v[12:15], v[156:159], v[242:245], v[12:15]
	global_load_dwordx4 v[144:147], v[248:249], off
	global_load_dwordx4 v[148:151], v[248:249], off offset:256
	global_load_dwordx4 v[152:155], v[250:251], off
	global_load_dwordx4 v[156:159], v[250:251], off offset:256
	s_waitcnt vmcnt(10)
	s_barrier
	s_add_i32 s8, s8, 6
	s_cmp_lt_u32 s8, 84
	s_cbranch_scc1 .Lg16_down_k
	s_mov_b32 s96, 0xac000
	s_add_i32 m0, vcc_lo, 16384
	v_lshl_add_u64 v[160:161], v[188:189], 0, s[96:97]
	global_load_lds_dwordx4 v[160:161], off
	global_load_lds_dwordx4 v[160:161], off offset:1024
	ds_read_b128 v[196:199], v246 offset:0
	ds_read_b128 v[200:203], v246 offset:1024
	ds_read_b128 v[204:207], v246 offset:2048
	ds_read_b128 v[242:245], v246 offset:3072
	s_mov_b32 s96, 0x2b000
	v_lshl_add_u64 v[248:249], v[184:185], 0, s[96:97]
	v_lshl_add_u64 v[250:251], v[186:187], 0, s[96:97]
	s_waitcnt vmcnt(8) lgkmcnt(3)
	v_mfma_f32_16x16x32_bf16 v[112:115], v[128:131], v[196:199], v[112:115]
	v_mfma_f32_16x16x32_bf16 v[120:123], v[132:135], v[196:199], v[120:123]
	v_mfma_f32_16x16x32_bf16 v[48:51], v[136:139], v[196:199], v[48:51]
	v_mfma_f32_16x16x32_bf16 v[56:59], v[140:143], v[196:199], v[56:59]
	ds_read_b128 v[196:199], v246 offset:4096
	s_waitcnt lgkmcnt(3)
	v_mfma_f32_16x16x32_bf16 v[116:119], v[128:131], v[200:203], v[116:119]
	v_mfma_f32_16x16x32_bf16 v[124:127], v[132:135], v[200:203], v[124:127]
	v_mfma_f32_16x16x32_bf16 v[52:55], v[136:139], v[200:203], v[52:55]
	v_mfma_f32_16x16x32_bf16 v[60:63], v[140:143], v[200:203], v[60:63]
	ds_read_b128 v[200:203], v246 offset:5120
	s_waitcnt lgkmcnt(3)
	v_mfma_f32_16x16x32_bf16 v[96:99], v[128:131], v[204:207], v[96:99]
	v_mfma_f32_16x16x32_bf16 v[104:107], v[132:135], v[204:207], v[104:107]
	v_mfma_f32_16x16x32_bf16 v[32:35], v[136:139], v[204:207], v[32:35]
	v_mfma_f32_16x16x32_bf16 v[40:43], v[140:143], v[204:207], v[40:43]
	ds_read_b128 v[204:207], v246 offset:6144
	s_waitcnt lgkmcnt(3)
	v_mfma_f32_16x16x32_bf16 v[100:103], v[128:131], v[242:245], v[100:103]
	v_mfma_f32_16x16x32_bf16 v[108:111], v[132:135], v[242:245], v[108:111]
	v_mfma_f32_16x16x32_bf16 v[36:39], v[136:139], v[242:245], v[36:39]
	v_mfma_f32_16x16x32_bf16 v[44:47], v[140:143], v[242:245], v[44:47]
	ds_read_b128 v[242:245], v246 offset:7168
	s_waitcnt lgkmcnt(3)
	v_mfma_f32_16x16x32_bf16 v[80:83], v[128:131], v[196:199], v[80:83]
	v_mfma_f32_16x16x32_bf16 v[88:91], v[132:135], v[196:199], v[88:91]
	v_mfma_f32_16x16x32_bf16 v[16:19], v[136:139], v[196:199], v[16:19]
	v_mfma_f32_16x16x32_bf16 v[24:27], v[140:143], v[196:199], v[24:27]
	s_waitcnt lgkmcnt(2)
	v_mfma_f32_16x16x32_bf16 v[84:87], v[128:131], v[200:203], v[84:87]
	v_mfma_f32_16x16x32_bf16 v[92:95], v[132:135], v[200:203], v[92:95]
	v_mfma_f32_16x16x32_bf16 v[20:23], v[136:139], v[200:203], v[20:23]
	v_mfma_f32_16x16x32_bf16 v[28:31], v[140:143], v[200:203], v[28:31]
	s_waitcnt lgkmcnt(1)
	v_mfma_f32_16x16x32_bf16 v[64:67], v[128:131], v[204:207], v[64:67]
	v_mfma_f32_16x16x32_bf16 v[72:75], v[132:135], v[204:207], v[72:75]
	v_mfma_f32_16x16x32_bf16 v[0:3], v[136:139], v[204:207], v[0:3]
	v_mfma_f32_16x16x32_bf16 v[8:11], v[140:143], v[204:207], v[8:11]
	s_waitcnt lgkmcnt(0)
	v_mfma_f32_16x16x32_bf16 v[68:71], v[128:131], v[242:245], v[68:71]
	v_mfma_f32_16x16x32_bf16 v[76:79], v[132:135], v[242:245], v[76:79]
	v_mfma_f32_16x16x32_bf16 v[4:7], v[136:139], v[242:245], v[4:7]
	v_mfma_f32_16x16x32_bf16 v[12:15], v[140:143], v[242:245], v[12:15]
	global_load_dwordx4 v[128:131], v[248:249], off
	global_load_dwordx4 v[132:135], v[248:249], off offset:256
	global_load_dwordx4 v[136:139], v[250:251], off
	global_load_dwordx4 v[140:143], v[250:251], off offset:256
	s_waitcnt vmcnt(10)
	s_barrier
	s_mov_b32 s96, 0xae000
	s_mov_b32 m0, vcc_lo
	v_lshl_add_u64 v[160:161], v[188:189], 0, s[96:97]
	global_load_lds_dwordx4 v[160:161], off
	global_load_lds_dwordx4 v[160:161], off offset:1024
	ds_read_b128 v[196:199], v246 offset:8192
	ds_read_b128 v[200:203], v246 offset:9216
	ds_read_b128 v[204:207], v246 offset:10240
	ds_read_b128 v[242:245], v246 offset:11264
	s_mov_b32 s96, 0x2b800
	v_lshl_add_u64 v[248:249], v[184:185], 0, s[96:97]
	v_lshl_add_u64 v[250:251], v[186:187], 0, s[96:97]
	s_waitcnt vmcnt(8) lgkmcnt(3)
	v_mfma_f32_16x16x32_bf16 v[112:115], v[144:147], v[196:199], v[112:115]
	v_mfma_f32_16x16x32_bf16 v[120:123], v[148:151], v[196:199], v[120:123]
	v_mfma_f32_16x16x32_bf16 v[48:51], v[152:155], v[196:199], v[48:51]
	v_mfma_f32_16x16x32_bf16 v[56:59], v[156:159], v[196:199], v[56:59]
	ds_read_b128 v[196:199], v246 offset:12288
	s_waitcnt lgkmcnt(3)
	v_mfma_f32_16x16x32_bf16 v[116:119], v[144:147], v[200:203], v[116:119]
	v_mfma_f32_16x16x32_bf16 v[124:127], v[148:151], v[200:203], v[124:127]
	v_mfma_f32_16x16x32_bf16 v[52:55], v[152:155], v[200:203], v[52:55]
	v_mfma_f32_16x16x32_bf16 v[60:63], v[156:159], v[200:203], v[60:63]
	ds_read_b128 v[200:203], v246 offset:13312
	s_waitcnt lgkmcnt(3)
	v_mfma_f32_16x16x32_bf16 v[96:99], v[144:147], v[204:207], v[96:99]
	v_mfma_f32_16x16x32_bf16 v[104:107], v[148:151], v[204:207], v[104:107]
	v_mfma_f32_16x16x32_bf16 v[32:35], v[152:155], v[204:207], v[32:35]
	v_mfma_f32_16x16x32_bf16 v[40:43], v[156:159], v[204:207], v[40:43]
	ds_read_b128 v[204:207], v246 offset:14336
	s_waitcnt lgkmcnt(3)
	v_mfma_f32_16x16x32_bf16 v[100:103], v[144:147], v[242:245], v[100:103]
	v_mfma_f32_16x16x32_bf16 v[108:111], v[148:151], v[242:245], v[108:111]
	v_mfma_f32_16x16x32_bf16 v[36:39], v[152:155], v[242:245], v[36:39]
	v_mfma_f32_16x16x32_bf16 v[44:47], v[156:159], v[242:245], v[44:47]
	ds_read_b128 v[242:245], v246 offset:15360
	s_waitcnt lgkmcnt(3)
	v_mfma_f32_16x16x32_bf16 v[80:83], v[144:147], v[196:199], v[80:83]
	v_mfma_f32_16x16x32_bf16 v[88:91], v[148:151], v[196:199], v[88:91]
	v_mfma_f32_16x16x32_bf16 v[16:19], v[152:155], v[196:199], v[16:19]
	v_mfma_f32_16x16x32_bf16 v[24:27], v[156:159], v[196:199], v[24:27]
	s_waitcnt lgkmcnt(2)
	v_mfma_f32_16x16x32_bf16 v[84:87], v[144:147], v[200:203], v[84:87]
	v_mfma_f32_16x16x32_bf16 v[92:95], v[148:151], v[200:203], v[92:95]
	v_mfma_f32_16x16x32_bf16 v[20:23], v[152:155], v[200:203], v[20:23]
	v_mfma_f32_16x16x32_bf16 v[28:31], v[156:159], v[200:203], v[28:31]
	s_waitcnt lgkmcnt(1)
	v_mfma_f32_16x16x32_bf16 v[64:67], v[144:147], v[204:207], v[64:67]
	v_mfma_f32_16x16x32_bf16 v[72:75], v[148:151], v[204:207], v[72:75]
	v_mfma_f32_16x16x32_bf16 v[0:3], v[152:155], v[204:207], v[0:3]
	v_mfma_f32_16x16x32_bf16 v[8:11], v[156:159], v[204:207], v[8:11]
	s_waitcnt lgkmcnt(0)
	v_mfma_f32_16x16x32_bf16 v[68:71], v[144:147], v[242:245], v[68:71]
	v_mfma_f32_16x16x32_bf16 v[76:79], v[148:151], v[242:245], v[76:79]
	v_mfma_f32_16x16x32_bf16 v[4:7], v[152:155], v[242:245], v[4:7]
	v_mfma_f32_16x16x32_bf16 v[12:15], v[156:159], v[242:245], v[12:15]
	global_load_dwordx4 v[144:147], v[248:249], off
	global_load_dwordx4 v[148:151], v[248:249], off offset:256
	global_load_dwordx4 v[152:155], v[250:251], off
	global_load_dwordx4 v[156:159], v[250:251], off offset:256
	s_waitcnt vmcnt(10)
	s_barrier
	ds_read_b128 v[196:199], v246 offset:16384
	ds_read_b128 v[200:203], v246 offset:17408
	ds_read_b128 v[204:207], v246 offset:18432
	ds_read_b128 v[242:245], v246 offset:19456
	s_waitcnt vmcnt(6) lgkmcnt(3)
	v_mfma_f32_16x16x32_bf16 v[112:115], v[128:131], v[196:199], v[112:115]
	v_mfma_f32_16x16x32_bf16 v[120:123], v[132:135], v[196:199], v[120:123]
	v_mfma_f32_16x16x32_bf16 v[48:51], v[136:139], v[196:199], v[48:51]
	v_mfma_f32_16x16x32_bf16 v[56:59], v[140:143], v[196:199], v[56:59]
	ds_read_b128 v[196:199], v246 offset:20480
	s_waitcnt lgkmcnt(3)
	v_mfma_f32_16x16x32_bf16 v[116:119], v[128:131], v[200:203], v[116:119]
	v_mfma_f32_16x16x32_bf16 v[124:127], v[132:135], v[200:203], v[124:127]
	v_mfma_f32_16x16x32_bf16 v[52:55], v[136:139], v[200:203], v[52:55]
	v_mfma_f32_16x16x32_bf16 v[60:63], v[140:143], v[200:203], v[60:63]
	ds_read_b128 v[200:203], v246 offset:21504
	s_waitcnt lgkmcnt(3)
	v_mfma_f32_16x16x32_bf16 v[96:99], v[128:131], v[204:207], v[96:99]
	v_mfma_f32_16x16x32_bf16 v[104:107], v[132:135], v[204:207], v[104:107]
	v_mfma_f32_16x16x32_bf16 v[32:35], v[136:139], v[204:207], v[32:35]
	v_mfma_f32_16x16x32_bf16 v[40:43], v[140:143], v[204:207], v[40:43]
	ds_read_b128 v[204:207], v246 offset:22528
	s_waitcnt lgkmcnt(3)
	v_mfma_f32_16x16x32_bf16 v[100:103], v[128:131], v[242:245], v[100:103]
	v_mfma_f32_16x16x32_bf16 v[108:111], v[132:135], v[242:245], v[108:111]
	v_mfma_f32_16x16x32_bf16 v[36:39], v[136:139], v[242:245], v[36:39]
	v_mfma_f32_16x16x32_bf16 v[44:47], v[140:143], v[242:245], v[44:47]
	ds_read_b128 v[242:245], v246 offset:23552
	s_waitcnt lgkmcnt(3)
	v_mfma_f32_16x16x32_bf16 v[80:83], v[128:131], v[196:199], v[80:83]
	v_mfma_f32_16x16x32_bf16 v[88:91], v[132:135], v[196:199], v[88:91]
	v_mfma_f32_16x16x32_bf16 v[16:19], v[136:139], v[196:199], v[16:19]
	v_mfma_f32_16x16x32_bf16 v[24:27], v[140:143], v[196:199], v[24:27]
	s_waitcnt lgkmcnt(2)
	v_mfma_f32_16x16x32_bf16 v[84:87], v[128:131], v[200:203], v[84:87]
	v_mfma_f32_16x16x32_bf16 v[92:95], v[132:135], v[200:203], v[92:95]
	v_mfma_f32_16x16x32_bf16 v[20:23], v[136:139], v[200:203], v[20:23]
	v_mfma_f32_16x16x32_bf16 v[28:31], v[140:143], v[200:203], v[28:31]
	s_waitcnt lgkmcnt(1)
	v_mfma_f32_16x16x32_bf16 v[64:67], v[128:131], v[204:207], v[64:67]
	v_mfma_f32_16x16x32_bf16 v[72:75], v[132:135], v[204:207], v[72:75]
	v_mfma_f32_16x16x32_bf16 v[0:3], v[136:139], v[204:207], v[0:3]
	v_mfma_f32_16x16x32_bf16 v[8:11], v[140:143], v[204:207], v[8:11]
	s_waitcnt lgkmcnt(0)
	v_mfma_f32_16x16x32_bf16 v[68:71], v[128:131], v[242:245], v[68:71]
	v_mfma_f32_16x16x32_bf16 v[76:79], v[132:135], v[242:245], v[76:79]
	v_mfma_f32_16x16x32_bf16 v[4:7], v[136:139], v[242:245], v[4:7]
	v_mfma_f32_16x16x32_bf16 v[12:15], v[140:143], v[242:245], v[12:15]
	s_waitcnt vmcnt(4)
	s_barrier
	ds_read_b128 v[196:199], v246 offset:0
	ds_read_b128 v[200:203], v246 offset:1024
	ds_read_b128 v[204:207], v246 offset:2048
	ds_read_b128 v[242:245], v246 offset:3072
	s_waitcnt vmcnt(0) lgkmcnt(3)
	v_mfma_f32_16x16x32_bf16 v[112:115], v[144:147], v[196:199], v[112:115]
	v_mfma_f32_16x16x32_bf16 v[120:123], v[148:151], v[196:199], v[120:123]
	v_mfma_f32_16x16x32_bf16 v[48:51], v[152:155], v[196:199], v[48:51]
	v_mfma_f32_16x16x32_bf16 v[56:59], v[156:159], v[196:199], v[56:59]
	ds_read_b128 v[196:199], v246 offset:4096
	s_waitcnt lgkmcnt(3)
	v_mfma_f32_16x16x32_bf16 v[116:119], v[144:147], v[200:203], v[116:119]
	v_mfma_f32_16x16x32_bf16 v[124:127], v[148:151], v[200:203], v[124:127]
	v_mfma_f32_16x16x32_bf16 v[52:55], v[152:155], v[200:203], v[52:55]
	v_mfma_f32_16x16x32_bf16 v[60:63], v[156:159], v[200:203], v[60:63]
	ds_read_b128 v[200:203], v246 offset:5120
	s_waitcnt lgkmcnt(3)
	v_mfma_f32_16x16x32_bf16 v[96:99], v[144:147], v[204:207], v[96:99]
	v_mfma_f32_16x16x32_bf16 v[104:107], v[148:151], v[204:207], v[104:107]
	v_mfma_f32_16x16x32_bf16 v[32:35], v[152:155], v[204:207], v[32:35]
	v_mfma_f32_16x16x32_bf16 v[40:43], v[156:159], v[204:207], v[40:43]
	ds_read_b128 v[204:207], v246 offset:6144
	s_waitcnt lgkmcnt(3)
	v_mfma_f32_16x16x32_bf16 v[100:103], v[144:147], v[242:245], v[100:103]
	v_mfma_f32_16x16x32_bf16 v[108:111], v[148:151], v[242:245], v[108:111]
	v_mfma_f32_16x16x32_bf16 v[36:39], v[152:155], v[242:245], v[36:39]
	v_mfma_f32_16x16x32_bf16 v[44:47], v[156:159], v[242:245], v[44:47]
	ds_read_b128 v[242:245], v246 offset:7168
	v_permlane16_swap_b32_e32 v112, v116
	v_permlane16_swap_b32_e32 v113, v117
	v_permlane16_swap_b32_e32 v114, v118
	v_permlane16_swap_b32_e32 v115, v119
	v_permlane16_swap_b32_e32 v120, v124
	v_permlane16_swap_b32_e32 v121, v125
	v_permlane16_swap_b32_e32 v122, v126
	v_permlane16_swap_b32_e32 v123, v127
	v_permlane16_swap_b32_e32 v48, v52
	v_permlane16_swap_b32_e32 v49, v53
	v_permlane16_swap_b32_e32 v50, v54
	v_permlane16_swap_b32_e32 v51, v55
	v_permlane16_swap_b32_e32 v56, v60
	v_permlane16_swap_b32_e32 v57, v61
	v_permlane16_swap_b32_e32 v58, v62
	v_permlane16_swap_b32_e32 v59, v63
	v_permlane32_swap_b32_e32 v112, v116
	v_permlane32_swap_b32_e32 v113, v117
	v_permlane32_swap_b32_e32 v114, v118
	v_permlane32_swap_b32_e32 v115, v119
	v_permlane32_swap_b32_e32 v120, v124
	v_permlane32_swap_b32_e32 v121, v125
	v_permlane32_swap_b32_e32 v122, v126
	v_permlane32_swap_b32_e32 v123, v127
	v_permlane32_swap_b32_e32 v48, v52
	v_permlane32_swap_b32_e32 v49, v53
	v_permlane32_swap_b32_e32 v50, v54
	v_permlane32_swap_b32_e32 v51, v55
	v_permlane32_swap_b32_e32 v56, v60
	v_permlane32_swap_b32_e32 v57, v61
	v_permlane32_swap_b32_e32 v58, v62
	v_permlane32_swap_b32_e32 v59, v63
	s_waitcnt lgkmcnt(3)
	v_mfma_f32_16x16x32_bf16 v[80:83], v[144:147], v[196:199], v[80:83]
	v_mfma_f32_16x16x32_bf16 v[88:91], v[148:151], v[196:199], v[88:91]
	v_mfma_f32_16x16x32_bf16 v[16:19], v[152:155], v[196:199], v[16:19]
	v_mfma_f32_16x16x32_bf16 v[24:27], v[156:159], v[196:199], v[24:27]
	s_waitcnt lgkmcnt(2)
	v_mfma_f32_16x16x32_bf16 v[84:87], v[144:147], v[200:203], v[84:87]
	v_mfma_f32_16x16x32_bf16 v[92:95], v[148:151], v[200:203], v[92:95]
	v_mfma_f32_16x16x32_bf16 v[20:23], v[152:155], v[200:203], v[20:23]
	v_mfma_f32_16x16x32_bf16 v[28:31], v[156:159], v[200:203], v[28:31]
	v_permlane16_swap_b32_e32 v96, v100
	v_permlane16_swap_b32_e32 v97, v101
	v_permlane16_swap_b32_e32 v98, v102
	v_permlane16_swap_b32_e32 v99, v103
	v_permlane16_swap_b32_e32 v104, v108
	v_permlane16_swap_b32_e32 v105, v109
	v_permlane16_swap_b32_e32 v106, v110
	v_permlane16_swap_b32_e32 v107, v111
	v_permlane16_swap_b32_e32 v32, v36
	v_permlane16_swap_b32_e32 v33, v37
	v_permlane16_swap_b32_e32 v34, v38
	v_permlane16_swap_b32_e32 v35, v39
	v_permlane16_swap_b32_e32 v40, v44
	v_permlane16_swap_b32_e32 v41, v45
	v_permlane16_swap_b32_e32 v42, v46
	v_permlane16_swap_b32_e32 v43, v47
	v_permlane32_swap_b32_e32 v96, v100
	v_permlane32_swap_b32_e32 v97, v101
	v_permlane32_swap_b32_e32 v98, v102
	v_permlane32_swap_b32_e32 v99, v103
	v_permlane32_swap_b32_e32 v104, v108
	v_permlane32_swap_b32_e32 v105, v109
	v_permlane32_swap_b32_e32 v106, v110
	v_permlane32_swap_b32_e32 v107, v111
	v_permlane32_swap_b32_e32 v32, v36
	v_permlane32_swap_b32_e32 v33, v37
	v_permlane32_swap_b32_e32 v34, v38
	v_permlane32_swap_b32_e32 v35, v39
	v_permlane32_swap_b32_e32 v40, v44
	v_permlane32_swap_b32_e32 v41, v45
	v_permlane32_swap_b32_e32 v42, v46
	v_permlane32_swap_b32_e32 v43, v47
	s_waitcnt lgkmcnt(1)
	v_mfma_f32_16x16x32_bf16 v[64:67], v[144:147], v[204:207], v[64:67]
	v_mfma_f32_16x16x32_bf16 v[72:75], v[148:151], v[204:207], v[72:75]
	v_mfma_f32_16x16x32_bf16 v[0:3], v[152:155], v[204:207], v[0:3]
	v_mfma_f32_16x16x32_bf16 v[8:11], v[156:159], v[204:207], v[8:11]
	s_waitcnt lgkmcnt(0)
	v_mfma_f32_16x16x32_bf16 v[68:71], v[144:147], v[242:245], v[68:71]
	v_mfma_f32_16x16x32_bf16 v[76:79], v[148:151], v[242:245], v[76:79]
	v_mfma_f32_16x16x32_bf16 v[4:7], v[152:155], v[242:245], v[4:7]
	v_mfma_f32_16x16x32_bf16 v[12:15], v[156:159], v[242:245], v[12:15]
	v_permlane16_swap_b32_e32 v80, v84
	v_permlane16_swap_b32_e32 v81, v85
	v_permlane16_swap_b32_e32 v82, v86
	v_permlane16_swap_b32_e32 v83, v87
	v_permlane16_swap_b32_e32 v88, v92
	v_permlane16_swap_b32_e32 v89, v93
	v_permlane16_swap_b32_e32 v90, v94
	v_permlane16_swap_b32_e32 v91, v95
	v_permlane16_swap_b32_e32 v16, v20
	v_permlane16_swap_b32_e32 v17, v21
	v_permlane16_swap_b32_e32 v18, v22
	v_permlane16_swap_b32_e32 v19, v23
	v_permlane16_swap_b32_e32 v24, v28
	v_permlane16_swap_b32_e32 v25, v29
	v_permlane16_swap_b32_e32 v26, v30
	v_permlane16_swap_b32_e32 v27, v31
	v_permlane32_swap_b32_e32 v80, v84
	v_permlane32_swap_b32_e32 v81, v85
	v_permlane32_swap_b32_e32 v82, v86
	v_permlane32_swap_b32_e32 v83, v87
	v_permlane32_swap_b32_e32 v88, v92
	v_permlane32_swap_b32_e32 v89, v93
	v_permlane32_swap_b32_e32 v90, v94
	v_permlane32_swap_b32_e32 v91, v95
	v_permlane32_swap_b32_e32 v16, v20
	v_permlane32_swap_b32_e32 v17, v21
	v_permlane32_swap_b32_e32 v18, v22
	v_permlane32_swap_b32_e32 v19, v23
	v_permlane32_swap_b32_e32 v24, v28
	v_permlane32_swap_b32_e32 v25, v29
	v_permlane32_swap_b32_e32 v26, v30
	v_permlane32_swap_b32_e32 v27, v31
	s_barrier
	s_setprio 0
	s_nop 7
	v_permlane16_swap_b32_e32 v64, v68
	v_permlane16_swap_b32_e32 v65, v69
	v_permlane16_swap_b32_e32 v66, v70
	v_permlane16_swap_b32_e32 v67, v71
	v_permlane16_swap_b32_e32 v72, v76
	v_permlane16_swap_b32_e32 v73, v77
	v_permlane16_swap_b32_e32 v74, v78
	v_permlane16_swap_b32_e32 v75, v79
	v_permlane16_swap_b32_e32 v0, v4
	v_permlane16_swap_b32_e32 v1, v5
	v_permlane16_swap_b32_e32 v2, v6
	v_permlane16_swap_b32_e32 v3, v7
	v_permlane16_swap_b32_e32 v8, v12
	v_permlane16_swap_b32_e32 v9, v13
	v_permlane16_swap_b32_e32 v10, v14
	v_permlane16_swap_b32_e32 v11, v15
	v_permlane32_swap_b32_e32 v64, v68
	v_permlane32_swap_b32_e32 v65, v69
	v_permlane32_swap_b32_e32 v66, v70
	v_permlane32_swap_b32_e32 v67, v71
	v_permlane32_swap_b32_e32 v72, v76
	v_permlane32_swap_b32_e32 v73, v77
	v_permlane32_swap_b32_e32 v74, v78
	v_permlane32_swap_b32_e32 v75, v79
	v_permlane32_swap_b32_e32 v0, v4
	v_permlane32_swap_b32_e32 v1, v5
	v_permlane32_swap_b32_e32 v2, v6
	v_permlane32_swap_b32_e32 v3, v7
	v_permlane32_swap_b32_e32 v8, v12
	v_permlane32_swap_b32_e32 v9, v13
	v_permlane32_swap_b32_e32 v10, v14
	v_permlane32_swap_b32_e32 v11, v15
	s_waitcnt vmcnt(0)
	s_movk_i32 s8, 0x2400
	s_waitcnt vmcnt(0)
	v_and_b32_e32 v132, 0xffffffc0, v181
	v_mul_lo_u32 v129, v237, s8
	v_lshlrev_b32_e32 v130, 2, v238
	v_lshl_add_u32 v156, s7, 8, v132
	v_mul_u32_u24_e32 v132, 0x110, v183
	v_or_b32_e32 v131, v129, v130
	v_lshlrev_b32_e32 v132, 2, v132
	v_add_u32_e32 v131, v131, v132
	v_add3_u32 v132, v129, v132, v130
	v_readlane_b32 s8, v253, 36
	v_lshlrev_b32_e32 v128, 2, v181
	v_add_u32_e32 v133, 0x800, v131
	v_add_u32_e32 v134, 0x800, v132
	v_lshrrev_b32_e32 v155, 4, v239
	v_readlane_b32 s12, v253, 40
	v_readlane_b32 s13, v253, 41
	v_readlane_b32 s14, v253, 42
	v_readlane_b32 s15, v253, 43
	v_readlane_b32 s16, v253, 44
	v_readlane_b32 s17, v253, 45
	v_readlane_b32 s18, v253, 46
	v_readlane_b32 s19, v253, 47
	v_and_b32_e32 v128, 60, v128
	ds_write2_b32 v131, v112, v113 offset1:68
	ds_write2_b32 v132, v96, v97 offset0:32 offset1:100
	ds_write2_b32 v131, v114, v115 offset0:136 offset1:204
	ds_write2_b32 v132, v98, v99 offset0:168 offset1:236
	ds_write2_b32 v133, v116, v117 offset0:32 offset1:100
	ds_write2_b32 v134, v100, v101 offset0:64 offset1:132
	ds_write2_b32 v133, v118, v119 offset0:168 offset1:236
	v_or_b32_e32 v100, v156, v155
	v_readlane_b32 s20, v253, 48
	v_readlane_b32 s21, v253, 49
	v_readlane_b32 s22, v253, 50
	v_readlane_b32 s23, v253, 51
	s_mov_b64 s[12:13], s[16:17]
	v_lshl_or_b32 v144, v128, 2, v129
	v_lshl_or_b32 v128, s6, 7, v128
	s_movk_i32 s6, 0x110
	v_cmp_gt_i32_e32 vcc, s39, v100
	v_add_u32_e32 v96, 0xffff8000, v100
	v_ashrrev_i32_e32 v97, 31, v100
	s_mov_b64 s[14:15], s[18:19]
	v_mad_u32_u24 v130, v155, s6, v144
	v_cndmask_b32_e32 v97, 0, v97, vcc
	v_cndmask_b32_e32 v96, v96, v100, vcc
	v_mov_b32_e32 v144, s63
	v_mov_b32_e32 v145, s15
	v_mov_b32_e32 v146, s62
	v_mov_b32_e32 v147, s14
	v_min_i32_e32 v100, 0x8000, v100
	v_add_u32_e32 v135, 0xa00, v132
	v_add_u32_e32 v136, 0x1000, v131
	v_add_u32_e32 v137, 0x1000, v132
	v_add_u32_e32 v138, 0x1200, v131
	v_add_u32_e32 v139, 0x1200, v132
	v_add_u32_e32 v140, 0x1800, v131
	v_add_u32_e32 v141, 0x1800, v132
	v_add_u32_e32 v142, 0x1a00, v131
	v_add_u32_e32 v143, 0x1c00, v132
	v_ashrrev_i32_e32 v129, 31, v128
	v_cndmask_b32_e32 v99, v144, v145, vcc
	v_cndmask_b32_e32 v98, v146, v147, vcc
	v_lshlrev_b64 v[96:97], 12, v[96:97]
	v_ashrrev_i32_e32 v100, 12, v100
	ds_write2_b32 v135, v102, v103 offset0:72 offset1:140
	ds_write2_b32 v136, v120, v121 offset0:64 offset1:132
	ds_write2_b32 v137, v104, v105 offset0:96 offset1:164
	ds_write2_b32 v138, v122, v123 offset0:72 offset1:140
	ds_write2_b32 v139, v106, v107 offset0:104 offset1:172
	ds_write2_b32 v140, v124, v125 offset0:96 offset1:164
	ds_write2_b32 v141, v108, v109 offset0:128 offset1:196
	ds_write2_b32 v142, v126, v127 offset0:104 offset1:172
	ds_write2_b32 v143, v110, v111 offset0:8 offset1:76
	v_lshl_add_u64 v[98:99], v[98:99], 0, v[96:97]
	v_lshlrev_b64 v[96:97], 2, v[128:129]
	v_mul_hi_i32_i24_e32 v101, 0x6000, v100
	v_mul_i32_i24_e32 v100, 0x6000, v100
	s_waitcnt lgkmcnt(0)
	v_lshl_add_u64 v[98:99], v[98:99], 0, v[96:97]
	v_lshl_add_u64 v[100:101], s[0:1], 0, v[100:101]
	v_lshl_add_u64 v[100:101], v[100:101], 0, v[96:97]
	ds_read_b128 v[102:105], v130
	global_load_dwordx4 v[106:109], v[98:99], off
	global_load_dwordx4 v[110:113], v[100:101], off
	v_or_b32_e32 v148, 4, v155
	v_or_b32_e32 v149, 8, v155
	v_or_b32_e32 v150, 12, v155
	v_or_b32_e32 v151, 16, v155
	v_or_b32_e32 v152, 20, v155
	v_or_b32_e32 v153, 24, v155
	v_or_b32_e32 v154, 28, v155
	v_or_b32_e32 v157, v156, v154
	v_readlane_b32 s6, v254, 11
	s_add_i32 s2, s2, s6
	s_cmp_lt_i32 s2, s26
	v_readlane_b32 s9, v253, 37
	v_readlane_b32 s10, v253, 38
	v_readlane_b32 s11, v253, 39
	s_mov_b64 s[16:17], s[20:21]
	s_mov_b64 s[18:19], s[22:23]
	s_waitcnt vmcnt(0) lgkmcnt(0)
	v_pk_fma_f32 v[102:103], v[102:103], v[110:111], v[106:107]
	v_pk_fma_f32 v[104:105], v[104:105], v[112:113], v[108:109]
	v_or_b32_e32 v106, v156, v148
	global_store_dwordx4 v[98:99], v[102:105], off
	v_cmp_gt_i32_e32 vcc, s39, v106
	s_nop 0
	v_ashrrev_i32_e32 v102, 31, v106
	v_add_u32_e32 v104, 0xffff8000, v106
	v_cndmask_b32_e32 v103, 0, v102, vcc
	v_cndmask_b32_e32 v102, v104, v106, vcc
	v_cndmask_b32_e32 v105, v144, v145, vcc
	v_cndmask_b32_e32 v104, v146, v147, vcc
	v_lshlrev_b64 v[102:103], 12, v[102:103]
	v_lshl_add_u64 v[102:103], v[104:105], 0, v[102:103]
	v_min_i32_e32 v104, 0x8000, v106
	v_ashrrev_i32_e32 v104, 12, v104
	v_mul_hi_i32_i24_e32 v105, 0x6000, v104
	v_mul_i32_i24_e32 v104, 0x6000, v104
	v_lshl_add_u64 v[102:103], v[102:103], 0, v[96:97]
	v_lshl_add_u64 v[104:105], s[0:1], 0, v[104:105]
	v_lshl_add_u64 v[104:105], v[104:105], 0, v[96:97]
	ds_read_b128 v[106:109], v130 offset:1088
	global_load_dwordx4 v[110:113], v[102:103], off
	global_load_dwordx4 v[114:117], v[104:105], off
	s_waitcnt vmcnt(0) lgkmcnt(0)
	v_pk_fma_f32 v[106:107], v[106:107], v[114:115], v[110:111]
	v_pk_fma_f32 v[108:109], v[108:109], v[116:117], v[112:113]
	v_or_b32_e32 v110, v156, v149
	global_store_dwordx4 v[102:103], v[106:109], off
	v_cmp_gt_i32_e32 vcc, s39, v110
	s_nop 0
	v_ashrrev_i32_e32 v106, 31, v110
	v_add_u32_e32 v108, 0xffff8000, v110
	v_cndmask_b32_e32 v107, 0, v106, vcc
	v_cndmask_b32_e32 v106, v108, v110, vcc
	v_cndmask_b32_e32 v109, v144, v145, vcc
	v_cndmask_b32_e32 v108, v146, v147, vcc
	v_lshlrev_b64 v[106:107], 12, v[106:107]
	v_lshl_add_u64 v[106:107], v[108:109], 0, v[106:107]
	v_min_i32_e32 v108, 0x8000, v110
	v_ashrrev_i32_e32 v108, 12, v108
	v_mul_hi_i32_i24_e32 v109, 0x6000, v108
	v_mul_i32_i24_e32 v108, 0x6000, v108
	v_lshl_add_u64 v[106:107], v[106:107], 0, v[96:97]
	v_lshl_add_u64 v[108:109], s[0:1], 0, v[108:109]
	v_lshl_add_u64 v[108:109], v[108:109], 0, v[96:97]
	ds_read_b128 v[110:113], v130 offset:2176
	global_load_dwordx4 v[114:117], v[106:107], off
	global_load_dwordx4 v[118:121], v[108:109], off
	s_waitcnt vmcnt(0) lgkmcnt(0)
	v_pk_fma_f32 v[110:111], v[110:111], v[118:119], v[114:115]
	v_pk_fma_f32 v[112:113], v[112:113], v[120:121], v[116:117]
	v_or_b32_e32 v114, v156, v150
	global_store_dwordx4 v[106:107], v[110:113], off
	v_cmp_gt_i32_e32 vcc, s39, v114
	s_nop 0
	v_ashrrev_i32_e32 v110, 31, v114
	v_add_u32_e32 v112, 0xffff8000, v114
	v_cndmask_b32_e32 v111, 0, v110, vcc
	v_cndmask_b32_e32 v110, v112, v114, vcc
	v_cndmask_b32_e32 v113, v144, v145, vcc
	v_cndmask_b32_e32 v112, v146, v147, vcc
	v_lshlrev_b64 v[110:111], 12, v[110:111]
	v_lshl_add_u64 v[110:111], v[112:113], 0, v[110:111]
	v_min_i32_e32 v112, 0x8000, v114
	v_ashrrev_i32_e32 v112, 12, v112
	v_mul_hi_i32_i24_e32 v113, 0x6000, v112
	v_mul_i32_i24_e32 v112, 0x6000, v112
	v_lshl_add_u64 v[110:111], v[110:111], 0, v[96:97]
	v_lshl_add_u64 v[112:113], s[0:1], 0, v[112:113]
	v_lshl_add_u64 v[112:113], v[112:113], 0, v[96:97]
	ds_read_b128 v[114:117], v130 offset:3264
	global_load_dwordx4 v[118:121], v[110:111], off
	global_load_dwordx4 v[122:125], v[112:113], off
	s_waitcnt vmcnt(0) lgkmcnt(0)
	v_pk_fma_f32 v[114:115], v[114:115], v[122:123], v[118:119]
	v_pk_fma_f32 v[116:117], v[116:117], v[124:125], v[120:121]
	v_or_b32_e32 v118, v156, v151
	global_store_dwordx4 v[110:111], v[114:117], off
	v_cmp_gt_i32_e32 vcc, s39, v118
	s_nop 0
	v_ashrrev_i32_e32 v114, 31, v118
	v_add_u32_e32 v116, 0xffff8000, v118
	v_cndmask_b32_e32 v115, 0, v114, vcc
	v_cndmask_b32_e32 v114, v116, v118, vcc
	v_cndmask_b32_e32 v117, v144, v145, vcc
	v_cndmask_b32_e32 v116, v146, v147, vcc
	v_lshlrev_b64 v[114:115], 12, v[114:115]
	v_lshl_add_u64 v[114:115], v[116:117], 0, v[114:115]
	v_min_i32_e32 v116, 0x8000, v118
	v_ashrrev_i32_e32 v116, 12, v116
	v_mul_hi_i32_i24_e32 v117, 0x6000, v116
	v_mul_i32_i24_e32 v116, 0x6000, v116
	v_lshl_add_u64 v[114:115], v[114:115], 0, v[96:97]
	v_lshl_add_u64 v[116:117], s[0:1], 0, v[116:117]
	v_lshl_add_u64 v[116:117], v[116:117], 0, v[96:97]
	ds_read_b128 v[118:121], v130 offset:4352
	global_load_dwordx4 v[122:125], v[114:115], off
	global_load_dwordx4 v[126:129], v[116:117], off
	s_waitcnt vmcnt(0) lgkmcnt(0)
	v_pk_fma_f32 v[118:119], v[118:119], v[126:127], v[122:123]
	v_pk_fma_f32 v[120:121], v[120:121], v[128:129], v[124:125]
	v_or_b32_e32 v122, v156, v152
	global_store_dwordx4 v[114:115], v[118:121], off
	v_cmp_gt_i32_e32 vcc, s39, v122
	s_nop 0
	v_ashrrev_i32_e32 v118, 31, v122
	v_add_u32_e32 v120, 0xffff8000, v122
	v_cndmask_b32_e32 v119, 0, v118, vcc
	v_cndmask_b32_e32 v118, v120, v122, vcc
	v_cndmask_b32_e32 v121, v144, v145, vcc
	v_cndmask_b32_e32 v120, v146, v147, vcc
	v_lshlrev_b64 v[118:119], 12, v[118:119]
	v_lshl_add_u64 v[118:119], v[120:121], 0, v[118:119]
	v_min_i32_e32 v120, 0x8000, v122
	v_ashrrev_i32_e32 v120, 12, v120
	v_mul_hi_i32_i24_e32 v121, 0x6000, v120
	v_mul_i32_i24_e32 v120, 0x6000, v120
	v_lshl_add_u64 v[118:119], v[118:119], 0, v[96:97]
	v_lshl_add_u64 v[120:121], s[0:1], 0, v[120:121]
	v_lshl_add_u64 v[120:121], v[120:121], 0, v[96:97]
	ds_read_b128 v[122:125], v130 offset:5440
	global_load_dwordx4 v[126:129], v[118:119], off
	global_load_dwordx4 v[158:161], v[120:121], off
	s_waitcnt vmcnt(0) lgkmcnt(0)
	v_pk_fma_f32 v[122:123], v[122:123], v[158:159], v[126:127]
	v_pk_fma_f32 v[124:125], v[124:125], v[160:161], v[128:129]
	v_or_b32_e32 v126, v156, v153
	global_store_dwordx4 v[118:119], v[122:125], off
	v_cmp_gt_i32_e32 vcc, s39, v126
	s_nop 0
	v_ashrrev_i32_e32 v122, 31, v126
	v_add_u32_e32 v124, 0xffff8000, v126
	v_cndmask_b32_e32 v123, 0, v122, vcc
	v_cndmask_b32_e32 v122, v124, v126, vcc
	v_cndmask_b32_e32 v125, v144, v145, vcc
	v_cndmask_b32_e32 v124, v146, v147, vcc
	v_lshlrev_b64 v[122:123], 12, v[122:123]
	v_lshl_add_u64 v[122:123], v[124:125], 0, v[122:123]
	v_min_i32_e32 v124, 0x8000, v126
	v_ashrrev_i32_e32 v124, 12, v124
	v_mul_hi_i32_i24_e32 v125, 0x6000, v124
	v_mul_i32_i24_e32 v124, 0x6000, v124
	v_lshl_add_u64 v[122:123], v[122:123], 0, v[96:97]
	v_lshl_add_u64 v[124:125], s[0:1], 0, v[124:125]
	v_lshl_add_u64 v[124:125], v[124:125], 0, v[96:97]
	ds_read_b128 v[126:129], v130 offset:6528
	global_load_dwordx4 v[158:161], v[122:123], off
	global_load_dwordx4 v[162:165], v[124:125], off
	v_cmp_gt_i32_e32 vcc, s39, v157
	s_waitcnt vmcnt(0) lgkmcnt(0)
	v_pk_fma_f32 v[126:127], v[126:127], v[162:163], v[158:159]
	v_pk_fma_f32 v[128:129], v[128:129], v[164:165], v[160:161]
	global_store_dwordx4 v[122:123], v[126:129], off
	ds_read_b128 v[158:161], v130 offset:7616
	s_nop 0
	v_ashrrev_i32_e32 v126, 31, v157
	v_add_u32_e32 v128, 0xffff8000, v157
	v_cndmask_b32_e32 v127, 0, v126, vcc
	v_cndmask_b32_e32 v126, v128, v157, vcc
	v_cndmask_b32_e32 v129, v144, v145, vcc
	v_cndmask_b32_e32 v128, v146, v147, vcc
	v_lshlrev_b64 v[126:127], 12, v[126:127]
	v_lshl_add_u64 v[126:127], v[128:129], 0, v[126:127]
	v_min_i32_e32 v128, 0x8000, v157
	v_ashrrev_i32_e32 v128, 12, v128
	v_mul_hi_i32_i24_e32 v129, 0x6000, v128
	v_mul_i32_i24_e32 v128, 0x6000, v128
	v_lshl_add_u64 v[126:127], v[126:127], 0, v[96:97]
	v_lshl_add_u64 v[128:129], s[0:1], 0, v[128:129]
	v_lshl_add_u64 v[128:129], v[128:129], 0, v[96:97]
	global_load_dwordx4 v[162:165], v[126:127], off
	global_load_dwordx4 v[166:169], v[128:129], off
	s_waitcnt vmcnt(0) lgkmcnt(0)
	v_pk_fma_f32 v[158:159], v[158:159], v[166:167], v[162:163]
	v_pk_fma_f32 v[160:161], v[160:161], v[168:169], v[164:165]
	global_store_dwordx4 v[126:127], v[158:161], off
	s_waitcnt lgkmcnt(0)
	ds_write2_b32 v131, v80, v81 offset1:68
	ds_write2_b32 v132, v64, v65 offset0:32 offset1:100
	ds_write2_b32 v131, v82, v83 offset0:136 offset1:204
	ds_write2_b32 v132, v66, v67 offset0:168 offset1:236
	ds_write2_b32 v133, v84, v85 offset0:32 offset1:100
	ds_write2_b32 v134, v68, v69 offset0:64 offset1:132
	ds_write2_b32 v133, v86, v87 offset0:168 offset1:236
	ds_write2_b32 v135, v70, v71 offset0:72 offset1:140
	ds_write2_b32 v136, v88, v89 offset0:64 offset1:132
	ds_write2_b32 v137, v72, v73 offset0:96 offset1:164
	ds_write2_b32 v138, v90, v91 offset0:72 offset1:140
	ds_write2_b32 v139, v74, v75 offset0:104 offset1:172
	ds_write2_b32 v140, v92, v93 offset0:96 offset1:164
	ds_write2_b32 v141, v76, v77 offset0:128 offset1:196
	ds_write2_b32 v142, v94, v95 offset0:104 offset1:172
	ds_write2_b32 v143, v78, v79 offset0:8 offset1:76
	s_waitcnt lgkmcnt(0)
	ds_read_b128 v[64:67], v130
	global_load_dwordx4 v[68:71], v[98:99], off offset:256
	global_load_dwordx4 v[72:75], v[100:101], off offset:256
	s_waitcnt vmcnt(0) lgkmcnt(0)
	v_pk_fma_f32 v[64:65], v[64:65], v[72:73], v[68:69]
	v_pk_fma_f32 v[66:67], v[66:67], v[74:75], v[70:71]
	global_store_dwordx4 v[98:99], v[64:67], off offset:256
	ds_read_b128 v[64:67], v130 offset:1088
	global_load_dwordx4 v[68:71], v[102:103], off offset:256
	global_load_dwordx4 v[72:75], v[104:105], off offset:256
	s_waitcnt vmcnt(0) lgkmcnt(0)
	v_pk_fma_f32 v[64:65], v[64:65], v[72:73], v[68:69]
	v_pk_fma_f32 v[66:67], v[66:67], v[74:75], v[70:71]
	global_store_dwordx4 v[102:103], v[64:67], off offset:256
	ds_read_b128 v[64:67], v130 offset:2176
	global_load_dwordx4 v[68:71], v[106:107], off offset:256
	global_load_dwordx4 v[72:75], v[108:109], off offset:256
	s_waitcnt vmcnt(0) lgkmcnt(0)
	v_pk_fma_f32 v[64:65], v[64:65], v[72:73], v[68:69]
	v_pk_fma_f32 v[66:67], v[66:67], v[74:75], v[70:71]
	global_store_dwordx4 v[106:107], v[64:67], off offset:256
	ds_read_b128 v[64:67], v130 offset:3264
	global_load_dwordx4 v[68:71], v[110:111], off offset:256
	global_load_dwordx4 v[72:75], v[112:113], off offset:256
	s_waitcnt vmcnt(0) lgkmcnt(0)
	v_pk_fma_f32 v[64:65], v[64:65], v[72:73], v[68:69]
	v_pk_fma_f32 v[66:67], v[66:67], v[74:75], v[70:71]
	global_store_dwordx4 v[110:111], v[64:67], off offset:256
	ds_read_b128 v[64:67], v130 offset:4352
	global_load_dwordx4 v[68:71], v[114:115], off offset:256
	global_load_dwordx4 v[72:75], v[116:117], off offset:256
	s_waitcnt vmcnt(0) lgkmcnt(0)
	v_pk_fma_f32 v[64:65], v[64:65], v[72:73], v[68:69]
	v_pk_fma_f32 v[66:67], v[66:67], v[74:75], v[70:71]
	global_store_dwordx4 v[114:115], v[64:67], off offset:256
	ds_read_b128 v[64:67], v130 offset:5440
	global_load_dwordx4 v[68:71], v[118:119], off offset:256
	global_load_dwordx4 v[72:75], v[120:121], off offset:256
	s_waitcnt vmcnt(0) lgkmcnt(0)
	v_pk_fma_f32 v[64:65], v[64:65], v[72:73], v[68:69]
	v_pk_fma_f32 v[66:67], v[66:67], v[74:75], v[70:71]
	global_store_dwordx4 v[118:119], v[64:67], off offset:256
	ds_read_b128 v[64:67], v130 offset:6528
	global_load_dwordx4 v[68:71], v[122:123], off offset:256
	global_load_dwordx4 v[72:75], v[124:125], off offset:256
	s_waitcnt vmcnt(0) lgkmcnt(0)
	v_pk_fma_f32 v[64:65], v[64:65], v[72:73], v[68:69]
	v_pk_fma_f32 v[66:67], v[66:67], v[74:75], v[70:71]
	global_store_dwordx4 v[122:123], v[64:67], off offset:256
	ds_read_b128 v[64:67], v130 offset:7616
	global_load_dwordx4 v[68:71], v[126:127], off offset:256
	global_load_dwordx4 v[72:75], v[128:129], off offset:256
	s_waitcnt vmcnt(0) lgkmcnt(0)
	v_pk_fma_f32 v[64:65], v[64:65], v[72:73], v[68:69]
	v_pk_fma_f32 v[66:67], v[66:67], v[74:75], v[70:71]
	global_store_dwordx4 v[126:127], v[64:67], off offset:256
	s_waitcnt lgkmcnt(0)
	ds_write2_b32 v131, v48, v49 offset1:68
	ds_write2_b32 v132, v32, v33 offset0:32 offset1:100
	ds_write2_b32 v131, v50, v51 offset0:136 offset1:204
	ds_write2_b32 v132, v34, v35 offset0:168 offset1:236
	ds_write2_b32 v133, v52, v53 offset0:32 offset1:100
	ds_write2_b32 v134, v36, v37 offset0:64 offset1:132
	ds_write2_b32 v133, v54, v55 offset0:168 offset1:236
	ds_write2_b32 v135, v38, v39 offset0:72 offset1:140
	ds_write2_b32 v136, v56, v57 offset0:64 offset1:132
	ds_write2_b32 v137, v40, v41 offset0:96 offset1:164
	ds_write2_b32 v138, v58, v59 offset0:72 offset1:140
	ds_write2_b32 v139, v42, v43 offset0:104 offset1:172
	ds_write2_b32 v140, v60, v61 offset0:96 offset1:164
	ds_write2_b32 v141, v44, v45 offset0:128 offset1:196
	ds_write2_b32 v142, v62, v63 offset0:104 offset1:172
	ds_write2_b32 v143, v46, v47 offset0:8 offset1:76
	v_or_b32_e32 v64, 32, v156
	v_or_b32_e32 v36, v64, v155
	v_cmp_gt_i32_e32 vcc, s39, v36
	v_ashrrev_i32_e32 v32, 31, v36
	v_add_u32_e32 v34, 0xffff8000, v36
	v_cndmask_b32_e32 v33, 0, v32, vcc
	v_cndmask_b32_e32 v32, v34, v36, vcc
	v_cndmask_b32_e32 v35, v144, v145, vcc
	v_cndmask_b32_e32 v34, v146, v147, vcc
	v_lshlrev_b64 v[32:33], 12, v[32:33]
	v_lshl_add_u64 v[32:33], v[34:35], 0, v[32:33]
	v_min_i32_e32 v34, 0x8000, v36
	v_ashrrev_i32_e32 v34, 12, v34
	v_mul_hi_i32_i24_e32 v35, 0x6000, v34
	v_mul_i32_i24_e32 v34, 0x6000, v34
	s_waitcnt lgkmcnt(0)
	v_lshl_add_u64 v[32:33], v[32:33], 0, v[96:97]
	v_lshl_add_u64 v[34:35], s[0:1], 0, v[34:35]
	v_lshl_add_u64 v[34:35], v[34:35], 0, v[96:97]
	ds_read_b128 v[36:39], v130
	global_load_dwordx4 v[40:43], v[32:33], off
	global_load_dwordx4 v[44:47], v[34:35], off
	s_waitcnt vmcnt(0) lgkmcnt(0)
	v_pk_fma_f32 v[36:37], v[36:37], v[44:45], v[40:41]
	v_pk_fma_f32 v[38:39], v[38:39], v[46:47], v[42:43]
	v_or_b32_e32 v40, v64, v148
	global_store_dwordx4 v[32:33], v[36:39], off
	v_cmp_gt_i32_e32 vcc, s39, v40
	s_nop 0
	v_ashrrev_i32_e32 v36, 31, v40
	v_add_u32_e32 v38, 0xffff8000, v40
	v_cndmask_b32_e32 v37, 0, v36, vcc
	v_cndmask_b32_e32 v36, v38, v40, vcc
	v_cndmask_b32_e32 v39, v144, v145, vcc
	v_cndmask_b32_e32 v38, v146, v147, vcc
	v_lshlrev_b64 v[36:37], 12, v[36:37]
	v_lshl_add_u64 v[36:37], v[38:39], 0, v[36:37]
	v_min_i32_e32 v38, 0x8000, v40
	v_ashrrev_i32_e32 v38, 12, v38
	v_mul_hi_i32_i24_e32 v39, 0x6000, v38
	v_mul_i32_i24_e32 v38, 0x6000, v38
	v_lshl_add_u64 v[36:37], v[36:37], 0, v[96:97]
	v_lshl_add_u64 v[38:39], s[0:1], 0, v[38:39]
	v_lshl_add_u64 v[38:39], v[38:39], 0, v[96:97]
	ds_read_b128 v[40:43], v130 offset:1088
	global_load_dwordx4 v[44:47], v[36:37], off
	global_load_dwordx4 v[48:51], v[38:39], off
	s_waitcnt vmcnt(0) lgkmcnt(0)
	v_pk_fma_f32 v[40:41], v[40:41], v[48:49], v[44:45]
	v_pk_fma_f32 v[42:43], v[42:43], v[50:51], v[46:47]
	v_or_b32_e32 v44, v64, v149
	global_store_dwordx4 v[36:37], v[40:43], off
	v_cmp_gt_i32_e32 vcc, s39, v44
	s_nop 0
	v_ashrrev_i32_e32 v40, 31, v44
	v_add_u32_e32 v42, 0xffff8000, v44
	v_cndmask_b32_e32 v41, 0, v40, vcc
	v_cndmask_b32_e32 v40, v42, v44, vcc
	v_cndmask_b32_e32 v43, v144, v145, vcc
	v_cndmask_b32_e32 v42, v146, v147, vcc
	v_lshlrev_b64 v[40:41], 12, v[40:41]
	v_lshl_add_u64 v[40:41], v[42:43], 0, v[40:41]
	v_min_i32_e32 v42, 0x8000, v44
	v_ashrrev_i32_e32 v42, 12, v42
	v_mul_hi_i32_i24_e32 v43, 0x6000, v42
	v_mul_i32_i24_e32 v42, 0x6000, v42
	v_lshl_add_u64 v[40:41], v[40:41], 0, v[96:97]
	v_lshl_add_u64 v[42:43], s[0:1], 0, v[42:43]
	v_lshl_add_u64 v[42:43], v[42:43], 0, v[96:97]
	ds_read_b128 v[44:47], v130 offset:2176
	global_load_dwordx4 v[48:51], v[40:41], off
	global_load_dwordx4 v[52:55], v[42:43], off
	s_waitcnt vmcnt(0) lgkmcnt(0)
	v_pk_fma_f32 v[44:45], v[44:45], v[52:53], v[48:49]
	v_pk_fma_f32 v[46:47], v[46:47], v[54:55], v[50:51]
	v_or_b32_e32 v48, v64, v150
	global_store_dwordx4 v[40:41], v[44:47], off
	v_cmp_gt_i32_e32 vcc, s39, v48
	s_nop 0
	v_ashrrev_i32_e32 v44, 31, v48
	v_add_u32_e32 v46, 0xffff8000, v48
	v_cndmask_b32_e32 v45, 0, v44, vcc
	v_cndmask_b32_e32 v44, v46, v48, vcc
	v_cndmask_b32_e32 v47, v144, v145, vcc
	v_cndmask_b32_e32 v46, v146, v147, vcc
	v_lshlrev_b64 v[44:45], 12, v[44:45]
	v_lshl_add_u64 v[44:45], v[46:47], 0, v[44:45]
	v_min_i32_e32 v46, 0x8000, v48
	v_ashrrev_i32_e32 v46, 12, v46
	v_mul_hi_i32_i24_e32 v47, 0x6000, v46
	v_mul_i32_i24_e32 v46, 0x6000, v46
	v_lshl_add_u64 v[44:45], v[44:45], 0, v[96:97]
	v_lshl_add_u64 v[46:47], s[0:1], 0, v[46:47]
	v_lshl_add_u64 v[46:47], v[46:47], 0, v[96:97]
	ds_read_b128 v[48:51], v130 offset:3264
	global_load_dwordx4 v[52:55], v[44:45], off
	global_load_dwordx4 v[56:59], v[46:47], off
	s_waitcnt vmcnt(0) lgkmcnt(0)
	v_pk_fma_f32 v[48:49], v[48:49], v[56:57], v[52:53]
	v_pk_fma_f32 v[50:51], v[50:51], v[58:59], v[54:55]
	v_or_b32_e32 v52, v64, v151
	global_store_dwordx4 v[44:45], v[48:51], off
	v_cmp_gt_i32_e32 vcc, s39, v52
	s_nop 0
	v_ashrrev_i32_e32 v48, 31, v52
	v_add_u32_e32 v50, 0xffff8000, v52
	v_cndmask_b32_e32 v49, 0, v48, vcc
	v_cndmask_b32_e32 v48, v50, v52, vcc
	v_cndmask_b32_e32 v51, v144, v145, vcc
	v_cndmask_b32_e32 v50, v146, v147, vcc
	v_lshlrev_b64 v[48:49], 12, v[48:49]
	v_lshl_add_u64 v[48:49], v[50:51], 0, v[48:49]
	v_min_i32_e32 v50, 0x8000, v52
	v_ashrrev_i32_e32 v50, 12, v50
	v_mul_hi_i32_i24_e32 v51, 0x6000, v50
	v_mul_i32_i24_e32 v50, 0x6000, v50
	v_lshl_add_u64 v[48:49], v[48:49], 0, v[96:97]
	v_lshl_add_u64 v[50:51], s[0:1], 0, v[50:51]
	v_lshl_add_u64 v[50:51], v[50:51], 0, v[96:97]
	ds_read_b128 v[52:55], v130 offset:4352
	global_load_dwordx4 v[56:59], v[48:49], off
	global_load_dwordx4 v[60:63], v[50:51], off
	s_waitcnt vmcnt(0) lgkmcnt(0)
	v_pk_fma_f32 v[52:53], v[52:53], v[60:61], v[56:57]
	v_pk_fma_f32 v[54:55], v[54:55], v[62:63], v[58:59]
	v_or_b32_e32 v56, v64, v152
	global_store_dwordx4 v[48:49], v[52:55], off
	v_cmp_gt_i32_e32 vcc, s39, v56
	s_nop 0
	v_ashrrev_i32_e32 v52, 31, v56
	v_add_u32_e32 v54, 0xffff8000, v56
	v_cndmask_b32_e32 v53, 0, v52, vcc
	v_cndmask_b32_e32 v52, v54, v56, vcc
	v_cndmask_b32_e32 v55, v144, v145, vcc
	v_cndmask_b32_e32 v54, v146, v147, vcc
	v_lshlrev_b64 v[52:53], 12, v[52:53]
	v_lshl_add_u64 v[52:53], v[54:55], 0, v[52:53]
	v_min_i32_e32 v54, 0x8000, v56
	v_ashrrev_i32_e32 v54, 12, v54
	v_mul_hi_i32_i24_e32 v55, 0x6000, v54
	v_mul_i32_i24_e32 v54, 0x6000, v54
	v_lshl_add_u64 v[52:53], v[52:53], 0, v[96:97]
	v_lshl_add_u64 v[54:55], s[0:1], 0, v[54:55]
	v_lshl_add_u64 v[54:55], v[54:55], 0, v[96:97]
	ds_read_b128 v[56:59], v130 offset:5440
	global_load_dwordx4 v[60:63], v[52:53], off
	global_load_dwordx4 v[66:69], v[54:55], off
	s_waitcnt vmcnt(0) lgkmcnt(0)
	v_pk_fma_f32 v[56:57], v[56:57], v[66:67], v[60:61]
	v_pk_fma_f32 v[58:59], v[58:59], v[68:69], v[62:63]
	v_or_b32_e32 v60, v64, v153
	global_store_dwordx4 v[52:53], v[56:59], off
	v_cmp_gt_i32_e32 vcc, s39, v60
	v_or_b32_e32 v64, v64, v154
	v_ashrrev_i32_e32 v56, 31, v60
	v_add_u32_e32 v58, 0xffff8000, v60
	v_cndmask_b32_e32 v57, 0, v56, vcc
	v_cndmask_b32_e32 v56, v58, v60, vcc
	v_cndmask_b32_e32 v59, v144, v145, vcc
	v_cndmask_b32_e32 v58, v146, v147, vcc
	v_lshlrev_b64 v[56:57], 12, v[56:57]
	v_lshl_add_u64 v[56:57], v[58:59], 0, v[56:57]
	v_min_i32_e32 v58, 0x8000, v60
	v_ashrrev_i32_e32 v58, 12, v58
	v_mul_hi_i32_i24_e32 v59, 0x6000, v58
	v_mul_i32_i24_e32 v58, 0x6000, v58
	v_lshl_add_u64 v[56:57], v[56:57], 0, v[96:97]
	v_lshl_add_u64 v[58:59], s[0:1], 0, v[58:59]
	v_lshl_add_u64 v[58:59], v[58:59], 0, v[96:97]
	ds_read_b128 v[60:63], v130 offset:6528
	global_load_dwordx4 v[66:69], v[56:57], off
	global_load_dwordx4 v[70:73], v[58:59], off
	v_cmp_gt_i32_e32 vcc, s39, v64
	s_waitcnt vmcnt(0) lgkmcnt(0)
	v_pk_fma_f32 v[60:61], v[60:61], v[70:71], v[66:67]
	v_pk_fma_f32 v[62:63], v[62:63], v[72:73], v[68:69]
	global_store_dwordx4 v[56:57], v[60:63], off
	s_nop 1
	v_ashrrev_i32_e32 v60, 31, v64
	v_add_u32_e32 v62, 0xffff8000, v64
	v_cndmask_b32_e32 v61, 0, v60, vcc
	v_cndmask_b32_e32 v60, v62, v64, vcc
	v_cndmask_b32_e32 v63, v144, v145, vcc
	v_cndmask_b32_e32 v62, v146, v147, vcc
	v_lshlrev_b64 v[60:61], 12, v[60:61]
	v_lshl_add_u64 v[60:61], v[62:63], 0, v[60:61]
	v_min_i32_e32 v62, 0x8000, v64
	v_ashrrev_i32_e32 v62, 12, v62
	v_mul_hi_i32_i24_e32 v63, 0x6000, v62
	v_mul_i32_i24_e32 v62, 0x6000, v62
	v_lshl_add_u64 v[60:61], v[60:61], 0, v[96:97]
	v_lshl_add_u64 v[62:63], s[0:1], 0, v[62:63]
	v_lshl_add_u64 v[62:63], v[62:63], 0, v[96:97]
	ds_read_b128 v[64:67], v130 offset:7616
	global_load_dwordx4 v[68:71], v[60:61], off
	global_load_dwordx4 v[72:75], v[62:63], off
	s_waitcnt vmcnt(0) lgkmcnt(0)
	v_pk_fma_f32 v[64:65], v[64:65], v[72:73], v[68:69]
	v_pk_fma_f32 v[66:67], v[66:67], v[74:75], v[70:71]
	global_store_dwordx4 v[60:61], v[64:67], off
	s_waitcnt lgkmcnt(0)
	ds_write2_b32 v131, v16, v17 offset1:68
	ds_write2_b32 v132, v0, v1 offset0:32 offset1:100
	ds_write2_b32 v131, v18, v19 offset0:136 offset1:204
	ds_write2_b32 v132, v2, v3 offset0:168 offset1:236
	ds_write2_b32 v133, v20, v21 offset0:32 offset1:100
	ds_write2_b32 v134, v4, v5 offset0:64 offset1:132
	ds_write2_b32 v133, v22, v23 offset0:168 offset1:236
	ds_write2_b32 v135, v6, v7 offset0:72 offset1:140
	ds_write2_b32 v136, v24, v25 offset0:64 offset1:132
	ds_write2_b32 v137, v8, v9 offset0:96 offset1:164
	ds_write2_b32 v138, v26, v27 offset0:72 offset1:140
	ds_write2_b32 v139, v10, v11 offset0:104 offset1:172
	ds_write2_b32 v140, v28, v29 offset0:96 offset1:164
	ds_write2_b32 v141, v12, v13 offset0:128 offset1:196
	ds_write2_b32 v142, v30, v31 offset0:104 offset1:172
	ds_write2_b32 v143, v14, v15 offset0:8 offset1:76
	s_waitcnt lgkmcnt(0)
	ds_read_b128 v[0:3], v130
	global_load_dwordx4 v[4:7], v[32:33], off offset:256
	global_load_dwordx4 v[8:11], v[34:35], off offset:256
	s_waitcnt vmcnt(0) lgkmcnt(0)
	v_pk_fma_f32 v[0:1], v[0:1], v[8:9], v[4:5]
	v_pk_fma_f32 v[2:3], v[2:3], v[10:11], v[6:7]
	global_store_dwordx4 v[32:33], v[0:3], off offset:256
	ds_read_b128 v[0:3], v130 offset:1088
	global_load_dwordx4 v[4:7], v[36:37], off offset:256
	global_load_dwordx4 v[8:11], v[38:39], off offset:256
	s_waitcnt vmcnt(0) lgkmcnt(0)
	v_pk_fma_f32 v[0:1], v[0:1], v[8:9], v[4:5]
	v_pk_fma_f32 v[2:3], v[2:3], v[10:11], v[6:7]
	global_store_dwordx4 v[36:37], v[0:3], off offset:256
	ds_read_b128 v[0:3], v130 offset:2176
	global_load_dwordx4 v[4:7], v[40:41], off offset:256
	global_load_dwordx4 v[8:11], v[42:43], off offset:256
	s_waitcnt vmcnt(0) lgkmcnt(0)
	v_pk_fma_f32 v[0:1], v[0:1], v[8:9], v[4:5]
	v_pk_fma_f32 v[2:3], v[2:3], v[10:11], v[6:7]
	global_store_dwordx4 v[40:41], v[0:3], off offset:256
	ds_read_b128 v[0:3], v130 offset:3264
	global_load_dwordx4 v[4:7], v[44:45], off offset:256
	global_load_dwordx4 v[8:11], v[46:47], off offset:256
	s_waitcnt vmcnt(0) lgkmcnt(0)
	v_pk_fma_f32 v[0:1], v[0:1], v[8:9], v[4:5]
	v_pk_fma_f32 v[2:3], v[2:3], v[10:11], v[6:7]
	global_store_dwordx4 v[44:45], v[0:3], off offset:256
	ds_read_b128 v[0:3], v130 offset:4352
	global_load_dwordx4 v[4:7], v[48:49], off offset:256
	global_load_dwordx4 v[8:11], v[50:51], off offset:256
	s_waitcnt vmcnt(0) lgkmcnt(0)
	v_pk_fma_f32 v[0:1], v[0:1], v[8:9], v[4:5]
	v_pk_fma_f32 v[2:3], v[2:3], v[10:11], v[6:7]
	global_store_dwordx4 v[48:49], v[0:3], off offset:256
	ds_read_b128 v[0:3], v130 offset:5440
	global_load_dwordx4 v[4:7], v[52:53], off offset:256
	global_load_dwordx4 v[8:11], v[54:55], off offset:256
	s_waitcnt vmcnt(0) lgkmcnt(0)
	v_pk_fma_f32 v[0:1], v[0:1], v[8:9], v[4:5]
	v_pk_fma_f32 v[2:3], v[2:3], v[10:11], v[6:7]
	global_store_dwordx4 v[52:53], v[0:3], off offset:256
	ds_read_b128 v[0:3], v130 offset:6528
	global_load_dwordx4 v[4:7], v[56:57], off offset:256
	global_load_dwordx4 v[8:11], v[58:59], off offset:256
	s_waitcnt vmcnt(0) lgkmcnt(0)
	v_pk_fma_f32 v[0:1], v[0:1], v[8:9], v[4:5]
	v_pk_fma_f32 v[2:3], v[2:3], v[10:11], v[6:7]
	global_store_dwordx4 v[56:57], v[0:3], off offset:256
	ds_read_b128 v[0:3], v130 offset:7616
	global_load_dwordx4 v[4:7], v[60:61], off offset:256
	global_load_dwordx4 v[8:11], v[62:63], off offset:256
	s_waitcnt vmcnt(0) lgkmcnt(0)
	v_pk_fma_f32 v[0:1], v[0:1], v[8:9], v[4:5]
	v_pk_fma_f32 v[2:3], v[2:3], v[10:11], v[6:7]
	global_store_dwordx4 v[60:61], v[0:3], off offset:256
	s_waitcnt lgkmcnt(0)
	s_barrier
	s_cbranch_scc1 .LBB0_1086
